# replace 374 IEEE 1/x division sequences (sigmoid/silu/gate-rescale epilogues) by single v_rcp_f32 (f32, results rounded to bf16 afterwards)
# speedup vs baseline: 1.0385x; 1.0296x over previous
.LBB0_239:
	v_lshl_add_u32 v214, s4, 8, v234
	v_ashrrev_i32_e32 v215, 31, v214
	v_lshl_add_u64 v[130:131], v[214:215], 2, s[66:67]
	flat_load_dword v0, v[130:131]
	flat_load_dword v132, v[130:131] offset:64
	flat_load_dword v133, v[130:131] offset:128
	flat_load_dword v134, v[130:131] offset:192
	flat_load_dword v135, v[130:131] offset:512
	flat_load_dword v136, v[130:131] offset:576
	flat_load_dword v137, v[130:131] offset:640
	s_lshl_b32 s57, s44, 8
	flat_load_dword v130, v[130:131] offset:704
	s_add_i32 s6, s44, -8
	v_or_b32_e32 v210, 16, v214
	v_or_b32_e32 v206, 32, v214
	v_or_b32_e32 v202, 48, v214
	v_add_u32_e32 v198, 0x80, v214
	v_add_u32_e32 v194, 0x90, v214
	v_add_u32_e32 v190, 0xa0, v214
	v_add_u32_e32 v174, 0xb0, v214
	v_ashrrev_i32_e32 v211, 31, v210
	v_ashrrev_i32_e32 v207, 31, v206
	v_ashrrev_i32_e32 v203, 31, v202
	v_ashrrev_i32_e32 v199, 31, v198
	v_ashrrev_i32_e32 v195, 31, v194
	v_ashrrev_i32_e32 v191, 31, v190
	v_ashrrev_i32_e32 v175, 31, v174
	s_mov_b64 s[4:5], -1
	s_cmp_lt_u32 s6, 9
	s_waitcnt vmcnt(0) lgkmcnt(0)
	v_fmamk_f32 v0, v0, 0x3a000000, v224
	v_cmp_gt_f32_e32 vcc, s19, v0
	v_mul_f32_e32 v131, 0x4b800000, v0
	s_nop 0
	v_cndmask_b32_e32 v0, v0, v131, vcc
	v_rsq_f32_e32 v0, v0
	s_nop 0
	v_mul_f32_e32 v131, 0x45800000, v0
	v_cndmask_b32_e32 v216, v0, v131, vcc
	v_fmamk_f32 v0, v132, 0x3a000000, v224
	v_cmp_gt_f32_e32 vcc, s19, v0
	v_mul_f32_e32 v131, 0x4b800000, v0
	s_nop 0
	v_cndmask_b32_e32 v0, v0, v131, vcc
	v_rsq_f32_e32 v0, v0
	s_nop 0
	v_mul_f32_e32 v131, 0x45800000, v0
	v_cndmask_b32_e32 v212, v0, v131, vcc
	v_fmamk_f32 v0, v133, 0x3a000000, v224
	v_cmp_gt_f32_e32 vcc, s19, v0
	v_mul_f32_e32 v131, 0x4b800000, v0
	s_nop 0
	v_cndmask_b32_e32 v0, v0, v131, vcc
	v_rsq_f32_e32 v0, v0
	s_nop 0
	v_mul_f32_e32 v131, 0x45800000, v0
	v_cndmask_b32_e32 v208, v0, v131, vcc
	v_fmamk_f32 v0, v134, 0x3a000000, v224
	v_cmp_gt_f32_e32 vcc, s19, v0
	v_mul_f32_e32 v131, 0x4b800000, v0
	s_nop 0
	v_cndmask_b32_e32 v0, v0, v131, vcc
	v_rsq_f32_e32 v0, v0
	s_nop 0
	v_mul_f32_e32 v131, 0x45800000, v0
	v_cndmask_b32_e32 v204, v0, v131, vcc
	v_fmamk_f32 v0, v135, 0x3a000000, v224
	v_cmp_gt_f32_e32 vcc, s19, v0
	v_mul_f32_e32 v131, 0x4b800000, v0
	s_nop 0
	v_cndmask_b32_e32 v0, v0, v131, vcc
	v_rsq_f32_e32 v0, v0
	s_nop 0
	v_mul_f32_e32 v131, 0x45800000, v0
	v_cndmask_b32_e32 v200, v0, v131, vcc
	v_fmamk_f32 v0, v136, 0x3a000000, v224
	v_cmp_gt_f32_e32 vcc, s19, v0
	v_mul_f32_e32 v131, 0x4b800000, v0
	s_nop 0
	v_cndmask_b32_e32 v0, v0, v131, vcc
	v_rsq_f32_e32 v0, v0
	s_nop 0
	v_mul_f32_e32 v131, 0x45800000, v0
	v_cndmask_b32_e32 v196, v0, v131, vcc
	v_fmamk_f32 v0, v137, 0x3a000000, v224
	v_cmp_gt_f32_e32 vcc, s19, v0
	v_mul_f32_e32 v131, 0x4b800000, v0
	s_nop 0
	v_cndmask_b32_e32 v0, v0, v131, vcc
	v_rsq_f32_e32 v0, v0
	s_nop 0
	v_mul_f32_e32 v131, 0x45800000, v0
	v_cndmask_b32_e32 v192, v0, v131, vcc
	v_fmamk_f32 v0, v130, 0x3a000000, v224
	v_cmp_gt_f32_e32 vcc, s19, v0
	v_mul_f32_e32 v130, 0x4b800000, v0
	s_nop 0
	v_cndmask_b32_e32 v0, v0, v130, vcc
	v_rsq_f32_e32 v0, v0
	s_nop 0
	v_mul_f32_e32 v130, 0x45800000, v0
	v_cndmask_b32_e32 v176, v0, v130, vcc
	v_or_b32_e32 v0, s57, v236
	s_cbranch_scc1 .LBB0_306
	s_cmp_gt_i32 s44, 17
	s_cselect_b64 s[4:5], -1, 0
	v_lshlrev_b64 v[138:139], 14, v[214:215]
	v_pk_mul_f32 v[132:133], v[128:129], v[216:217] op_sel_hi:[1,0]
	v_pk_mul_f32 v[130:131], v[126:127], v[216:217] op_sel_hi:[1,0]
	v_pk_mul_f32 v[136:137], v[124:125], v[216:217] op_sel_hi:[1,0]
	v_pk_mul_f32 v[134:135], v[122:123], v[216:217] op_sel_hi:[1,0]
	s_mov_b64 s[6:7], -1
	s_and_b64 vcc, exec, s[4:5]
	v_lshl_add_u64 v[144:145], s[60:61], 0, v[138:139]
	s_cbranch_vccz .LBB0_242
	v_mul_f32_e32 v138, 0xbfb8aa3b, v130
	v_exp_f32_e32 v138, v138
	s_nop 0
	v_add_f32_e32 v138, 1.0, v138
	s_nop 0
	v_rcp_f32_e32 v138, v138
	s_nop 0
	v_mul_f32_e32 v139, 0xbfb8aa3b, v131
	v_exp_f32_e32 v139, v139
	s_nop 0
	v_add_f32_e32 v139, 1.0, v139
	s_nop 0
	v_rcp_f32_e32 v139, v139
	s_nop 0
	v_cvt_pk_bf16_f32 v138, v138, v139
	v_mul_f32_e32 v139, 0xbfb8aa3b, v132
	v_exp_f32_e32 v139, v139
	s_nop 0
	v_add_f32_e32 v139, 1.0, v139
	s_nop 0
	v_rcp_f32_e32 v139, v139
	s_nop 0
	v_mul_f32_e32 v140, 0xbfb8aa3b, v133
	v_exp_f32_e32 v140, v140
	s_nop 0
	v_add_f32_e32 v140, 1.0, v140
	s_nop 0
	v_rcp_f32_e32 v140, v140
	s_nop 0
	v_cvt_pk_bf16_f32 v139, v139, v140
	v_mul_f32_e32 v140, 0xbfb8aa3b, v134
	v_exp_f32_e32 v140, v140
	s_nop 0
	v_add_f32_e32 v140, 1.0, v140
	s_nop 0
	v_rcp_f32_e32 v140, v140
	s_nop 0
	v_mul_f32_e32 v141, 0xbfb8aa3b, v135
	v_exp_f32_e32 v141, v141
	s_nop 0
	v_add_f32_e32 v141, 1.0, v141
	s_nop 0
	v_rcp_f32_e32 v141, v141
	s_nop 0
	v_cvt_pk_bf16_f32 v140, v140, v141
	v_mul_f32_e32 v141, 0xbfb8aa3b, v136
	v_exp_f32_e32 v141, v141
	s_nop 0
	v_add_f32_e32 v141, 1.0, v141
	s_nop 0
	v_rcp_f32_e32 v141, v141
	s_nop 0
	v_mul_f32_e32 v142, 0xbfb8aa3b, v137
	v_exp_f32_e32 v142, v142
	s_nop 0
	v_add_f32_e32 v142, 1.0, v142
	s_mov_b64 s[6:7], 0
	v_rcp_f32_e32 v142, v142
	s_nop 0
	v_cvt_pk_bf16_f32 v141, v141, v142
	v_lshl_add_u64 v[142:143], v[0:1], 1, v[144:145]
	v_add_co_u32_e32 v142, vcc, 0xffffdc00, v142
	s_nop 1
	v_addc_co_u32_e32 v143, vcc, -1, v143, vcc
	flat_store_dwordx4 v[142:143], v[138:141] nt

.LBB0_244:
	v_mov_b32_e32 v217, v216
	s_nop 0
	v_mov_b32_e32 v134, v216
	v_mov_b32_e32 v135, v216
	v_cndmask_b32_e64 v138, 0, 1, s[4:5]
	v_pk_mul_f32 v[132:133], v[120:121], v[134:135]
	v_pk_mul_f32 v[130:131], v[118:119], v[216:217]
	v_pk_mul_f32 v[136:137], v[116:117], v[134:135]
	v_pk_mul_f32 v[134:135], v[114:115], v[216:217]
	v_cmp_ne_u32_e64 s[40:41], 1, v138
	s_andn2_b64 vcc, exec, s[4:5]
	s_mov_b64 s[4:5], -1
	s_cbranch_vccnz .LBB0_246
	v_mul_f32_e32 v138, 0xbfb8aa3b, v130
	v_exp_f32_e32 v138, v138
	v_lshl_add_u64 v[144:145], v[0:1], 1, v[144:145]
	v_add_f32_e32 v138, 1.0, v138
	s_nop 0
	v_rcp_f32_e32 v138, v138
	s_nop 0
	v_mul_f32_e32 v139, 0xbfb8aa3b, v131
	v_exp_f32_e32 v139, v139
	s_nop 0
	v_add_f32_e32 v139, 1.0, v139
	s_nop 0
	v_rcp_f32_e32 v139, v139
	s_nop 0
	v_cvt_pk_bf16_f32 v138, v138, v139
	v_mul_f32_e32 v139, 0xbfb8aa3b, v132
	v_exp_f32_e32 v139, v139
	s_nop 0
	v_add_f32_e32 v139, 1.0, v139
	s_nop 0
	v_rcp_f32_e32 v139, v139
	s_nop 0
	v_mul_f32_e32 v140, 0xbfb8aa3b, v133
	v_exp_f32_e32 v140, v140
	s_nop 0
	v_add_f32_e32 v140, 1.0, v140
	s_nop 0
	v_rcp_f32_e32 v140, v140
	s_nop 0
	v_cvt_pk_bf16_f32 v139, v139, v140
	v_mul_f32_e32 v140, 0xbfb8aa3b, v134
	v_exp_f32_e32 v140, v140
	s_nop 0
	v_add_f32_e32 v140, 1.0, v140
	s_nop 0
	v_rcp_f32_e32 v140, v140
	s_nop 0
	v_mul_f32_e32 v141, 0xbfb8aa3b, v135
	v_exp_f32_e32 v141, v141
	s_nop 0
	v_add_f32_e32 v141, 1.0, v141
	s_nop 0
	v_rcp_f32_e32 v141, v141
	s_nop 0
	v_cvt_pk_bf16_f32 v140, v140, v141
	v_mul_f32_e32 v141, 0xbfb8aa3b, v136
	v_exp_f32_e32 v141, v141
	s_nop 0
	v_add_f32_e32 v141, 1.0, v141
	s_nop 0
	v_rcp_f32_e32 v141, v141
	s_nop 0
	v_mul_f32_e32 v142, 0xbfb8aa3b, v137
	v_exp_f32_e32 v142, v142
	s_nop 0
	v_add_f32_e32 v142, 1.0, v142
	s_mov_b64 s[4:5], 0
	v_add_co_u32_e32 v144, vcc, 0xffffdd00, v144
	v_rcp_f32_e32 v142, v142
	s_nop 0
	s_nop 0
	v_addc_co_u32_e32 v145, vcc, -1, v145, vcc
	v_cvt_pk_bf16_f32 v141, v141, v142
	flat_store_dwordx4 v[144:145], v[138:141] nt

.LBB0_248:
	v_lshlrev_b64 v[138:139], 14, v[210:211]
	v_pk_mul_f32 v[132:133], v[112:113], v[212:213] op_sel_hi:[1,0]
	v_pk_mul_f32 v[130:131], v[110:111], v[212:213] op_sel_hi:[1,0]
	v_pk_mul_f32 v[136:137], v[108:109], v[212:213] op_sel_hi:[1,0]
	v_pk_mul_f32 v[134:135], v[106:107], v[212:213] op_sel_hi:[1,0]
	s_mov_b64 s[4:5], -1
	s_and_b64 vcc, exec, s[40:41]
	v_lshl_add_u64 v[144:145], s[60:61], 0, v[138:139]
	s_cbranch_vccnz .LBB0_250
	v_mul_f32_e32 v138, 0xbfb8aa3b, v130
	v_exp_f32_e32 v138, v138
	s_nop 0
	v_add_f32_e32 v138, 1.0, v138
	s_nop 0
	v_rcp_f32_e32 v138, v138
	s_nop 0
	v_mul_f32_e32 v139, 0xbfb8aa3b, v131
	v_exp_f32_e32 v139, v139
	s_nop 0
	v_add_f32_e32 v139, 1.0, v139
	s_nop 0
	v_rcp_f32_e32 v139, v139
	s_nop 0
	v_cvt_pk_bf16_f32 v138, v138, v139
	v_mul_f32_e32 v139, 0xbfb8aa3b, v132
	v_exp_f32_e32 v139, v139
	s_nop 0
	v_add_f32_e32 v139, 1.0, v139
	s_nop 0
	v_rcp_f32_e32 v139, v139
	s_nop 0
	v_mul_f32_e32 v140, 0xbfb8aa3b, v133
	v_exp_f32_e32 v140, v140
	s_nop 0
	v_add_f32_e32 v140, 1.0, v140
	s_nop 0
	v_rcp_f32_e32 v140, v140
	s_nop 0
	v_cvt_pk_bf16_f32 v139, v139, v140
	v_mul_f32_e32 v140, 0xbfb8aa3b, v134
	v_exp_f32_e32 v140, v140
	s_nop 0
	v_add_f32_e32 v140, 1.0, v140
	s_nop 0
	v_rcp_f32_e32 v140, v140
	s_nop 0
	v_mul_f32_e32 v141, 0xbfb8aa3b, v135
	v_exp_f32_e32 v141, v141
	s_nop 0
	v_add_f32_e32 v141, 1.0, v141
	s_nop 0
	v_rcp_f32_e32 v141, v141
	s_nop 0
	v_cvt_pk_bf16_f32 v140, v140, v141
	v_mul_f32_e32 v141, 0xbfb8aa3b, v136
	v_exp_f32_e32 v141, v141
	s_nop 0
	v_add_f32_e32 v141, 1.0, v141
	s_nop 0
	v_rcp_f32_e32 v141, v141
	s_nop 0
	v_mul_f32_e32 v142, 0xbfb8aa3b, v137
	v_exp_f32_e32 v142, v142
	s_nop 0
	v_add_f32_e32 v142, 1.0, v142
	s_mov_b64 s[4:5], 0
	v_rcp_f32_e32 v142, v142
	s_nop 0
	v_lshl_add_u64 v[146:147], v[0:1], 1, v[144:145]
	v_add_co_u32_e32 v146, vcc, 0xffffdc00, v146
	v_cvt_pk_bf16_f32 v141, v141, v142
	s_nop 1
	v_addc_co_u32_e32 v147, vcc, -1, v147, vcc
	flat_store_dwordx4 v[146:147], v[138:141] nt

.LBB0_252:
	v_mov_b32_e32 v213, v212
	s_nop 0
	v_mov_b32_e32 v134, v212
	v_mov_b32_e32 v135, v212
	v_pk_mul_f32 v[132:133], v[104:105], v[134:135]
	v_pk_mul_f32 v[130:131], v[102:103], v[212:213]
	v_pk_mul_f32 v[136:137], v[100:101], v[134:135]
	v_pk_mul_f32 v[134:135], v[98:99], v[212:213]
	s_and_b64 vcc, exec, s[40:41]
	s_mov_b64 s[4:5], -1
	s_cbranch_vccnz .LBB0_254
	v_mul_f32_e32 v138, 0xbfb8aa3b, v130
	v_exp_f32_e32 v138, v138
	v_lshl_add_u64 v[144:145], v[0:1], 1, v[144:145]
	v_add_f32_e32 v138, 1.0, v138
	s_nop 0
	v_rcp_f32_e32 v138, v138
	s_nop 0
	v_mul_f32_e32 v139, 0xbfb8aa3b, v131
	v_exp_f32_e32 v139, v139
	s_nop 0
	v_add_f32_e32 v139, 1.0, v139
	s_nop 0
	v_rcp_f32_e32 v139, v139
	s_nop 0
	v_cvt_pk_bf16_f32 v138, v138, v139
	v_mul_f32_e32 v139, 0xbfb8aa3b, v132
	v_exp_f32_e32 v139, v139
	s_nop 0
	v_add_f32_e32 v139, 1.0, v139
	s_nop 0
	v_rcp_f32_e32 v139, v139
	s_nop 0
	v_mul_f32_e32 v140, 0xbfb8aa3b, v133
	v_exp_f32_e32 v140, v140
	s_nop 0
	v_add_f32_e32 v140, 1.0, v140
	s_nop 0
	v_rcp_f32_e32 v140, v140
	s_nop 0
	v_cvt_pk_bf16_f32 v139, v139, v140
	v_mul_f32_e32 v140, 0xbfb8aa3b, v134
	v_exp_f32_e32 v140, v140
	s_nop 0
	v_add_f32_e32 v140, 1.0, v140
	s_nop 0
	v_rcp_f32_e32 v140, v140
	s_nop 0
	v_mul_f32_e32 v141, 0xbfb8aa3b, v135
	v_exp_f32_e32 v141, v141
	s_nop 0
	v_add_f32_e32 v141, 1.0, v141
	s_nop 0
	v_rcp_f32_e32 v141, v141
	s_nop 0
	v_cvt_pk_bf16_f32 v140, v140, v141
	v_mul_f32_e32 v141, 0xbfb8aa3b, v136
	v_exp_f32_e32 v141, v141
	s_nop 0
	v_add_f32_e32 v141, 1.0, v141
	s_nop 0
	v_rcp_f32_e32 v141, v141
	s_nop 0
	v_mul_f32_e32 v142, 0xbfb8aa3b, v137
	v_exp_f32_e32 v142, v142
	s_nop 0
	v_add_f32_e32 v142, 1.0, v142
	s_mov_b64 s[4:5], 0
	v_add_co_u32_e32 v144, vcc, 0xffffdd00, v144
	v_rcp_f32_e32 v142, v142
	s_nop 0
	s_nop 0
	v_addc_co_u32_e32 v145, vcc, -1, v145, vcc
	v_cvt_pk_bf16_f32 v141, v141, v142
	flat_store_dwordx4 v[144:145], v[138:141] nt

.LBB0_256:
	v_lshlrev_b64 v[138:139], 14, v[206:207]
	v_pk_mul_f32 v[132:133], v[96:97], v[208:209] op_sel_hi:[1,0]
	v_pk_mul_f32 v[130:131], v[94:95], v[208:209] op_sel_hi:[1,0]
	v_pk_mul_f32 v[136:137], v[92:93], v[208:209] op_sel_hi:[1,0]
	v_pk_mul_f32 v[134:135], v[90:91], v[208:209] op_sel_hi:[1,0]
	s_mov_b64 s[4:5], -1
	s_and_b64 vcc, exec, s[40:41]
	v_lshl_add_u64 v[144:145], s[60:61], 0, v[138:139]
	s_cbranch_vccnz .LBB0_258
	v_mul_f32_e32 v138, 0xbfb8aa3b, v130
	v_exp_f32_e32 v138, v138
	s_nop 0
	v_add_f32_e32 v138, 1.0, v138
	s_nop 0
	v_rcp_f32_e32 v138, v138
	s_nop 0
	v_mul_f32_e32 v139, 0xbfb8aa3b, v131
	v_exp_f32_e32 v139, v139
	s_nop 0
	v_add_f32_e32 v139, 1.0, v139
	s_nop 0
	v_rcp_f32_e32 v139, v139
	s_nop 0
	v_cvt_pk_bf16_f32 v138, v138, v139
	v_mul_f32_e32 v139, 0xbfb8aa3b, v132
	v_exp_f32_e32 v139, v139
	s_nop 0
	v_add_f32_e32 v139, 1.0, v139
	s_nop 0
	v_rcp_f32_e32 v139, v139
	s_nop 0
	v_mul_f32_e32 v140, 0xbfb8aa3b, v133
	v_exp_f32_e32 v140, v140
	s_nop 0
	v_add_f32_e32 v140, 1.0, v140
	s_nop 0
	v_rcp_f32_e32 v140, v140
	s_nop 0
	v_cvt_pk_bf16_f32 v139, v139, v140
	v_mul_f32_e32 v140, 0xbfb8aa3b, v134
	v_exp_f32_e32 v140, v140
	s_nop 0
	v_add_f32_e32 v140, 1.0, v140
	s_nop 0
	v_rcp_f32_e32 v140, v140
	s_nop 0
	v_mul_f32_e32 v141, 0xbfb8aa3b, v135
	v_exp_f32_e32 v141, v141
	s_nop 0
	v_add_f32_e32 v141, 1.0, v141
	s_nop 0
	v_rcp_f32_e32 v141, v141
	s_nop 0
	v_cvt_pk_bf16_f32 v140, v140, v141
	v_mul_f32_e32 v141, 0xbfb8aa3b, v136
	v_exp_f32_e32 v141, v141
	s_nop 0
	v_add_f32_e32 v141, 1.0, v141
	s_nop 0
	v_rcp_f32_e32 v141, v141
	s_nop 0
	v_mul_f32_e32 v142, 0xbfb8aa3b, v137
	v_exp_f32_e32 v142, v142
	s_nop 0
	v_add_f32_e32 v142, 1.0, v142
	s_mov_b64 s[4:5], 0
	v_rcp_f32_e32 v142, v142
	s_nop 0
	v_lshl_add_u64 v[146:147], v[0:1], 1, v[144:145]
	v_add_co_u32_e32 v146, vcc, 0xffffdc00, v146
	v_cvt_pk_bf16_f32 v141, v141, v142
	s_nop 1
	v_addc_co_u32_e32 v147, vcc, -1, v147, vcc
	flat_store_dwordx4 v[146:147], v[138:141] nt

.LBB0_260:
	v_mov_b32_e32 v209, v208
	s_nop 0
	v_mov_b32_e32 v134, v208
	v_mov_b32_e32 v135, v208
	v_pk_mul_f32 v[132:133], v[88:89], v[134:135]
	v_pk_mul_f32 v[130:131], v[86:87], v[208:209]
	v_pk_mul_f32 v[136:137], v[84:85], v[134:135]
	v_pk_mul_f32 v[134:135], v[82:83], v[208:209]
	s_and_b64 vcc, exec, s[40:41]
	s_mov_b64 s[4:5], -1
	s_cbranch_vccnz .LBB0_262
	v_mul_f32_e32 v138, 0xbfb8aa3b, v130
	v_exp_f32_e32 v138, v138
	v_lshl_add_u64 v[144:145], v[0:1], 1, v[144:145]
	v_add_f32_e32 v138, 1.0, v138
	s_nop 0
	v_rcp_f32_e32 v138, v138
	s_nop 0
	v_mul_f32_e32 v139, 0xbfb8aa3b, v131
	v_exp_f32_e32 v139, v139
	s_nop 0
	v_add_f32_e32 v139, 1.0, v139
	s_nop 0
	v_rcp_f32_e32 v139, v139
	s_nop 0
	v_cvt_pk_bf16_f32 v138, v138, v139
	v_mul_f32_e32 v139, 0xbfb8aa3b, v132
	v_exp_f32_e32 v139, v139
	s_nop 0
	v_add_f32_e32 v139, 1.0, v139
	s_nop 0
	v_rcp_f32_e32 v139, v139
	s_nop 0
	v_mul_f32_e32 v140, 0xbfb8aa3b, v133
	v_exp_f32_e32 v140, v140
	s_nop 0
	v_add_f32_e32 v140, 1.0, v140
	s_nop 0
	v_rcp_f32_e32 v140, v140
	s_nop 0
	v_cvt_pk_bf16_f32 v139, v139, v140
	v_mul_f32_e32 v140, 0xbfb8aa3b, v134
	v_exp_f32_e32 v140, v140
	s_nop 0
	v_add_f32_e32 v140, 1.0, v140
	s_nop 0
	v_rcp_f32_e32 v140, v140
	s_nop 0
	v_mul_f32_e32 v141, 0xbfb8aa3b, v135
	v_exp_f32_e32 v141, v141
	s_nop 0
	v_add_f32_e32 v141, 1.0, v141
	s_nop 0
	v_rcp_f32_e32 v141, v141
	s_nop 0
	v_cvt_pk_bf16_f32 v140, v140, v141
	v_mul_f32_e32 v141, 0xbfb8aa3b, v136
	v_exp_f32_e32 v141, v141
	s_nop 0
	v_add_f32_e32 v141, 1.0, v141
	s_nop 0
	v_rcp_f32_e32 v141, v141
	s_nop 0
	v_mul_f32_e32 v142, 0xbfb8aa3b, v137
	v_exp_f32_e32 v142, v142
	s_nop 0
	v_add_f32_e32 v142, 1.0, v142
	s_mov_b64 s[4:5], 0
	v_add_co_u32_e32 v144, vcc, 0xffffdd00, v144
	v_rcp_f32_e32 v142, v142
	s_nop 0
	s_nop 0
	v_addc_co_u32_e32 v145, vcc, -1, v145, vcc
	v_cvt_pk_bf16_f32 v141, v141, v142
	flat_store_dwordx4 v[144:145], v[138:141] nt

.LBB0_264:
	v_lshlrev_b64 v[138:139], 14, v[202:203]
	v_pk_mul_f32 v[132:133], v[80:81], v[204:205] op_sel_hi:[1,0]
	v_pk_mul_f32 v[130:131], v[78:79], v[204:205] op_sel_hi:[1,0]
	v_pk_mul_f32 v[136:137], v[76:77], v[204:205] op_sel_hi:[1,0]
	v_pk_mul_f32 v[134:135], v[74:75], v[204:205] op_sel_hi:[1,0]
	s_mov_b64 s[4:5], -1
	s_and_b64 vcc, exec, s[40:41]
	v_lshl_add_u64 v[144:145], s[60:61], 0, v[138:139]
	s_cbranch_vccnz .LBB0_266
	v_mul_f32_e32 v138, 0xbfb8aa3b, v130
	v_exp_f32_e32 v138, v138
	s_nop 0
	v_add_f32_e32 v138, 1.0, v138
	s_nop 0
	v_rcp_f32_e32 v138, v138
	s_nop 0
	v_mul_f32_e32 v139, 0xbfb8aa3b, v131
	v_exp_f32_e32 v139, v139
	s_nop 0
	v_add_f32_e32 v139, 1.0, v139
	s_nop 0
	v_rcp_f32_e32 v139, v139
	s_nop 0
	v_cvt_pk_bf16_f32 v138, v138, v139
	v_mul_f32_e32 v139, 0xbfb8aa3b, v132
	v_exp_f32_e32 v139, v139
	s_nop 0
	v_add_f32_e32 v139, 1.0, v139
	s_nop 0
	v_rcp_f32_e32 v139, v139
	s_nop 0
	v_mul_f32_e32 v140, 0xbfb8aa3b, v133
	v_exp_f32_e32 v140, v140
	s_nop 0
	v_add_f32_e32 v140, 1.0, v140
	s_nop 0
	v_rcp_f32_e32 v140, v140
	s_nop 0
	v_cvt_pk_bf16_f32 v139, v139, v140
	v_mul_f32_e32 v140, 0xbfb8aa3b, v134
	v_exp_f32_e32 v140, v140
	s_nop 0
	v_add_f32_e32 v140, 1.0, v140
	s_nop 0
	v_rcp_f32_e32 v140, v140
	s_nop 0
	v_mul_f32_e32 v141, 0xbfb8aa3b, v135
	v_exp_f32_e32 v141, v141
	s_nop 0
	v_add_f32_e32 v141, 1.0, v141
	s_nop 0
	v_rcp_f32_e32 v141, v141
	s_nop 0
	v_cvt_pk_bf16_f32 v140, v140, v141
	v_mul_f32_e32 v141, 0xbfb8aa3b, v136
	v_exp_f32_e32 v141, v141
	s_nop 0
	v_add_f32_e32 v141, 1.0, v141
	s_nop 0
	v_rcp_f32_e32 v141, v141
	s_nop 0
	v_mul_f32_e32 v142, 0xbfb8aa3b, v137
	v_exp_f32_e32 v142, v142
	s_nop 0
	v_add_f32_e32 v142, 1.0, v142
	s_mov_b64 s[4:5], 0
	v_rcp_f32_e32 v142, v142
	s_nop 0
	v_lshl_add_u64 v[146:147], v[0:1], 1, v[144:145]
	v_add_co_u32_e32 v146, vcc, 0xffffdc00, v146
	v_cvt_pk_bf16_f32 v141, v141, v142
	s_nop 1
	v_addc_co_u32_e32 v147, vcc, -1, v147, vcc
	flat_store_dwordx4 v[146:147], v[138:141] nt

.LBB0_268:
	v_mov_b32_e32 v205, v204
	s_nop 0
	v_mov_b32_e32 v134, v204
	v_mov_b32_e32 v135, v204
	v_pk_mul_f32 v[132:133], v[72:73], v[134:135]
	v_pk_mul_f32 v[130:131], v[70:71], v[204:205]
	v_pk_mul_f32 v[136:137], v[68:69], v[134:135]
	v_pk_mul_f32 v[134:135], v[66:67], v[204:205]
	s_and_b64 vcc, exec, s[40:41]
	s_mov_b64 s[4:5], -1
	s_cbranch_vccnz .LBB0_270
	v_mul_f32_e32 v138, 0xbfb8aa3b, v130
	v_exp_f32_e32 v138, v138
	v_lshl_add_u64 v[144:145], v[0:1], 1, v[144:145]
	v_add_f32_e32 v138, 1.0, v138
	s_nop 0
	v_rcp_f32_e32 v138, v138
	s_nop 0
	v_mul_f32_e32 v139, 0xbfb8aa3b, v131
	v_exp_f32_e32 v139, v139
	s_nop 0
	v_add_f32_e32 v139, 1.0, v139
	s_nop 0
	v_rcp_f32_e32 v139, v139
	s_nop 0
	v_cvt_pk_bf16_f32 v138, v138, v139
	v_mul_f32_e32 v139, 0xbfb8aa3b, v132
	v_exp_f32_e32 v139, v139
	s_nop 0
	v_add_f32_e32 v139, 1.0, v139
	s_nop 0
	v_rcp_f32_e32 v139, v139
	s_nop 0
	v_mul_f32_e32 v140, 0xbfb8aa3b, v133
	v_exp_f32_e32 v140, v140
	s_nop 0
	v_add_f32_e32 v140, 1.0, v140
	s_nop 0
	v_rcp_f32_e32 v140, v140
	s_nop 0
	v_cvt_pk_bf16_f32 v139, v139, v140
	v_mul_f32_e32 v140, 0xbfb8aa3b, v134
	v_exp_f32_e32 v140, v140
	s_nop 0
	v_add_f32_e32 v140, 1.0, v140
	s_nop 0
	v_rcp_f32_e32 v140, v140
	s_nop 0
	v_mul_f32_e32 v141, 0xbfb8aa3b, v135
	v_exp_f32_e32 v141, v141
	s_nop 0
	v_add_f32_e32 v141, 1.0, v141
	s_nop 0
	v_rcp_f32_e32 v141, v141
	s_nop 0
	v_cvt_pk_bf16_f32 v140, v140, v141
	v_mul_f32_e32 v141, 0xbfb8aa3b, v136
	v_exp_f32_e32 v141, v141
	s_nop 0
	v_add_f32_e32 v141, 1.0, v141
	s_nop 0
	v_rcp_f32_e32 v141, v141
	s_nop 0
	v_mul_f32_e32 v142, 0xbfb8aa3b, v137
	v_exp_f32_e32 v142, v142
	s_nop 0
	v_add_f32_e32 v142, 1.0, v142
	s_mov_b64 s[4:5], 0
	v_add_co_u32_e32 v144, vcc, 0xffffdd00, v144
	v_rcp_f32_e32 v142, v142
	s_nop 0
	s_nop 0
	v_addc_co_u32_e32 v145, vcc, -1, v145, vcc
	v_cvt_pk_bf16_f32 v141, v141, v142
	flat_store_dwordx4 v[144:145], v[138:141] nt

.LBB0_272:
	v_lshlrev_b64 v[138:139], 14, v[198:199]
	v_pk_mul_f32 v[132:133], v[64:65], v[200:201] op_sel_hi:[1,0]
	v_pk_mul_f32 v[130:131], v[62:63], v[200:201] op_sel_hi:[1,0]
	v_pk_mul_f32 v[136:137], v[60:61], v[200:201] op_sel_hi:[1,0]
	v_pk_mul_f32 v[134:135], v[58:59], v[200:201] op_sel_hi:[1,0]
	s_mov_b64 s[4:5], -1
	s_and_b64 vcc, exec, s[40:41]
	v_lshl_add_u64 v[144:145], s[60:61], 0, v[138:139]
	s_cbranch_vccnz .LBB0_274
	v_mul_f32_e32 v138, 0xbfb8aa3b, v130
	v_exp_f32_e32 v138, v138
	s_nop 0
	v_add_f32_e32 v138, 1.0, v138
	s_nop 0
	v_rcp_f32_e32 v138, v138
	s_nop 0
	v_mul_f32_e32 v139, 0xbfb8aa3b, v131
	v_exp_f32_e32 v139, v139
	s_nop 0
	v_add_f32_e32 v139, 1.0, v139
	s_nop 0
	v_rcp_f32_e32 v139, v139
	s_nop 0
	v_cvt_pk_bf16_f32 v138, v138, v139
	v_mul_f32_e32 v139, 0xbfb8aa3b, v132
	v_exp_f32_e32 v139, v139
	s_nop 0
	v_add_f32_e32 v139, 1.0, v139
	s_nop 0
	v_rcp_f32_e32 v139, v139
	s_nop 0
	v_mul_f32_e32 v140, 0xbfb8aa3b, v133
	v_exp_f32_e32 v140, v140
	s_nop 0
	v_add_f32_e32 v140, 1.0, v140
	s_nop 0
	v_rcp_f32_e32 v140, v140
	s_nop 0
	v_cvt_pk_bf16_f32 v139, v139, v140
	v_mul_f32_e32 v140, 0xbfb8aa3b, v134
	v_exp_f32_e32 v140, v140
	s_nop 0
	v_add_f32_e32 v140, 1.0, v140
	s_nop 0
	v_rcp_f32_e32 v140, v140
	s_nop 0
	v_mul_f32_e32 v141, 0xbfb8aa3b, v135
	v_exp_f32_e32 v141, v141
	s_nop 0
	v_add_f32_e32 v141, 1.0, v141
	s_nop 0
	v_rcp_f32_e32 v141, v141
	s_nop 0
	v_cvt_pk_bf16_f32 v140, v140, v141
	v_mul_f32_e32 v141, 0xbfb8aa3b, v136
	v_exp_f32_e32 v141, v141
	s_nop 0
	v_add_f32_e32 v141, 1.0, v141
	s_nop 0
	v_rcp_f32_e32 v141, v141
	s_nop 0
	v_mul_f32_e32 v142, 0xbfb8aa3b, v137
	v_exp_f32_e32 v142, v142
	s_nop 0
	v_add_f32_e32 v142, 1.0, v142
	s_mov_b64 s[4:5], 0
	v_rcp_f32_e32 v142, v142
	s_nop 0
	v_lshl_add_u64 v[146:147], v[0:1], 1, v[144:145]
	v_add_co_u32_e32 v146, vcc, 0xffffdc00, v146
	v_cvt_pk_bf16_f32 v141, v141, v142
	s_nop 1
	v_addc_co_u32_e32 v147, vcc, -1, v147, vcc
	flat_store_dwordx4 v[146:147], v[138:141] nt

.LBB0_276:
	v_mov_b32_e32 v201, v200
	s_nop 0
	v_mov_b32_e32 v134, v200
	v_mov_b32_e32 v135, v200
	v_pk_mul_f32 v[132:133], v[56:57], v[134:135]
	v_pk_mul_f32 v[130:131], v[54:55], v[200:201]
	v_pk_mul_f32 v[136:137], v[52:53], v[134:135]
	v_pk_mul_f32 v[134:135], v[50:51], v[200:201]
	s_and_b64 vcc, exec, s[40:41]
	s_mov_b64 s[4:5], -1
	s_cbranch_vccnz .LBB0_278
	v_mul_f32_e32 v138, 0xbfb8aa3b, v130
	v_exp_f32_e32 v138, v138
	v_lshl_add_u64 v[144:145], v[0:1], 1, v[144:145]
	v_add_f32_e32 v138, 1.0, v138
	s_nop 0
	v_rcp_f32_e32 v138, v138
	s_nop 0
	v_mul_f32_e32 v139, 0xbfb8aa3b, v131
	v_exp_f32_e32 v139, v139
	s_nop 0
	v_add_f32_e32 v139, 1.0, v139
	s_nop 0
	v_rcp_f32_e32 v139, v139
	s_nop 0
	v_cvt_pk_bf16_f32 v138, v138, v139
	v_mul_f32_e32 v139, 0xbfb8aa3b, v132
	v_exp_f32_e32 v139, v139
	s_nop 0
	v_add_f32_e32 v139, 1.0, v139
	s_nop 0
	v_rcp_f32_e32 v139, v139
	s_nop 0
	v_mul_f32_e32 v140, 0xbfb8aa3b, v133
	v_exp_f32_e32 v140, v140
	s_nop 0
	v_add_f32_e32 v140, 1.0, v140
	s_nop 0
	v_rcp_f32_e32 v140, v140
	s_nop 0
	v_cvt_pk_bf16_f32 v139, v139, v140
	v_mul_f32_e32 v140, 0xbfb8aa3b, v134
	v_exp_f32_e32 v140, v140
	s_nop 0
	v_add_f32_e32 v140, 1.0, v140
	s_nop 0
	v_rcp_f32_e32 v140, v140
	s_nop 0
	v_mul_f32_e32 v141, 0xbfb8aa3b, v135
	v_exp_f32_e32 v141, v141
	s_nop 0
	v_add_f32_e32 v141, 1.0, v141
	s_nop 0
	v_rcp_f32_e32 v141, v141
	s_nop 0
	v_cvt_pk_bf16_f32 v140, v140, v141
	v_mul_f32_e32 v141, 0xbfb8aa3b, v136
	v_exp_f32_e32 v141, v141
	s_nop 0
	v_add_f32_e32 v141, 1.0, v141
	s_nop 0
	v_rcp_f32_e32 v141, v141
	s_nop 0
	v_mul_f32_e32 v142, 0xbfb8aa3b, v137
	v_exp_f32_e32 v142, v142
	s_nop 0
	v_add_f32_e32 v142, 1.0, v142
	s_mov_b64 s[4:5], 0
	v_add_co_u32_e32 v144, vcc, 0xffffdd00, v144
	v_rcp_f32_e32 v142, v142
	s_nop 0
	s_nop 0
	v_addc_co_u32_e32 v145, vcc, -1, v145, vcc
	v_cvt_pk_bf16_f32 v141, v141, v142
	flat_store_dwordx4 v[144:145], v[138:141] nt

.LBB0_280:
	v_lshlrev_b64 v[138:139], 14, v[194:195]
	v_pk_mul_f32 v[132:133], v[48:49], v[196:197] op_sel_hi:[1,0]
	v_pk_mul_f32 v[130:131], v[46:47], v[196:197] op_sel_hi:[1,0]
	v_pk_mul_f32 v[136:137], v[44:45], v[196:197] op_sel_hi:[1,0]
	v_pk_mul_f32 v[134:135], v[42:43], v[196:197] op_sel_hi:[1,0]
	s_mov_b64 s[4:5], -1
	s_and_b64 vcc, exec, s[40:41]
	v_lshl_add_u64 v[144:145], s[60:61], 0, v[138:139]
	s_cbranch_vccnz .LBB0_282
	v_mul_f32_e32 v138, 0xbfb8aa3b, v130
	v_exp_f32_e32 v138, v138
	s_nop 0
	v_add_f32_e32 v138, 1.0, v138
	s_nop 0
	v_rcp_f32_e32 v138, v138
	s_nop 0
	v_mul_f32_e32 v139, 0xbfb8aa3b, v131
	v_exp_f32_e32 v139, v139
	s_nop 0
	v_add_f32_e32 v139, 1.0, v139
	s_nop 0
	v_rcp_f32_e32 v139, v139
	s_nop 0
	v_cvt_pk_bf16_f32 v138, v138, v139
	v_mul_f32_e32 v139, 0xbfb8aa3b, v132
	v_exp_f32_e32 v139, v139
	s_nop 0
	v_add_f32_e32 v139, 1.0, v139
	s_nop 0
	v_rcp_f32_e32 v139, v139
	s_nop 0
	v_mul_f32_e32 v140, 0xbfb8aa3b, v133
	v_exp_f32_e32 v140, v140
	s_nop 0
	v_add_f32_e32 v140, 1.0, v140
	s_nop 0
	v_rcp_f32_e32 v140, v140
	s_nop 0
	v_cvt_pk_bf16_f32 v139, v139, v140
	v_mul_f32_e32 v140, 0xbfb8aa3b, v134
	v_exp_f32_e32 v140, v140
	s_nop 0
	v_add_f32_e32 v140, 1.0, v140
	s_nop 0
	v_rcp_f32_e32 v140, v140
	s_nop 0
	v_mul_f32_e32 v141, 0xbfb8aa3b, v135
	v_exp_f32_e32 v141, v141
	s_nop 0
	v_add_f32_e32 v141, 1.0, v141
	s_nop 0
	v_rcp_f32_e32 v141, v141
	s_nop 0
	v_cvt_pk_bf16_f32 v140, v140, v141
	v_mul_f32_e32 v141, 0xbfb8aa3b, v136
	v_exp_f32_e32 v141, v141
	s_nop 0
	v_add_f32_e32 v141, 1.0, v141
	s_nop 0
	v_rcp_f32_e32 v141, v141
	s_nop 0
	v_mul_f32_e32 v142, 0xbfb8aa3b, v137
	v_exp_f32_e32 v142, v142
	s_nop 0
	v_add_f32_e32 v142, 1.0, v142
	s_mov_b64 s[4:5], 0
	v_rcp_f32_e32 v142, v142
	s_nop 0
	v_lshl_add_u64 v[146:147], v[0:1], 1, v[144:145]
	v_add_co_u32_e32 v146, vcc, 0xffffdc00, v146
	v_cvt_pk_bf16_f32 v141, v141, v142
	s_nop 1
	v_addc_co_u32_e32 v147, vcc, -1, v147, vcc
	flat_store_dwordx4 v[146:147], v[138:141] nt

.LBB0_284:
	v_mov_b32_e32 v197, v196
	s_nop 0
	v_mov_b32_e32 v134, v196
	v_mov_b32_e32 v135, v196
	v_pk_mul_f32 v[132:133], v[40:41], v[134:135]
	v_pk_mul_f32 v[130:131], v[38:39], v[196:197]
	v_pk_mul_f32 v[136:137], v[36:37], v[134:135]
	v_pk_mul_f32 v[134:135], v[34:35], v[196:197]
	s_and_b64 vcc, exec, s[40:41]
	s_mov_b64 s[4:5], -1
	s_cbranch_vccnz .LBB0_286
	v_mul_f32_e32 v138, 0xbfb8aa3b, v130
	v_exp_f32_e32 v138, v138
	v_lshl_add_u64 v[144:145], v[0:1], 1, v[144:145]
	v_add_f32_e32 v138, 1.0, v138
	s_nop 0
	v_rcp_f32_e32 v138, v138
	s_nop 0
	v_mul_f32_e32 v139, 0xbfb8aa3b, v131
	v_exp_f32_e32 v139, v139
	s_nop 0
	v_add_f32_e32 v139, 1.0, v139
	s_nop 0
	v_rcp_f32_e32 v139, v139
	s_nop 0
	v_cvt_pk_bf16_f32 v138, v138, v139
	v_mul_f32_e32 v139, 0xbfb8aa3b, v132
	v_exp_f32_e32 v139, v139
	s_nop 0
	v_add_f32_e32 v139, 1.0, v139
	s_nop 0
	v_rcp_f32_e32 v139, v139
	s_nop 0
	v_mul_f32_e32 v140, 0xbfb8aa3b, v133
	v_exp_f32_e32 v140, v140
	s_nop 0
	v_add_f32_e32 v140, 1.0, v140
	s_nop 0
	v_rcp_f32_e32 v140, v140
	s_nop 0
	v_cvt_pk_bf16_f32 v139, v139, v140
	v_mul_f32_e32 v140, 0xbfb8aa3b, v134
	v_exp_f32_e32 v140, v140
	s_nop 0
	v_add_f32_e32 v140, 1.0, v140
	s_nop 0
	v_rcp_f32_e32 v140, v140
	s_nop 0
	v_mul_f32_e32 v141, 0xbfb8aa3b, v135
	v_exp_f32_e32 v141, v141
	s_nop 0
	v_add_f32_e32 v141, 1.0, v141
	s_nop 0
	v_rcp_f32_e32 v141, v141
	s_nop 0
	v_cvt_pk_bf16_f32 v140, v140, v141
	v_mul_f32_e32 v141, 0xbfb8aa3b, v136
	v_exp_f32_e32 v141, v141
	s_nop 0
	v_add_f32_e32 v141, 1.0, v141
	s_nop 0
	v_rcp_f32_e32 v141, v141
	s_nop 0
	v_mul_f32_e32 v142, 0xbfb8aa3b, v137
	v_exp_f32_e32 v142, v142
	s_nop 0
	v_add_f32_e32 v142, 1.0, v142
	s_mov_b64 s[4:5], 0
	v_add_co_u32_e32 v144, vcc, 0xffffdd00, v144
	v_rcp_f32_e32 v142, v142
	s_nop 0
	s_nop 0
	v_addc_co_u32_e32 v145, vcc, -1, v145, vcc
	v_cvt_pk_bf16_f32 v141, v141, v142
	flat_store_dwordx4 v[144:145], v[138:141] nt

.LBB0_288:
	v_lshlrev_b64 v[138:139], 14, v[190:191]
	v_pk_mul_f32 v[132:133], v[32:33], v[192:193] op_sel_hi:[1,0]
	v_pk_mul_f32 v[130:131], v[30:31], v[192:193] op_sel_hi:[1,0]
	v_pk_mul_f32 v[136:137], v[28:29], v[192:193] op_sel_hi:[1,0]
	v_pk_mul_f32 v[134:135], v[26:27], v[192:193] op_sel_hi:[1,0]
	s_mov_b64 s[4:5], -1
	s_and_b64 vcc, exec, s[40:41]
	v_lshl_add_u64 v[144:145], s[60:61], 0, v[138:139]
	s_cbranch_vccnz .LBB0_290
	v_mul_f32_e32 v138, 0xbfb8aa3b, v130
	v_exp_f32_e32 v138, v138
	s_nop 0
	v_add_f32_e32 v138, 1.0, v138
	s_nop 0
	v_rcp_f32_e32 v138, v138
	s_nop 0
	v_mul_f32_e32 v139, 0xbfb8aa3b, v131
	v_exp_f32_e32 v139, v139
	s_nop 0
	v_add_f32_e32 v139, 1.0, v139
	s_nop 0
	v_rcp_f32_e32 v139, v139
	s_nop 0
	v_cvt_pk_bf16_f32 v138, v138, v139
	v_mul_f32_e32 v139, 0xbfb8aa3b, v132
	v_exp_f32_e32 v139, v139
	s_nop 0
	v_add_f32_e32 v139, 1.0, v139
	s_nop 0
	v_rcp_f32_e32 v139, v139
	s_nop 0
	v_mul_f32_e32 v140, 0xbfb8aa3b, v133
	v_exp_f32_e32 v140, v140
	s_nop 0
	v_add_f32_e32 v140, 1.0, v140
	s_nop 0
	v_rcp_f32_e32 v140, v140
	s_nop 0
	v_cvt_pk_bf16_f32 v139, v139, v140
	v_mul_f32_e32 v140, 0xbfb8aa3b, v134
	v_exp_f32_e32 v140, v140
	s_nop 0
	v_add_f32_e32 v140, 1.0, v140
	s_nop 0
	v_rcp_f32_e32 v140, v140
	s_nop 0
	v_mul_f32_e32 v141, 0xbfb8aa3b, v135
	v_exp_f32_e32 v141, v141
	s_nop 0
	v_add_f32_e32 v141, 1.0, v141
	s_nop 0
	v_rcp_f32_e32 v141, v141
	s_nop 0
	v_cvt_pk_bf16_f32 v140, v140, v141
	v_mul_f32_e32 v141, 0xbfb8aa3b, v136
	v_exp_f32_e32 v141, v141
	s_nop 0
	v_add_f32_e32 v141, 1.0, v141
	s_nop 0
	v_rcp_f32_e32 v141, v141
	s_nop 0
	v_mul_f32_e32 v142, 0xbfb8aa3b, v137
	v_exp_f32_e32 v142, v142
	s_nop 0
	v_add_f32_e32 v142, 1.0, v142
	s_mov_b64 s[4:5], 0
	v_rcp_f32_e32 v142, v142
	s_nop 0
	v_lshl_add_u64 v[146:147], v[0:1], 1, v[144:145]
	v_add_co_u32_e32 v146, vcc, 0xffffdc00, v146
	v_cvt_pk_bf16_f32 v141, v141, v142
	s_nop 1
	v_addc_co_u32_e32 v147, vcc, -1, v147, vcc
	flat_store_dwordx4 v[146:147], v[138:141] nt

.LBB0_292:
	v_mov_b32_e32 v193, v192
	s_nop 0
	v_mov_b32_e32 v134, v192
	v_mov_b32_e32 v135, v192
	v_pk_mul_f32 v[132:133], v[24:25], v[134:135]
	v_pk_mul_f32 v[130:131], v[22:23], v[192:193]
	v_pk_mul_f32 v[136:137], v[20:21], v[134:135]
	v_pk_mul_f32 v[134:135], v[18:19], v[192:193]
	s_and_b64 vcc, exec, s[40:41]
	s_mov_b64 s[4:5], -1
	s_cbranch_vccnz .LBB0_294
	v_mul_f32_e32 v138, 0xbfb8aa3b, v130
	v_exp_f32_e32 v138, v138
	v_lshl_add_u64 v[144:145], v[0:1], 1, v[144:145]
	v_add_f32_e32 v138, 1.0, v138
	s_nop 0
	v_rcp_f32_e32 v138, v138
	s_nop 0
	v_mul_f32_e32 v139, 0xbfb8aa3b, v131
	v_exp_f32_e32 v139, v139
	s_nop 0
	v_add_f32_e32 v139, 1.0, v139
	s_nop 0
	v_rcp_f32_e32 v139, v139
	s_nop 0
	v_cvt_pk_bf16_f32 v138, v138, v139
	v_mul_f32_e32 v139, 0xbfb8aa3b, v132
	v_exp_f32_e32 v139, v139
	s_nop 0
	v_add_f32_e32 v139, 1.0, v139
	s_nop 0
	v_rcp_f32_e32 v139, v139
	s_nop 0
	v_mul_f32_e32 v140, 0xbfb8aa3b, v133
	v_exp_f32_e32 v140, v140
	s_nop 0
	v_add_f32_e32 v140, 1.0, v140
	s_nop 0
	v_rcp_f32_e32 v140, v140
	s_nop 0
	v_cvt_pk_bf16_f32 v139, v139, v140
	v_mul_f32_e32 v140, 0xbfb8aa3b, v134
	v_exp_f32_e32 v140, v140
	s_nop 0
	v_add_f32_e32 v140, 1.0, v140
	s_nop 0
	v_rcp_f32_e32 v140, v140
	s_nop 0
	v_mul_f32_e32 v141, 0xbfb8aa3b, v135
	v_exp_f32_e32 v141, v141
	s_nop 0
	v_add_f32_e32 v141, 1.0, v141
	s_nop 0
	v_rcp_f32_e32 v141, v141
	s_nop 0
	v_cvt_pk_bf16_f32 v140, v140, v141
	v_mul_f32_e32 v141, 0xbfb8aa3b, v136
	v_exp_f32_e32 v141, v141
	s_nop 0
	v_add_f32_e32 v141, 1.0, v141
	s_nop 0
	v_rcp_f32_e32 v141, v141
	s_nop 0
	v_mul_f32_e32 v142, 0xbfb8aa3b, v137
	v_exp_f32_e32 v142, v142
	s_nop 0
	v_add_f32_e32 v142, 1.0, v142
	s_mov_b64 s[4:5], 0
	v_add_co_u32_e32 v144, vcc, 0xffffdd00, v144
	v_rcp_f32_e32 v142, v142
	s_nop 0
	s_nop 0
	v_addc_co_u32_e32 v145, vcc, -1, v145, vcc
	v_cvt_pk_bf16_f32 v141, v141, v142
	flat_store_dwordx4 v[144:145], v[138:141] nt

.LBB0_296:
	v_lshlrev_b64 v[138:139], 14, v[174:175]
	v_pk_mul_f32 v[132:133], v[16:17], v[176:177] op_sel_hi:[1,0]
	v_pk_mul_f32 v[130:131], v[14:15], v[176:177] op_sel_hi:[1,0]
	v_pk_mul_f32 v[136:137], v[12:13], v[176:177] op_sel_hi:[1,0]
	v_pk_mul_f32 v[134:135], v[10:11], v[176:177] op_sel_hi:[1,0]
	s_mov_b64 s[4:5], -1
	s_and_b64 vcc, exec, s[40:41]
	v_lshl_add_u64 v[144:145], s[60:61], 0, v[138:139]
	s_cbranch_vccnz .LBB0_298
	v_mul_f32_e32 v138, 0xbfb8aa3b, v130
	v_exp_f32_e32 v138, v138
	s_nop 0
	v_add_f32_e32 v138, 1.0, v138
	s_nop 0
	v_rcp_f32_e32 v138, v138
	s_nop 0
	v_mul_f32_e32 v139, 0xbfb8aa3b, v131
	v_exp_f32_e32 v139, v139
	s_nop 0
	v_add_f32_e32 v139, 1.0, v139
	s_nop 0
	v_rcp_f32_e32 v139, v139
	s_nop 0
	v_cvt_pk_bf16_f32 v138, v138, v139
	v_mul_f32_e32 v139, 0xbfb8aa3b, v132
	v_exp_f32_e32 v139, v139
	s_nop 0
	v_add_f32_e32 v139, 1.0, v139
	s_nop 0
	v_rcp_f32_e32 v139, v139
	s_nop 0
	v_mul_f32_e32 v140, 0xbfb8aa3b, v133
	v_exp_f32_e32 v140, v140
	s_nop 0
	v_add_f32_e32 v140, 1.0, v140
	s_nop 0
	v_rcp_f32_e32 v140, v140
	s_nop 0
	v_cvt_pk_bf16_f32 v139, v139, v140
	v_mul_f32_e32 v140, 0xbfb8aa3b, v134
	v_exp_f32_e32 v140, v140
	s_nop 0
	v_add_f32_e32 v140, 1.0, v140
	s_nop 0
	v_rcp_f32_e32 v140, v140
	s_nop 0
	v_mul_f32_e32 v141, 0xbfb8aa3b, v135
	v_exp_f32_e32 v141, v141
	s_nop 0
	v_add_f32_e32 v141, 1.0, v141
	s_nop 0
	v_rcp_f32_e32 v141, v141
	s_nop 0
	v_cvt_pk_bf16_f32 v140, v140, v141
	v_mul_f32_e32 v141, 0xbfb8aa3b, v136
	v_exp_f32_e32 v141, v141
	s_nop 0
	v_add_f32_e32 v141, 1.0, v141
	s_nop 0
	v_rcp_f32_e32 v141, v141
	s_nop 0
	v_mul_f32_e32 v142, 0xbfb8aa3b, v137
	v_exp_f32_e32 v142, v142
	s_nop 0
	v_add_f32_e32 v142, 1.0, v142
	s_mov_b64 s[4:5], 0
	v_rcp_f32_e32 v142, v142
	s_nop 0
	v_lshl_add_u64 v[146:147], v[0:1], 1, v[144:145]
	v_add_co_u32_e32 v146, vcc, 0xffffdc00, v146
	v_cvt_pk_bf16_f32 v141, v141, v142
	s_nop 1
	v_addc_co_u32_e32 v147, vcc, -1, v147, vcc
	flat_store_dwordx4 v[146:147], v[138:141] nt

.LBB0_300:
	v_mov_b32_e32 v177, v176
	s_nop 0
	v_mov_b32_e32 v134, v176
	v_mov_b32_e32 v135, v176
	v_pk_mul_f32 v[132:133], v[8:9], v[134:135]
	v_pk_mul_f32 v[130:131], v[6:7], v[176:177]
	v_pk_mul_f32 v[136:137], v[4:5], v[134:135]
	v_pk_mul_f32 v[134:135], v[2:3], v[176:177]
	s_and_b64 vcc, exec, s[40:41]
	s_mov_b64 s[4:5], -1
	s_cbranch_vccnz .LBB0_302
	v_mul_f32_e32 v138, 0xbfb8aa3b, v130
	v_exp_f32_e32 v138, v138
	v_lshl_add_u64 v[144:145], v[0:1], 1, v[144:145]
	v_add_f32_e32 v138, 1.0, v138
	s_nop 0
	v_rcp_f32_e32 v138, v138
	s_nop 0
	v_mul_f32_e32 v139, 0xbfb8aa3b, v131
	v_exp_f32_e32 v139, v139
	s_nop 0
	v_add_f32_e32 v139, 1.0, v139
	s_nop 0
	v_rcp_f32_e32 v139, v139
	s_nop 0
	v_cvt_pk_bf16_f32 v138, v138, v139
	v_mul_f32_e32 v139, 0xbfb8aa3b, v132
	v_exp_f32_e32 v139, v139
	s_nop 0
	v_add_f32_e32 v139, 1.0, v139
	s_nop 0
	v_rcp_f32_e32 v139, v139
	s_nop 0
	v_mul_f32_e32 v140, 0xbfb8aa3b, v133
	v_exp_f32_e32 v140, v140
	s_nop 0
	v_add_f32_e32 v140, 1.0, v140
	s_nop 0
	v_rcp_f32_e32 v140, v140
	s_nop 0
	v_cvt_pk_bf16_f32 v139, v139, v140
	v_mul_f32_e32 v140, 0xbfb8aa3b, v134
	v_exp_f32_e32 v140, v140
	s_nop 0
	v_add_f32_e32 v140, 1.0, v140
	s_nop 0
	v_rcp_f32_e32 v140, v140
	s_nop 0
	v_mul_f32_e32 v141, 0xbfb8aa3b, v135
	v_exp_f32_e32 v141, v141
	s_nop 0
	v_add_f32_e32 v141, 1.0, v141
	s_nop 0
	v_rcp_f32_e32 v141, v141
	s_nop 0
	v_cvt_pk_bf16_f32 v140, v140, v141
	v_mul_f32_e32 v141, 0xbfb8aa3b, v136
	v_exp_f32_e32 v141, v141
	s_nop 0
	v_add_f32_e32 v141, 1.0, v141
	s_nop 0
	v_rcp_f32_e32 v141, v141
	s_nop 0
	v_mul_f32_e32 v142, 0xbfb8aa3b, v137
	v_exp_f32_e32 v142, v142
	s_nop 0
	v_add_f32_e32 v142, 1.0, v142
	s_mov_b64 s[4:5], 0
	v_add_co_u32_e32 v144, vcc, 0xffffdd00, v144
	v_rcp_f32_e32 v142, v142
	s_nop 0
	s_nop 0
	v_addc_co_u32_e32 v145, vcc, -1, v145, vcc
	v_cvt_pk_bf16_f32 v141, v141, v142
	flat_store_dwordx4 v[144:145], v[138:141] nt

.LBB0_1139:
	v_cmp_gt_f32_e32 vcc, s19, v3
	s_mov_b32 s10, 0x3f317217
	v_readlane_b32 s64, v252, 16
	v_cndmask_b32_e64 v68, 0, 32, vcc
	v_ldexp_f32 v68, v3, v68
	v_log_f32_e32 v68, v68
	v_readlane_b32 s66, v252, 18
	v_readlane_b32 s67, v252, 19
	v_readlane_b32 s65, v252, 17
	v_mul_f32_e32 v69, 0x3f317217, v68
	v_fma_f32 v69, v68, s10, -v69
	v_fmac_f32_e32 v69, 0x3377d1cf, v68
	s_mov_b32 s10, 0x7f800000
	v_fmac_f32_e32 v69, 0x3f317217, v68
	v_cmp_lt_f32_e64 s[46:47], |v68|, s10
	s_mov_b32 s10, 0x23c00000
	v_readlane_b32 s68, v252, 20
	v_cndmask_b32_e64 v68, v68, v69, s[46:47]
	v_cndmask_b32_e32 v69, 0, v228, vcc
	v_sub_f32_e32 v68, v68, v69
	v_add_f32_e32 v2, v2, v68
	v_or_b32_e32 v68, s90, v74
	v_mov_b32_e32 v69, v1
	v_lshl_add_u64 v[68:69], v[68:69], 2, s[66:67]
	global_load_dword v68, v[68:69], off
	v_readlane_b32 s69, v252, 21
	v_readlane_b32 s70, v252, 22
	v_readlane_b32 s71, v252, 23
	v_readlane_b32 s72, v252, 24
	v_readlane_b32 s73, v252, 25
	v_readlane_b32 s74, v252, 26
	v_readlane_b32 s75, v252, 27
	v_readlane_b32 s76, v252, 28
	v_readlane_b32 s77, v252, 29
	v_readlane_b32 s78, v252, 30
	v_readlane_b32 s79, v252, 31
	s_waitcnt vmcnt(0)
	v_sub_f32_e32 v2, v68, v2
	v_mul_f32_e32 v2, 0x3fb8aa3b, v2
	v_exp_f32_e32 v2, v2
	s_nop 0
	v_add_f32_e32 v2, 1.0, v2
	s_nop 0
	v_rcp_f32_e32 v2, v2
	s_nop 0
	v_div_scale_f32 v68, s[34:35], v3, v3, v2
	v_rcp_f32_e32 v69, v68
	s_mov_b64 s[34:35], 0x23c00c00
	v_fma_f32 v71, -v68, v69, 1.0
	v_fmac_f32_e32 v69, v71, v69
	v_div_scale_f32 v71, vcc, v2, v3, v2
	v_mul_f32_e32 v74, v71, v69
	v_fma_f32 v75, -v68, v74, v71
	v_fmac_f32_e32 v74, v75, v69
	v_fma_f32 v68, -v68, v74, v71
	v_div_fmas_f32 v68, v68, v69, v74
	v_div_fixup_f32 v68, v68, v3, v2
	v_lshlrev_b64 v[2:3], 12, v[72:73]
	v_mov_b32_e32 v73, v66
	v_mov_b32_e32 v66, v65
	v_mov_b32_e32 v72, v64
	v_pk_mul_f32 v[64:65], v[66:67], v[68:69] op_sel_hi:[1,0]
	v_lshl_add_u64 v[2:3], s[0:1], 0, v[2:3]
	v_pk_mul_f32 v[72:73], v[72:73], v[68:69] op_sel_hi:[1,0]
	v_and_b32_sdwa v69, v64, v225 dst_sel:DWORD dst_unused:UNUSED_PAD src0_sel:WORD_1 src1_sel:DWORD
	v_lshl_add_u64 v[2:3], v[2:3], 0, v[0:1]
	v_mov_b32_e32 v71, v1
	v_and_b32_sdwa v66, v72, v225 dst_sel:DWORD dst_unused:UNUSED_PAD src0_sel:WORD_1 src1_sel:DWORD
	v_and_b32_sdwa v67, v65, v225 dst_sel:DWORD dst_unused:UNUSED_PAD src0_sel:WORD_1 src1_sel:DWORD
	v_add3_u32 v64, v64, v69, s23
	v_lshl_add_u64 v[70:71], v[2:3], 0, v[70:71]
	v_and_b32_sdwa v0, v73, v225 dst_sel:DWORD dst_unused:UNUSED_PAD src0_sel:WORD_1 src1_sel:DWORD
	v_add3_u32 v66, v72, v66, s23
	v_add3_u32 v65, v65, v67, s23
	v_and_b32_e32 v64, 0xffff0000, v64
	v_add3_u32 v0, v73, v0, s23
	v_and_b32_e32 v65, 0xffff0000, v65
	v_or_b32_sdwa v64, v64, v66 dst_sel:DWORD dst_unused:UNUSED_PAD src0_sel:DWORD src1_sel:WORD_1
	v_add_co_u32_e32 v66, vcc, s10, v70
	v_or_b32_sdwa v65, v65, v0 dst_sel:DWORD dst_unused:UNUSED_PAD src0_sel:DWORD src1_sel:WORD_1
	s_nop 0
	v_addc_co_u32_e32 v67, vcc, 0, v71, vcc
	flat_store_dwordx2 v[66:67], v[64:65] offset:3072 nt
	v_mov_b32_e32 v64, v60
	v_mov_b32_e32 v65, v62
	v_pk_mul_f32 v[64:65], v[64:65], v[68:69] op_sel_hi:[1,0]
	v_mov_b32_e32 v62, v61
	v_pk_mul_f32 v[60:61], v[62:63], v[68:69] op_sel_hi:[1,0]
	v_and_b32_sdwa v62, v64, v225 dst_sel:DWORD dst_unused:UNUSED_PAD src0_sel:WORD_1 src1_sel:DWORD
	v_add3_u32 v62, v64, v62, s23
	v_and_b32_sdwa v63, v61, v225 dst_sel:DWORD dst_unused:UNUSED_PAD src0_sel:WORD_1 src1_sel:DWORD
	v_and_b32_sdwa v64, v60, v225 dst_sel:DWORD dst_unused:UNUSED_PAD src0_sel:WORD_1 src1_sel:DWORD
	v_and_b32_sdwa v0, v65, v225 dst_sel:DWORD dst_unused:UNUSED_PAD src0_sel:WORD_1 src1_sel:DWORD
	v_add3_u32 v61, v61, v63, s23
	v_add3_u32 v60, v60, v64, s23
	v_add3_u32 v0, v65, v0, s23
	v_and_b32_e32 v61, 0xffff0000, v61
	v_and_b32_e32 v60, 0xffff0000, v60
	v_lshl_add_u64 v[2:3], v[70:71], 0, s[34:35]
	v_or_b32_sdwa v61, v61, v0 dst_sel:DWORD dst_unused:UNUSED_PAD src0_sel:DWORD src1_sel:WORD_1
	v_or_b32_sdwa v60, v60, v62 dst_sel:DWORD dst_unused:UNUSED_PAD src0_sel:DWORD src1_sel:WORD_1
	flat_store_dwordx2 v[2:3], v[60:61] offset:32 nt
	v_mov_b32_e32 v60, v56
	v_mov_b32_e32 v61, v58
	v_pk_mul_f32 v[60:61], v[60:61], v[68:69] op_sel_hi:[1,0]
	v_mov_b32_e32 v58, v57
	v_pk_mul_f32 v[56:57], v[58:59], v[68:69] op_sel_hi:[1,0]
	v_and_b32_sdwa v58, v60, v225 dst_sel:DWORD dst_unused:UNUSED_PAD src0_sel:WORD_1 src1_sel:DWORD
	v_add3_u32 v58, v60, v58, s23
	v_and_b32_sdwa v59, v57, v225 dst_sel:DWORD dst_unused:UNUSED_PAD src0_sel:WORD_1 src1_sel:DWORD
	v_and_b32_sdwa v60, v56, v225 dst_sel:DWORD dst_unused:UNUSED_PAD src0_sel:WORD_1 src1_sel:DWORD
	v_and_b32_sdwa v0, v61, v225 dst_sel:DWORD dst_unused:UNUSED_PAD src0_sel:WORD_1 src1_sel:DWORD
	v_add3_u32 v57, v57, v59, s23
	v_add3_u32 v56, v56, v60, s23
	v_add3_u32 v0, v61, v0, s23
	v_and_b32_e32 v57, 0xffff0000, v57
	v_and_b32_e32 v56, 0xffff0000, v56
	v_or_b32_sdwa v57, v57, v0 dst_sel:DWORD dst_unused:UNUSED_PAD src0_sel:DWORD src1_sel:WORD_1
	v_or_b32_sdwa v56, v56, v58 dst_sel:DWORD dst_unused:UNUSED_PAD src0_sel:DWORD src1_sel:WORD_1
	flat_store_dwordx2 v[2:3], v[56:57] offset:64 nt
	v_mov_b32_e32 v56, v52
	v_mov_b32_e32 v57, v54
	v_pk_mul_f32 v[56:57], v[56:57], v[68:69] op_sel_hi:[1,0]
	v_mov_b32_e32 v54, v53
	v_pk_mul_f32 v[52:53], v[54:55], v[68:69] op_sel_hi:[1,0]
	v_and_b32_sdwa v54, v56, v225 dst_sel:DWORD dst_unused:UNUSED_PAD src0_sel:WORD_1 src1_sel:DWORD
	v_add3_u32 v54, v56, v54, s23
	v_and_b32_sdwa v55, v53, v225 dst_sel:DWORD dst_unused:UNUSED_PAD src0_sel:WORD_1 src1_sel:DWORD
	v_and_b32_sdwa v56, v52, v225 dst_sel:DWORD dst_unused:UNUSED_PAD src0_sel:WORD_1 src1_sel:DWORD
	v_and_b32_sdwa v0, v57, v225 dst_sel:DWORD dst_unused:UNUSED_PAD src0_sel:WORD_1 src1_sel:DWORD
	v_add3_u32 v53, v53, v55, s23
	v_add3_u32 v52, v52, v56, s23
	v_add3_u32 v0, v57, v0, s23
	v_and_b32_e32 v53, 0xffff0000, v53
	v_and_b32_e32 v52, 0xffff0000, v52
	v_or_b32_sdwa v53, v53, v0 dst_sel:DWORD dst_unused:UNUSED_PAD src0_sel:DWORD src1_sel:WORD_1
	v_or_b32_sdwa v52, v52, v54 dst_sel:DWORD dst_unused:UNUSED_PAD src0_sel:DWORD src1_sel:WORD_1
	flat_store_dwordx2 v[2:3], v[52:53] offset:96 nt
	s_or_b64 exec, exec, s[58:59]
	s_xor_b32 s10, s11, 1
	s_and_saveexec_b64 s[46:47], s[44:45]
	s_cbranch_execz .LBB0_1120

.LBB0_1198:
	s_or_b64 exec, exec, s[6:7]
	v_mfma_f32_16x16x32_bf16 v[114:117], v[60:63], v[8:11], 0
	v_lshl_add_u64 v[56:57], v[56:57], 0, v[0:1]
	v_add_u32_e32 v83, 0x400, v101
	flat_load_dwordx4 v[56:59], v[56:57]
	v_mfma_f32_16x16x32_bf16 v[118:121], v[60:63], v[12:15], 0
	s_nop 7
	ds_write2_b32 v101, v114, v118 offset1:16
	ds_write2_b32 v101, v115, v119 offset0:132 offset1:148
	ds_write2_b32 v83, v116, v120 offset0:8 offset1:24
	ds_write2_b32 v83, v117, v121 offset0:140 offset1:156
	v_mfma_f32_16x16x32_bf16 v[114:117], v[60:63], v[16:19], 0
	s_nop 7
	ds_write_b32 v101, v114 offset:128
	ds_write_b32 v101, v115 offset:656
	ds_write_b32 v101, v116 offset:1184
	ds_write_b32 v101, v117 offset:1712
	v_mfma_f32_16x16x32_bf16 v[114:117], v[60:63], v[20:23], 0
	v_add_u32_e32 v93, 0x400, v103
	s_xor_b64 s[6:7], s[38:39], -1
	s_mov_b64 s[38:39], 0
	v_mfma_f32_16x16x32_bf16 v[118:121], v[60:63], v[28:31], 0
	s_nop 3
	ds_write2_b32 v103, v114, v115 offset1:132
	ds_write2_b32 v93, v116, v117 offset0:8 offset1:140
	v_mfma_f32_16x16x32_bf16 v[114:117], v[60:63], v[24:27], 0
	s_nop 7
	ds_write2_b32 v101, v114, v118 offset0:64 offset1:80
	ds_write2_b32 v101, v115, v119 offset0:196 offset1:212
	ds_write2_b32 v83, v116, v120 offset0:72 offset1:88
	ds_write2_b32 v83, v117, v121 offset0:204 offset1:220
	v_mfma_f32_16x16x32_bf16 v[114:117], v[60:63], v[32:35], 0
	s_nop 7
	ds_write_b32 v101, v114 offset:384
	ds_write_b32 v101, v115 offset:912
	ds_write_b32 v101, v116 offset:1440
	ds_write_b32 v101, v117 offset:1968
	v_mfma_f32_16x16x32_bf16 v[60:63], v[60:63], v[36:39], 0
	s_nop 7
	ds_write2_b32 v104, v60, v61 offset1:132
	v_add_u32_e32 v60, 0x400, v104
	ds_write2_b32 v60, v62, v63 offset0:8 offset1:140
	s_waitcnt lgkmcnt(0)
	ds_read2st64_b32 v[60:61], v105 offset1:1
	v_mul_f32_e32 v62, v3, v97
	v_fma_f32 v62, v2, v96, -v62
	s_waitcnt lgkmcnt(0)
	v_add_f32_e32 v62, v62, v60
	v_mul_f32_e32 v60, v2, v97
	v_fmac_f32_e32 v60, v3, v96
	v_add_f32_e32 v63, v60, v61
	ds_read2_b32 v[60:61], v105 offset0:132 offset1:196
	v_mul_f32_e32 v83, v3, v63
	v_fma_f32 v83, v2, v62, -v83
	ds_write2st64_b32 v105, v62, v63 offset1:1
	s_waitcnt lgkmcnt(0)
	v_add_f32_e32 v83, v60, v83
	v_mul_f32_e32 v60, v2, v63
	v_fmac_f32_e32 v60, v3, v62
	v_add_u32_e32 v63, 32, v105
	v_add_f32_e32 v62, v60, v61
	ds_read2st64_b32 v[60:61], v63 offset0:4 offset1:5
	v_mul_f32_e32 v93, v3, v62
	v_fma_f32 v93, v2, v83, -v93
	ds_write2_b32 v105, v83, v62 offset0:132 offset1:196
	s_waitcnt lgkmcnt(0)
	v_add_f32_e32 v93, v60, v93
	v_mul_f32_e32 v60, v2, v62
	v_fmac_f32_e32 v60, v3, v83
	v_add_f32_e32 v62, v60, v61
	ds_write2st64_b32 v63, v93, v62 offset0:4 offset1:5
	v_add_u32_e32 v63, 48, v105
	ds_read2st64_b32 v[60:61], v63 offset0:6 offset1:7
	v_mul_f32_e32 v83, v3, v62
	v_fma_f32 v83, v2, v93, -v83
	s_waitcnt lgkmcnt(0)
	v_add_f32_e32 v83, v60, v83
	v_mul_f32_e32 v60, v2, v62
	v_fmac_f32_e32 v60, v3, v93
	v_add_f32_e32 v62, v60, v61
	ds_write2st64_b32 v63, v83, v62 offset0:6 offset1:7
	v_add_u32_e32 v63, 64, v105
	ds_read2st64_b32 v[60:61], v63 offset0:8 offset1:9
	v_mul_f32_e32 v93, v3, v62
	v_fma_f32 v93, v2, v83, -v93
	s_waitcnt lgkmcnt(0)
	v_add_f32_e32 v93, v60, v93
	v_mul_f32_e32 v60, v2, v62
	v_fmac_f32_e32 v60, v3, v83
	v_add_f32_e32 v62, v60, v61
	ds_write2st64_b32 v63, v93, v62 offset0:8 offset1:9
	v_add_u32_e32 v63, 0x50, v105
	ds_read2st64_b32 v[60:61], v63 offset0:10 offset1:11
	v_mul_f32_e32 v83, v3, v62
	v_fma_f32 v83, v2, v93, -v83
	s_waitcnt lgkmcnt(0)
	v_add_f32_e32 v83, v60, v83
	v_mul_f32_e32 v60, v2, v62
	v_fmac_f32_e32 v60, v3, v93
	v_add_f32_e32 v62, v60, v61
	ds_write2st64_b32 v63, v83, v62 offset0:10 offset1:11
	v_add_u32_e32 v63, 0x60, v105
	ds_read2st64_b32 v[60:61], v63 offset0:12 offset1:13
	v_mul_f32_e32 v93, v3, v62
	v_fma_f32 v93, v2, v83, -v93
	s_waitcnt lgkmcnt(0)
	v_add_f32_e32 v93, v60, v93
	v_mul_f32_e32 v60, v2, v62
	v_fmac_f32_e32 v60, v3, v83
	v_add_f32_e32 v62, v60, v61
	ds_write2st64_b32 v63, v93, v62 offset0:12 offset1:13
	v_add_u32_e32 v63, 0x70, v105
	ds_read2st64_b32 v[60:61], v63 offset0:14 offset1:15
	v_mul_f32_e32 v83, v3, v62
	v_fma_f32 v83, v2, v93, -v83
	s_waitcnt lgkmcnt(0)
	v_add_f32_e32 v83, v60, v83
	v_mul_f32_e32 v60, v2, v62
	v_fmac_f32_e32 v60, v3, v93
	v_add_f32_e32 v62, v60, v61
	ds_write2st64_b32 v63, v83, v62 offset0:14 offset1:15
	v_add_u32_e32 v63, 0x80, v105
	ds_read2st64_b32 v[60:61], v63 offset0:16 offset1:17
	v_mul_f32_e32 v93, v3, v62
	v_fma_f32 v93, v2, v83, -v93
	s_waitcnt lgkmcnt(0)
	v_add_f32_e32 v93, v60, v93
	v_mul_f32_e32 v60, v2, v62
	v_fmac_f32_e32 v60, v3, v83
	v_add_f32_e32 v62, v60, v61
	ds_write2st64_b32 v63, v93, v62 offset0:16 offset1:17
	v_add_u32_e32 v63, 0x90, v105
	ds_read2st64_b32 v[60:61], v63 offset0:18 offset1:19
	v_mul_f32_e32 v83, v3, v62
	v_fma_f32 v83, v2, v93, -v83
	s_waitcnt lgkmcnt(0)
	v_add_f32_e32 v83, v60, v83
	v_mul_f32_e32 v60, v2, v62
	v_fmac_f32_e32 v60, v3, v93
	v_add_f32_e32 v62, v60, v61
	ds_write2st64_b32 v63, v83, v62 offset0:18 offset1:19
	v_add_u32_e32 v63, 0xa0, v105
	ds_read2st64_b32 v[60:61], v63 offset0:20 offset1:21
	v_mul_f32_e32 v93, v3, v62
	v_fma_f32 v93, v2, v83, -v93
	s_waitcnt lgkmcnt(0)
	v_add_f32_e32 v93, v60, v93
	v_mul_f32_e32 v60, v2, v62
	v_fmac_f32_e32 v60, v3, v83
	v_add_f32_e32 v62, v60, v61
	ds_write2st64_b32 v63, v93, v62 offset0:20 offset1:21
	v_add_u32_e32 v63, 0xb0, v105
	ds_read2st64_b32 v[60:61], v63 offset0:22 offset1:23
	v_mul_f32_e32 v83, v3, v62
	v_fma_f32 v83, v2, v93, -v83
	s_waitcnt lgkmcnt(0)
	v_add_f32_e32 v83, v60, v83
	v_mul_f32_e32 v60, v2, v62
	v_fmac_f32_e32 v60, v3, v93
	v_add_f32_e32 v62, v60, v61
	ds_write2st64_b32 v63, v83, v62 offset0:22 offset1:23
	v_add_u32_e32 v63, 0xc0, v105
	ds_read2st64_b32 v[60:61], v63 offset0:24 offset1:25
	v_mul_f32_e32 v93, v3, v62
	v_fma_f32 v93, v2, v83, -v93
	s_waitcnt lgkmcnt(0)
	v_add_f32_e32 v93, v60, v93
	v_mul_f32_e32 v60, v2, v62
	v_fmac_f32_e32 v60, v3, v83
	v_add_f32_e32 v62, v60, v61
	ds_write2st64_b32 v63, v93, v62 offset0:24 offset1:25
	v_add_u32_e32 v63, 0xd0, v105
	ds_read2st64_b32 v[60:61], v63 offset0:26 offset1:27
	v_mul_f32_e32 v83, v3, v62
	v_fma_f32 v83, v2, v93, -v83
	s_waitcnt lgkmcnt(0)
	v_add_f32_e32 v83, v60, v83
	v_mul_f32_e32 v60, v2, v62
	v_fmac_f32_e32 v60, v3, v93
	v_add_f32_e32 v62, v60, v61
	ds_write2st64_b32 v63, v83, v62 offset0:26 offset1:27
	v_add_u32_e32 v63, 0xe0, v105
	ds_read2st64_b32 v[60:61], v63 offset0:28 offset1:29
	v_mul_f32_e32 v93, v3, v62
	v_mul_f32_e32 v62, v2, v62
	v_fma_f32 v93, v2, v83, -v93
	v_fmac_f32_e32 v62, v3, v83
	v_add_u32_e32 v83, 0xf0, v105
	ds_read2st64_b32 v[96:97], v83 offset0:30 offset1:31
	s_waitcnt lgkmcnt(0)
	v_add_f32_e32 v60, v60, v93
	v_add_f32_e32 v62, v62, v61
	ds_write2st64_b32 v63, v60, v62 offset0:28 offset1:29
	v_pk_mul_f32 v[62:63], v[98:99], v[62:63] op_sel_hi:[1,0]
	s_nop 0
	v_pk_fma_f32 v[114:115], v[2:3], v[60:61], v[62:63] neg_lo:[0,0,1] neg_hi:[0,0,1]
	v_pk_fma_f32 v[60:61], v[2:3], v[60:61], v[62:63] op_sel_hi:[1,0,1]
	s_nop 0
	v_mov_b32_e32 v115, v61
	v_pk_add_f32 v[96:97], v[96:97], v[114:115]
	ds_write2st64_b32 v83, v96, v97 offset0:30 offset1:31
	s_waitcnt lgkmcnt(0)
	ds_read_b128 v[60:63], v100
	ds_read_b128 v[114:117], v100 offset:16
	s_waitcnt lgkmcnt(0)
	v_bfe_u32 v83, v60, 16, 1
	v_add3_u32 v60, v60, v83, s23
	v_bfe_u32 v83, v61, 16, 1
	v_lshrrev_b32_e32 v60, 16, v60
	v_add3_u32 v61, v61, v83, s23
	v_and_or_b32 v60, v61, s15, v60
	v_and_b32_sdwa v61, v63, v225 dst_sel:DWORD dst_unused:UNUSED_PAD src0_sel:WORD_1 src1_sel:DWORD
	v_and_b32_sdwa v83, v62, v225 dst_sel:DWORD dst_unused:UNUSED_PAD src0_sel:WORD_1 src1_sel:DWORD
	v_add3_u32 v62, v62, v83, s23
	v_add3_u32 v61, v63, v61, s23
	v_perm_b32 v61, v61, v62, s22
	v_and_b32_sdwa v62, v115, v225 dst_sel:DWORD dst_unused:UNUSED_PAD src0_sel:WORD_1 src1_sel:DWORD
	v_and_b32_sdwa v63, v114, v225 dst_sel:DWORD dst_unused:UNUSED_PAD src0_sel:WORD_1 src1_sel:DWORD
	v_add3_u32 v63, v114, v63, s23
	v_add3_u32 v62, v115, v62, s23
	v_perm_b32 v62, v62, v63, s22
	v_and_b32_sdwa v63, v117, v225 dst_sel:DWORD dst_unused:UNUSED_PAD src0_sel:WORD_1 src1_sel:DWORD
	v_and_b32_sdwa v83, v116, v225 dst_sel:DWORD dst_unused:UNUSED_PAD src0_sel:WORD_1 src1_sel:DWORD
	v_add3_u32 v83, v116, v83, s23
	v_add3_u32 v63, v117, v63, s23
	ds_read_b128 v[114:117], v100 offset:128
	ds_read_b128 v[118:121], v100 offset:144
	v_perm_b32 v63, v63, v83, s22
	s_waitcnt lgkmcnt(0)
	v_bfe_u32 v83, v114, 16, 1
	v_add3_u32 v83, v114, v83, s23
	v_bfe_u32 v93, v115, 16, 1
	v_lshrrev_b32_e32 v83, 16, v83
	v_add3_u32 v93, v115, v93, s23
	v_and_or_b32 v114, v93, s15, v83
	v_and_b32_sdwa v83, v117, v225 dst_sel:DWORD dst_unused:UNUSED_PAD src0_sel:WORD_1 src1_sel:DWORD
	v_and_b32_sdwa v93, v116, v225 dst_sel:DWORD dst_unused:UNUSED_PAD src0_sel:WORD_1 src1_sel:DWORD
	v_add3_u32 v93, v116, v93, s23
	v_add3_u32 v83, v117, v83, s23
	v_perm_b32 v115, v83, v93, s22
	v_and_b32_sdwa v83, v119, v225 dst_sel:DWORD dst_unused:UNUSED_PAD src0_sel:WORD_1 src1_sel:DWORD
	v_and_b32_sdwa v93, v118, v225 dst_sel:DWORD dst_unused:UNUSED_PAD src0_sel:WORD_1 src1_sel:DWORD
	v_mfma_f32_16x16x32_bf16 v[60:63], v[40:43], v[60:63], 0
	v_add3_u32 v93, v118, v93, s23
	v_add3_u32 v83, v119, v83, s23
	v_perm_b32 v116, v83, v93, s22
	v_and_b32_sdwa v83, v121, v225 dst_sel:DWORD dst_unused:UNUSED_PAD src0_sel:WORD_1 src1_sel:DWORD
	v_and_b32_sdwa v93, v120, v225 dst_sel:DWORD dst_unused:UNUSED_PAD src0_sel:WORD_1 src1_sel:DWORD
	v_add3_u32 v93, v120, v93, s23
	v_add3_u32 v83, v121, v83, s23
	v_perm_b32 v117, v83, v93, s22
	s_nop 1
	v_mfma_f32_16x16x32_bf16 v[60:63], v[44:47], v[114:117], v[60:63]
	ds_read_b128 v[114:117], v100 offset:256
	ds_read_b128 v[118:121], v100 offset:272
	s_waitcnt lgkmcnt(0)
	v_bfe_u32 v83, v114, 16, 1
	v_add3_u32 v83, v114, v83, s23
	v_bfe_u32 v93, v115, 16, 1
	v_lshrrev_b32_e32 v83, 16, v83
	v_add3_u32 v93, v115, v93, s23
	v_and_or_b32 v114, v93, s15, v83
	v_and_b32_sdwa v83, v117, v225 dst_sel:DWORD dst_unused:UNUSED_PAD src0_sel:WORD_1 src1_sel:DWORD
	v_and_b32_sdwa v93, v116, v225 dst_sel:DWORD dst_unused:UNUSED_PAD src0_sel:WORD_1 src1_sel:DWORD
	v_add3_u32 v93, v116, v93, s23
	v_add3_u32 v83, v117, v83, s23
	v_perm_b32 v115, v83, v93, s22
	v_and_b32_sdwa v83, v119, v225 dst_sel:DWORD dst_unused:UNUSED_PAD src0_sel:WORD_1 src1_sel:DWORD
	v_and_b32_sdwa v93, v118, v225 dst_sel:DWORD dst_unused:UNUSED_PAD src0_sel:WORD_1 src1_sel:DWORD
	v_add3_u32 v93, v118, v93, s23
	v_add3_u32 v83, v119, v83, s23
	v_perm_b32 v116, v83, v93, s22
	v_and_b32_sdwa v83, v121, v225 dst_sel:DWORD dst_unused:UNUSED_PAD src0_sel:WORD_1 src1_sel:DWORD
	v_and_b32_sdwa v93, v120, v225 dst_sel:DWORD dst_unused:UNUSED_PAD src0_sel:WORD_1 src1_sel:DWORD
	v_add3_u32 v93, v120, v93, s23
	v_add3_u32 v83, v121, v83, s23
	v_perm_b32 v117, v83, v93, s22
	s_nop 1
	v_mfma_f32_16x16x32_bf16 v[60:63], v[48:51], v[114:117], v[60:63]
	ds_read_b128 v[114:117], v100 offset:384
	ds_read_b128 v[118:121], v100 offset:400
	s_waitcnt lgkmcnt(0)
	s_waitcnt lgkmcnt(0)
	v_bfe_u32 v83, v114, 16, 1
	v_add3_u32 v83, v114, v83, s23
	v_bfe_u32 v93, v115, 16, 1
	v_lshrrev_b32_e32 v83, 16, v83
	v_add3_u32 v93, v115, v93, s23
	v_and_or_b32 v114, v93, s15, v83
	v_and_b32_sdwa v83, v117, v225 dst_sel:DWORD dst_unused:UNUSED_PAD src0_sel:WORD_1 src1_sel:DWORD
	v_and_b32_sdwa v93, v116, v225 dst_sel:DWORD dst_unused:UNUSED_PAD src0_sel:WORD_1 src1_sel:DWORD
	v_add3_u32 v93, v116, v93, s23
	v_add3_u32 v83, v117, v83, s23
	v_perm_b32 v115, v83, v93, s22
	v_and_b32_sdwa v83, v119, v225 dst_sel:DWORD dst_unused:UNUSED_PAD src0_sel:WORD_1 src1_sel:DWORD
	v_and_b32_sdwa v93, v118, v225 dst_sel:DWORD dst_unused:UNUSED_PAD src0_sel:WORD_1 src1_sel:DWORD
	v_add3_u32 v93, v118, v93, s23
	v_add3_u32 v83, v119, v83, s23
	v_perm_b32 v116, v83, v93, s22
	v_and_b32_sdwa v83, v121, v225 dst_sel:DWORD dst_unused:UNUSED_PAD src0_sel:WORD_1 src1_sel:DWORD
	v_and_b32_sdwa v93, v120, v225 dst_sel:DWORD dst_unused:UNUSED_PAD src0_sel:WORD_1 src1_sel:DWORD
	v_add3_u32 v93, v120, v93, s23
	v_add3_u32 v83, v121, v83, s23
	v_perm_b32 v117, v83, v93, s22
	s_nop 1
	v_mfma_f32_16x16x32_bf16 v[60:63], v[52:55], v[114:117], v[60:63]
	s_waitcnt vmcnt(0)
	s_nop 6
	v_pk_fma_f32 v[56:57], v[4:5], v[56:57], v[60:61]
	v_pk_fma_f32 v[58:59], v[6:7], v[58:59], v[62:63]
	v_mul_f32_e32 v62, 0x3d372713, v56
	v_mul_f32_e32 v83, 0x3d372713, v57
	v_mul_f32_e32 v62, v56, v62
	v_mul_f32_e32 v83, v57, v83
	v_mov_b32_e32 v60, v56
	v_fma_f32 v56, v56, v62, v56
	v_mov_b32_e32 v62, v57
	v_fmac_f32_e32 v57, v57, v83
	v_mul_f32_e32 v57, 0x3f4c422a, v57
	v_add_f32_e32 v57, v57, v57
	v_mul_f32_e32 v57, 0x3fb8aa3b, v57
	v_exp_f32_e32 v114, v57
	v_mul_f32_e32 v57, 0x3d372713, v58
	v_mul_f32_e32 v57, v58, v57
	v_fma_f32 v57, v58, v57, v58
	v_mul_f32_e32 v56, 0x3f4c422a, v56
	v_mul_f32_e32 v57, 0x3f4c422a, v57
	v_add_f32_e32 v56, v56, v56
	v_add_f32_e32 v57, v57, v57
	v_mul_f32_e32 v56, 0x3fb8aa3b, v56
	v_mul_f32_e32 v57, 0x3fb8aa3b, v57
	v_exp_f32_e32 v56, v56
	v_exp_f32_e32 v57, v57
	v_mov_b32_e32 v61, v58
	v_mov_b32_e32 v63, v59
	v_pk_mul_f32 v[60:61], v[60:61], 0.5 op_sel_hi:[1,0]
	v_pk_add_f32 v[56:57], v[56:57], 1.0 op_sel_hi:[1,0]
	s_nop 0
	s_nop 0
	v_rcp_f32_e32 v57, v57
	s_nop 0
	s_nop 0
	v_rcp_f32_e32 v56, v56
	s_nop 0
	v_mul_f32_e32 v58, 0x3d372713, v59
	v_mul_f32_e32 v58, v59, v58
	v_fmac_f32_e32 v59, v59, v58
	v_mul_f32_e32 v58, 0x3f4c422a, v59
	v_add_f32_e32 v58, v58, v58
	v_mul_f32_e32 v58, 0x3fb8aa3b, v58
	v_exp_f32_e32 v115, v58
	v_pk_fma_f32 v[56:57], v[56:57], 2.0, 1.0 op_sel_hi:[1,0,0] neg_lo:[1,0,0] neg_hi:[1,0,0]
	v_pk_add_f32 v[58:59], v[114:115], 1.0 op_sel_hi:[1,0]
	v_pk_add_f32 v[56:57], v[56:57], 1.0 op_sel_hi:[1,0]
	s_nop 0
	v_pk_mul_f32 v[56:57], v[60:61], v[56:57]
	s_nop 0
	v_rcp_f32_e32 v59, v59
	s_nop 0
	s_nop 0
	v_rcp_f32_e32 v58, v58
	s_nop 0
	v_pk_fma_f32 v[58:59], v[58:59], 2.0, 1.0 op_sel_hi:[1,0,0] neg_lo:[1,0,0] neg_hi:[1,0,0]
	v_pk_mul_f32 v[60:61], v[62:63], 0.5 op_sel_hi:[1,0]
	v_pk_add_f32 v[58:59], v[58:59], 1.0 op_sel_hi:[1,0]
	s_andn2_b64 vcc, exec, s[6:7]
	v_pk_mul_f32 v[58:59], v[60:61], v[58:59]
	v_and_b32_sdwa v61, v56, v225 dst_sel:DWORD dst_unused:UNUSED_PAD src0_sel:WORD_1 src1_sel:DWORD
	v_and_b32_sdwa v60, v57, v225 dst_sel:DWORD dst_unused:UNUSED_PAD src0_sel:WORD_1 src1_sel:DWORD
	v_add3_u32 v56, v56, v61, s23
	v_and_b32_sdwa v61, v58, v225 dst_sel:DWORD dst_unused:UNUSED_PAD src0_sel:WORD_1 src1_sel:DWORD
	v_add3_u32 v57, v57, v60, s23
	v_and_b32_sdwa v60, v59, v225 dst_sel:DWORD dst_unused:UNUSED_PAD src0_sel:WORD_1 src1_sel:DWORD
	v_add3_u32 v58, v58, v61, s23
	v_add3_u32 v59, v59, v60, s23
	v_and_b32_e32 v58, 0xffff0000, v58
	v_and_b32_e32 v59, 0xffff0000, v59
	v_or_b32_sdwa v56, v58, v56 dst_sel:DWORD dst_unused:UNUSED_PAD src0_sel:DWORD src1_sel:WORD_1
	v_or_b32_e32 v58, s18, v64
	v_or_b32_sdwa v57, v59, v57 dst_sel:DWORD dst_unused:UNUSED_PAD src0_sel:DWORD src1_sel:WORD_1
	v_mad_u32_u24 v58, v58, s17, v81
	s_mov_b32 s18, 16
	ds_write_b64 v58, v[56:57]
	s_cbranch_vccz .LBB0_1196

.LBB0_1202:
	v_lshl_add_u64 v[56:57], v[78:79], 0, s[4:5]
	s_mov_b32 s6, 0x300000
	v_add_co_u32_e32 v40, vcc, s6, v56
	s_mov_b32 s6, 0x304000
	s_nop 0
	v_addc_co_u32_e32 v41, vcc, 0, v57, vcc
	ds_read_b128 v[44:47], v42
	ds_read_b128 v[48:51], v42 offset:16640
	flat_load_dwordx4 v[30:33], v[40:41]
	v_add_co_u32_e32 v38, vcc, s6, v56
	s_mov_b32 s6, 0x308000
	s_nop 0
	v_addc_co_u32_e32 v39, vcc, 0, v57, vcc
	flat_load_dwordx4 v[52:55], v[38:39]
	s_add_u32 s4, s4, 0x100
	s_addc_u32 s5, s5, 0
	s_cmpk_lg_i32 s4, 0x400
	s_waitcnt vmcnt(0) lgkmcnt(0)
	v_mfma_f32_16x16x32_bf16 v[34:37], v[30:33], v[44:47], v[34:37]
	v_mfma_f32_16x16x32_bf16 v[26:29], v[30:33], v[48:51], v[26:29]
	v_add_co_u32_e32 v32, vcc, s6, v56
	s_mov_b32 s6, 0x30c000
	s_nop 0
	v_addc_co_u32_e32 v33, vcc, 0, v57, vcc
	v_mfma_f32_16x16x32_bf16 v[22:25], v[52:55], v[44:47], v[22:25]
	v_add_co_u32_e32 v30, vcc, s6, v56
	v_mfma_f32_16x16x32_bf16 v[18:21], v[52:55], v[48:51], v[18:21]
	flat_load_dwordx4 v[52:55], v[32:33]
	v_addc_co_u32_e32 v31, vcc, 0, v57, vcc
	s_waitcnt vmcnt(0) lgkmcnt(0)
	v_mfma_f32_16x16x32_bf16 v[14:17], v[52:55], v[44:47], v[14:17]
	v_mfma_f32_16x16x32_bf16 v[10:13], v[52:55], v[48:51], v[10:13]
	flat_load_dwordx4 v[52:55], v[30:31]
	s_waitcnt vmcnt(0) lgkmcnt(0)
	v_mfma_f32_16x16x32_bf16 v[2:5], v[52:55], v[48:51], v[2:5]
	flat_load_dwordx4 v[48:51], v[40:41] offset:64
	v_mfma_f32_16x16x32_bf16 v[6:9], v[52:55], v[44:47], v[6:9]
	ds_read_b128 v[44:47], v42 offset:64
	ds_read_b128 v[52:55], v42 offset:16704
	s_waitcnt vmcnt(0) lgkmcnt(0)
	v_mfma_f32_16x16x32_bf16 v[34:37], v[48:51], v[44:47], v[34:37]
	v_mfma_f32_16x16x32_bf16 v[26:29], v[48:51], v[52:55], v[26:29]
	flat_load_dwordx4 v[48:51], v[38:39] offset:64
	s_waitcnt vmcnt(0) lgkmcnt(0)
	v_mfma_f32_16x16x32_bf16 v[22:25], v[48:51], v[44:47], v[22:25]
	v_mfma_f32_16x16x32_bf16 v[18:21], v[48:51], v[52:55], v[18:21]
	flat_load_dwordx4 v[48:51], v[32:33] offset:64
	s_waitcnt vmcnt(0) lgkmcnt(0)
	v_mfma_f32_16x16x32_bf16 v[14:17], v[48:51], v[44:47], v[14:17]
	v_mfma_f32_16x16x32_bf16 v[10:13], v[48:51], v[52:55], v[10:13]
	flat_load_dwordx4 v[48:51], v[30:31] offset:64
	s_waitcnt vmcnt(0) lgkmcnt(0)
	v_mfma_f32_16x16x32_bf16 v[6:9], v[48:51], v[44:47], v[6:9]
	ds_read_b128 v[44:47], v42 offset:128
	v_mfma_f32_16x16x32_bf16 v[2:5], v[48:51], v[52:55], v[2:5]
	flat_load_dwordx4 v[48:51], v[40:41] offset:128
	ds_read_b128 v[52:55], v42 offset:16768
	s_waitcnt vmcnt(0) lgkmcnt(0)
	v_mfma_f32_16x16x32_bf16 v[34:37], v[48:51], v[44:47], v[34:37]
	v_mfma_f32_16x16x32_bf16 v[26:29], v[48:51], v[52:55], v[26:29]
	flat_load_dwordx4 v[48:51], v[38:39] offset:128
	s_waitcnt vmcnt(0) lgkmcnt(0)
	v_mfma_f32_16x16x32_bf16 v[22:25], v[48:51], v[44:47], v[22:25]
	v_mfma_f32_16x16x32_bf16 v[18:21], v[48:51], v[52:55], v[18:21]
	flat_load_dwordx4 v[48:51], v[32:33] offset:128
	s_waitcnt vmcnt(0) lgkmcnt(0)
	v_mfma_f32_16x16x32_bf16 v[14:17], v[48:51], v[44:47], v[14:17]
	v_mfma_f32_16x16x32_bf16 v[10:13], v[48:51], v[52:55], v[10:13]
	flat_load_dwordx4 v[48:51], v[30:31] offset:128
	s_waitcnt vmcnt(0) lgkmcnt(0)
	v_mfma_f32_16x16x32_bf16 v[6:9], v[48:51], v[44:47], v[6:9]
	ds_read_b128 v[44:47], v42 offset:192
	v_mfma_f32_16x16x32_bf16 v[2:5], v[48:51], v[52:55], v[2:5]
	flat_load_dwordx4 v[48:51], v[40:41] offset:192
	ds_read_b128 v[52:55], v42 offset:16832
	flat_load_dwordx4 v[38:41], v[38:39] offset:192
	v_add_u32_e32 v42, 0x100, v42
	s_waitcnt vmcnt(0) lgkmcnt(0)
	v_mfma_f32_16x16x32_bf16 v[22:25], v[38:41], v[44:47], v[22:25]
	v_mfma_f32_16x16x32_bf16 v[18:21], v[38:41], v[52:55], v[18:21]
	flat_load_dwordx4 v[38:41], v[32:33] offset:192
	s_nop 0
	flat_load_dwordx4 v[30:33], v[30:31] offset:192
	v_mfma_f32_16x16x32_bf16 v[34:37], v[48:51], v[44:47], v[34:37]
	v_mfma_f32_16x16x32_bf16 v[26:29], v[48:51], v[52:55], v[26:29]
	s_waitcnt vmcnt(0) lgkmcnt(0)
	v_mfma_f32_16x16x32_bf16 v[14:17], v[38:41], v[44:47], v[14:17]
	v_mfma_f32_16x16x32_bf16 v[10:13], v[38:41], v[52:55], v[10:13]
	v_mfma_f32_16x16x32_bf16 v[6:9], v[30:33], v[44:47], v[6:9]
	v_mfma_f32_16x16x32_bf16 v[2:5], v[30:33], v[52:55], v[2:5]
	s_cbranch_scc1 .LBB0_1202
	global_load_dwordx4 v[30:33], v[76:77], off
	ds_read_b64 v[38:39], v113
	v_ashrrev_i32_e32 v93, 31, v92
	s_mov_b64 s[6:7], 0x23c00400
	v_readlane_b32 s48, v255, 0
	v_readlane_b32 s54, v255, 6
	s_add_i32 s11, s11, s54
	s_cmpk_gt_i32 s11, 0xff
	v_readlane_b32 s49, v255, 1
	v_readlane_b32 s50, v255, 2
	v_readlane_b32 s51, v255, 3
	v_readlane_b32 s52, v255, 4
	v_readlane_b32 s53, v255, 5
	v_readlane_b32 s55, v255, 7
	s_waitcnt vmcnt(0)
	v_pk_add_f32 v[34:35], v[34:35], v[30:31]
	v_pk_add_f32 v[36:37], v[36:37], v[32:33]
	v_mul_f32_e32 v35, 0xbfb8aa3b, v35
	v_mul_f32_e32 v34, 0xbfb8aa3b, v34
	v_exp_f32_e32 v40, v35
	v_mul_f32_e32 v35, 0xbfb8aa3b, v36
	v_exp_f32_e32 v34, v34
	v_exp_f32_e32 v35, v35
	v_mul_f32_e32 v36, 0xbfb8aa3b, v37
	v_exp_f32_e32 v41, v36
	s_waitcnt lgkmcnt(0)
	v_lshlrev_b32_e32 v37, 16, v39
	v_pk_add_f32 v[34:35], v[34:35], 1.0 op_sel_hi:[1,0]
	v_lshlrev_b32_e32 v36, 16, v38
	v_and_b32_e32 v39, 0xffff0000, v39
	v_and_b32_e32 v38, 0xffff0000, v38
	v_pk_add_f32 v[26:27], v[26:27], v[30:31]
	v_rcp_f32_e32 v35, v35
	s_nop 0
	v_mul_f32_e32 v26, 0xbfb8aa3b, v26
	v_pk_add_f32 v[32:33], v[28:29], v[32:33]
	v_rcp_f32_e32 v34, v34
	s_nop 0
	v_pk_mul_f32 v[34:35], v[34:35], v[36:37]
	v_pk_add_f32 v[36:37], v[40:41], 1.0 op_sel_hi:[1,0]
	s_nop 0
	s_nop 0
	v_rcp_f32_e32 v37, v37
	s_nop 0
	s_nop 0
	v_rcp_f32_e32 v36, v36
	s_nop 0
	v_pk_mul_f32 v[36:37], v[36:37], v[38:39]
	v_and_b32_sdwa v38, v35, v225 dst_sel:DWORD dst_unused:UNUSED_PAD src0_sel:WORD_1 src1_sel:DWORD
	v_and_b32_sdwa v39, v34, v225 dst_sel:DWORD dst_unused:UNUSED_PAD src0_sel:WORD_1 src1_sel:DWORD
	v_add3_u32 v34, v34, v39, s23
	v_add3_u32 v35, v35, v38, s23
	v_and_b32_sdwa v38, v37, v225 dst_sel:DWORD dst_unused:UNUSED_PAD src0_sel:WORD_1 src1_sel:DWORD
	v_and_b32_sdwa v39, v36, v225 dst_sel:DWORD dst_unused:UNUSED_PAD src0_sel:WORD_1 src1_sel:DWORD
	v_add3_u32 v37, v37, v38, s23
	v_add3_u32 v36, v36, v39, s23
	v_and_b32_e32 v37, 0xffff0000, v37
	v_and_b32_e32 v36, 0xffff0000, v36
	v_or_b32_sdwa v37, v37, v35 dst_sel:DWORD dst_unused:UNUSED_PAD src0_sel:DWORD src1_sel:WORD_1
	v_or_b32_sdwa v36, v36, v34 dst_sel:DWORD dst_unused:UNUSED_PAD src0_sel:DWORD src1_sel:WORD_1
	v_lshlrev_b64 v[34:35], 12, v[92:93]
	v_lshl_add_u64 v[34:35], s[0:1], 0, v[34:35]
	v_lshl_add_u64 v[34:35], v[34:35], 0, s[6:7]
	v_lshl_add_u64 v[38:39], v[34:35], 0, v[84:85]
	flat_store_dwordx2 v[38:39], v[36:37]
	v_exp_f32_e32 v38, v26
	v_mul_f32_e32 v26, 0xbfb8aa3b, v27
	v_exp_f32_e32 v28, v26
	v_mul_f32_e32 v26, 0xbfb8aa3b, v32
	ds_read_b64 v[36:37], v113 offset:16640
	v_exp_f32_e32 v39, v26
	v_mul_f32_e32 v26, 0xbfb8aa3b, v33
	v_exp_f32_e32 v29, v26
	v_pk_add_f32 v[32:33], v[38:39], 1.0 op_sel_hi:[1,0]
	s_waitcnt lgkmcnt(0)
	v_lshlrev_b32_e32 v30, 16, v36
	v_and_b32_e32 v26, 0xffff0000, v36
	v_lshlrev_b32_e32 v31, 16, v37
	v_and_b32_e32 v27, 0xffff0000, v37
	v_pk_add_f32 v[28:29], v[28:29], 1.0 op_sel_hi:[1,0]
	v_rcp_f32_e32 v33, v33
	s_nop 0
	s_nop 0
	v_rcp_f32_e32 v32, v32
	s_nop 0
	v_pk_mul_f32 v[30:31], v[32:33], v[30:31]
	s_nop 0
	v_rcp_f32_e32 v29, v29
	s_nop 0
	s_nop 0
	v_rcp_f32_e32 v28, v28
	s_nop 0
	v_pk_mul_f32 v[26:27], v[28:29], v[26:27]
	v_and_b32_sdwa v29, v30, v225 dst_sel:DWORD dst_unused:UNUSED_PAD src0_sel:WORD_1 src1_sel:DWORD
	v_and_b32_sdwa v28, v31, v225 dst_sel:DWORD dst_unused:UNUSED_PAD src0_sel:WORD_1 src1_sel:DWORD
	v_add3_u32 v29, v30, v29, s23
	v_and_b32_sdwa v30, v27, v225 dst_sel:DWORD dst_unused:UNUSED_PAD src0_sel:WORD_1 src1_sel:DWORD
	v_add3_u32 v28, v31, v28, s23
	v_and_b32_sdwa v31, v26, v225 dst_sel:DWORD dst_unused:UNUSED_PAD src0_sel:WORD_1 src1_sel:DWORD
	v_add3_u32 v27, v27, v30, s23
	v_add3_u32 v26, v26, v31, s23
	v_and_b32_e32 v27, 0xffff0000, v27
	v_and_b32_e32 v26, 0xffff0000, v26
	v_or_b32_sdwa v27, v27, v28 dst_sel:DWORD dst_unused:UNUSED_PAD src0_sel:DWORD src1_sel:WORD_1
	v_or_b32_e32 v28, s8, v102
	v_or_b32_sdwa v26, v26, v29 dst_sel:DWORD dst_unused:UNUSED_PAD src0_sel:DWORD src1_sel:WORD_1
	v_ashrrev_i32_e32 v29, 31, v28
	v_lshlrev_b64 v[28:29], 12, v[28:29]
	v_lshl_add_u64 v[28:29], s[0:1], 0, v[28:29]
	v_lshl_add_u64 v[30:31], v[28:29], 0, s[6:7]
	v_lshl_add_u64 v[28:29], v[30:31], 0, v[84:85]
	flat_store_dwordx2 v[28:29], v[26:27]
	global_load_dwordx4 v[26:29], v[76:77], off offset:64
	ds_read_b64 v[32:33], v106
	s_waitcnt vmcnt(0)
	v_pk_add_f32 v[22:23], v[22:23], v[26:27]
	v_pk_add_f32 v[24:25], v[24:25], v[28:29]
	v_mul_f32_e32 v23, 0xbfb8aa3b, v23
	v_mul_f32_e32 v22, 0xbfb8aa3b, v22
	v_exp_f32_e32 v36, v23
	v_mul_f32_e32 v23, 0xbfb8aa3b, v24
	v_exp_f32_e32 v22, v22
	v_exp_f32_e32 v23, v23
	v_mul_f32_e32 v24, 0xbfb8aa3b, v25
	v_exp_f32_e32 v37, v24
	s_waitcnt lgkmcnt(0)
	v_lshlrev_b32_e32 v25, 16, v33
	v_pk_add_f32 v[22:23], v[22:23], 1.0 op_sel_hi:[1,0]
	v_lshlrev_b32_e32 v24, 16, v32
	v_and_b32_e32 v33, 0xffff0000, v33
	v_and_b32_e32 v32, 0xffff0000, v32
	v_pk_add_f32 v[18:19], v[18:19], v[26:27]
	v_rcp_f32_e32 v23, v23
	s_nop 0
	v_pk_add_f32 v[20:21], v[20:21], v[28:29]
	v_mul_f32_e32 v19, 0xbfb8aa3b, v19
	v_mul_f32_e32 v18, 0xbfb8aa3b, v18
	v_rcp_f32_e32 v22, v22
	s_nop 0
	v_pk_mul_f32 v[22:23], v[22:23], v[24:25]
	v_pk_add_f32 v[24:25], v[36:37], 1.0 op_sel_hi:[1,0]
	v_exp_f32_e32 v18, v18
	s_nop 0
	v_rcp_f32_e32 v25, v25
	s_nop 0
	s_nop 0
	v_rcp_f32_e32 v24, v24
	s_nop 0
	v_pk_mul_f32 v[24:25], v[24:25], v[32:33]
	v_and_b32_sdwa v32, v23, v225 dst_sel:DWORD dst_unused:UNUSED_PAD src0_sel:WORD_1 src1_sel:DWORD
	v_and_b32_sdwa v33, v22, v225 dst_sel:DWORD dst_unused:UNUSED_PAD src0_sel:WORD_1 src1_sel:DWORD
	v_add3_u32 v22, v22, v33, s23
	v_add3_u32 v23, v23, v32, s23
	v_and_b32_sdwa v32, v25, v225 dst_sel:DWORD dst_unused:UNUSED_PAD src0_sel:WORD_1 src1_sel:DWORD
	v_and_b32_sdwa v33, v24, v225 dst_sel:DWORD dst_unused:UNUSED_PAD src0_sel:WORD_1 src1_sel:DWORD
	v_add3_u32 v25, v25, v32, s23
	v_add3_u32 v24, v24, v33, s23
	v_and_b32_e32 v25, 0xffff0000, v25
	v_and_b32_e32 v24, 0xffff0000, v24
	v_or_b32_sdwa v23, v25, v23 dst_sel:DWORD dst_unused:UNUSED_PAD src0_sel:DWORD src1_sel:WORD_1
	v_or_b32_sdwa v22, v24, v22 dst_sel:DWORD dst_unused:UNUSED_PAD src0_sel:DWORD src1_sel:WORD_1
	v_lshl_add_u64 v[24:25], v[34:35], 0, v[86:87]
	flat_store_dwordx2 v[24:25], v[22:23]
	v_exp_f32_e32 v24, v19
	v_mul_f32_e32 v19, 0xbfb8aa3b, v20
	v_exp_f32_e32 v19, v19
	ds_read_b64 v[22:23], v107
	v_mul_f32_e32 v20, 0xbfb8aa3b, v21
	v_exp_f32_e32 v25, v20
	v_pk_add_f32 v[18:19], v[18:19], 1.0 op_sel_hi:[1,0]
	s_waitcnt lgkmcnt(0)
	v_lshlrev_b32_e32 v21, 16, v23
	v_lshlrev_b32_e32 v20, 16, v22
	v_and_b32_e32 v23, 0xffff0000, v23
	v_and_b32_e32 v22, 0xffff0000, v22
	v_rcp_f32_e32 v19, v19
	s_nop 0
	s_nop 0
	v_rcp_f32_e32 v18, v18
	s_nop 0
	v_pk_mul_f32 v[18:19], v[18:19], v[20:21]
	v_pk_add_f32 v[20:21], v[24:25], 1.0 op_sel_hi:[1,0]
	s_nop 0
	s_nop 0
	v_rcp_f32_e32 v21, v21
	s_nop 0
	s_nop 0
	v_rcp_f32_e32 v20, v20
	s_nop 0
	v_pk_mul_f32 v[20:21], v[20:21], v[22:23]
	v_and_b32_sdwa v22, v19, v225 dst_sel:DWORD dst_unused:UNUSED_PAD src0_sel:WORD_1 src1_sel:DWORD
	v_and_b32_sdwa v23, v18, v225 dst_sel:DWORD dst_unused:UNUSED_PAD src0_sel:WORD_1 src1_sel:DWORD
	v_add3_u32 v18, v18, v23, s23
	v_add3_u32 v19, v19, v22, s23
	v_and_b32_sdwa v22, v21, v225 dst_sel:DWORD dst_unused:UNUSED_PAD src0_sel:WORD_1 src1_sel:DWORD
	v_and_b32_sdwa v23, v20, v225 dst_sel:DWORD dst_unused:UNUSED_PAD src0_sel:WORD_1 src1_sel:DWORD
	v_add3_u32 v21, v21, v22, s23
	v_add3_u32 v20, v20, v23, s23
	v_and_b32_e32 v21, 0xffff0000, v21
	v_and_b32_e32 v20, 0xffff0000, v20
	v_or_b32_sdwa v19, v21, v19 dst_sel:DWORD dst_unused:UNUSED_PAD src0_sel:DWORD src1_sel:WORD_1
	v_or_b32_sdwa v18, v20, v18 dst_sel:DWORD dst_unused:UNUSED_PAD src0_sel:DWORD src1_sel:WORD_1
	v_lshl_add_u64 v[20:21], v[30:31], 0, v[86:87]
	flat_store_dwordx2 v[20:21], v[18:19]
	global_load_dwordx4 v[18:21], v[76:77], off offset:128
	ds_read_b64 v[22:23], v108
	s_waitcnt vmcnt(0)
	v_pk_add_f32 v[14:15], v[14:15], v[18:19]
	v_pk_add_f32 v[16:17], v[16:17], v[20:21]
	v_mul_f32_e32 v15, 0xbfb8aa3b, v15
	v_mul_f32_e32 v14, 0xbfb8aa3b, v14
	v_exp_f32_e32 v24, v15
	v_mul_f32_e32 v15, 0xbfb8aa3b, v16
	v_exp_f32_e32 v14, v14
	v_exp_f32_e32 v15, v15
	v_mul_f32_e32 v16, 0xbfb8aa3b, v17
	v_exp_f32_e32 v25, v16
	s_waitcnt lgkmcnt(0)
	v_lshlrev_b32_e32 v17, 16, v23
	v_pk_add_f32 v[14:15], v[14:15], 1.0 op_sel_hi:[1,0]
	v_lshlrev_b32_e32 v16, 16, v22
	v_and_b32_e32 v23, 0xffff0000, v23
	v_and_b32_e32 v22, 0xffff0000, v22
	v_pk_add_f32 v[10:11], v[10:11], v[18:19]
	v_rcp_f32_e32 v15, v15
	s_nop 0
	v_pk_add_f32 v[12:13], v[12:13], v[20:21]
	v_mul_f32_e32 v11, 0xbfb8aa3b, v11
	v_mul_f32_e32 v10, 0xbfb8aa3b, v10
	v_rcp_f32_e32 v14, v14
	s_nop 0
	v_pk_mul_f32 v[14:15], v[14:15], v[16:17]
	v_pk_add_f32 v[16:17], v[24:25], 1.0 op_sel_hi:[1,0]
	v_exp_f32_e32 v10, v10
	s_nop 0
	v_rcp_f32_e32 v17, v17
	s_nop 0
	s_nop 0
	v_rcp_f32_e32 v16, v16
	s_nop 0
	v_pk_mul_f32 v[16:17], v[16:17], v[22:23]
	v_and_b32_sdwa v22, v15, v225 dst_sel:DWORD dst_unused:UNUSED_PAD src0_sel:WORD_1 src1_sel:DWORD
	v_and_b32_sdwa v23, v14, v225 dst_sel:DWORD dst_unused:UNUSED_PAD src0_sel:WORD_1 src1_sel:DWORD
	v_add3_u32 v14, v14, v23, s23
	v_add3_u32 v15, v15, v22, s23
	v_and_b32_sdwa v22, v17, v225 dst_sel:DWORD dst_unused:UNUSED_PAD src0_sel:WORD_1 src1_sel:DWORD
	v_and_b32_sdwa v23, v16, v225 dst_sel:DWORD dst_unused:UNUSED_PAD src0_sel:WORD_1 src1_sel:DWORD
	v_add3_u32 v17, v17, v22, s23
	v_add3_u32 v16, v16, v23, s23
	v_and_b32_e32 v17, 0xffff0000, v17
	v_and_b32_e32 v16, 0xffff0000, v16
	v_or_b32_sdwa v15, v17, v15 dst_sel:DWORD dst_unused:UNUSED_PAD src0_sel:DWORD src1_sel:WORD_1
	v_or_b32_sdwa v14, v16, v14 dst_sel:DWORD dst_unused:UNUSED_PAD src0_sel:DWORD src1_sel:WORD_1
	v_lshl_add_u64 v[16:17], v[34:35], 0, v[88:89]
	flat_store_dwordx2 v[16:17], v[14:15]
	v_exp_f32_e32 v16, v11
	v_mul_f32_e32 v11, 0xbfb8aa3b, v12
	v_exp_f32_e32 v11, v11
	ds_read_b64 v[14:15], v109
	v_mul_f32_e32 v12, 0xbfb8aa3b, v13
	v_exp_f32_e32 v17, v12
	v_pk_add_f32 v[10:11], v[10:11], 1.0 op_sel_hi:[1,0]
	s_waitcnt lgkmcnt(0)
	v_lshlrev_b32_e32 v13, 16, v15
	v_lshlrev_b32_e32 v12, 16, v14
	v_and_b32_e32 v15, 0xffff0000, v15
	v_and_b32_e32 v14, 0xffff0000, v14
	v_rcp_f32_e32 v11, v11
	s_nop 0
	s_nop 0
	v_rcp_f32_e32 v10, v10
	s_nop 0
	v_pk_mul_f32 v[10:11], v[10:11], v[12:13]
	v_pk_add_f32 v[12:13], v[16:17], 1.0 op_sel_hi:[1,0]
	s_nop 0
	s_nop 0
	v_rcp_f32_e32 v13, v13
	s_nop 0
	s_nop 0
	v_rcp_f32_e32 v12, v12
	s_nop 0
	v_pk_mul_f32 v[12:13], v[12:13], v[14:15]
	v_and_b32_sdwa v14, v11, v225 dst_sel:DWORD dst_unused:UNUSED_PAD src0_sel:WORD_1 src1_sel:DWORD
	v_and_b32_sdwa v15, v10, v225 dst_sel:DWORD dst_unused:UNUSED_PAD src0_sel:WORD_1 src1_sel:DWORD
	v_add3_u32 v10, v10, v15, s23
	v_add3_u32 v11, v11, v14, s23
	v_and_b32_sdwa v14, v13, v225 dst_sel:DWORD dst_unused:UNUSED_PAD src0_sel:WORD_1 src1_sel:DWORD
	v_and_b32_sdwa v15, v12, v225 dst_sel:DWORD dst_unused:UNUSED_PAD src0_sel:WORD_1 src1_sel:DWORD
	v_add3_u32 v13, v13, v14, s23
	v_add3_u32 v12, v12, v15, s23
	v_and_b32_e32 v13, 0xffff0000, v13
	v_and_b32_e32 v12, 0xffff0000, v12
	v_or_b32_sdwa v11, v13, v11 dst_sel:DWORD dst_unused:UNUSED_PAD src0_sel:DWORD src1_sel:WORD_1
	v_or_b32_sdwa v10, v12, v10 dst_sel:DWORD dst_unused:UNUSED_PAD src0_sel:DWORD src1_sel:WORD_1
	v_lshl_add_u64 v[12:13], v[30:31], 0, v[88:89]
	flat_store_dwordx2 v[12:13], v[10:11]
	global_load_dwordx4 v[10:13], v[76:77], off offset:192
	ds_read_b64 v[14:15], v110
	s_waitcnt vmcnt(0)
	v_pk_add_f32 v[6:7], v[6:7], v[10:11]
	v_pk_add_f32 v[8:9], v[8:9], v[12:13]
	v_mul_f32_e32 v7, 0xbfb8aa3b, v7
	v_mul_f32_e32 v6, 0xbfb8aa3b, v6
	v_exp_f32_e32 v16, v7
	v_mul_f32_e32 v7, 0xbfb8aa3b, v8
	v_exp_f32_e32 v6, v6
	v_exp_f32_e32 v7, v7
	v_mul_f32_e32 v8, 0xbfb8aa3b, v9
	v_exp_f32_e32 v17, v8
	s_waitcnt lgkmcnt(0)
	v_lshlrev_b32_e32 v9, 16, v15
	v_pk_add_f32 v[6:7], v[6:7], 1.0 op_sel_hi:[1,0]
	v_lshlrev_b32_e32 v8, 16, v14
	v_and_b32_e32 v15, 0xffff0000, v15
	v_and_b32_e32 v14, 0xffff0000, v14
	v_pk_add_f32 v[2:3], v[2:3], v[10:11]
	v_rcp_f32_e32 v7, v7
	s_nop 0
	v_pk_add_f32 v[4:5], v[4:5], v[12:13]
	v_mul_f32_e32 v3, 0xbfb8aa3b, v3
	v_mul_f32_e32 v2, 0xbfb8aa3b, v2
	v_rcp_f32_e32 v6, v6
	s_nop 0
	v_pk_mul_f32 v[6:7], v[6:7], v[8:9]
	v_pk_add_f32 v[8:9], v[16:17], 1.0 op_sel_hi:[1,0]
	v_exp_f32_e32 v2, v2
	s_nop 0
	v_rcp_f32_e32 v9, v9
	s_nop 0
	s_nop 0
	v_rcp_f32_e32 v8, v8
	s_nop 0
	v_pk_mul_f32 v[8:9], v[8:9], v[14:15]
	v_and_b32_sdwa v14, v7, v225 dst_sel:DWORD dst_unused:UNUSED_PAD src0_sel:WORD_1 src1_sel:DWORD
	v_and_b32_sdwa v15, v6, v225 dst_sel:DWORD dst_unused:UNUSED_PAD src0_sel:WORD_1 src1_sel:DWORD
	v_add3_u32 v6, v6, v15, s23
	v_add3_u32 v7, v7, v14, s23
	v_and_b32_sdwa v14, v9, v225 dst_sel:DWORD dst_unused:UNUSED_PAD src0_sel:WORD_1 src1_sel:DWORD
	v_and_b32_sdwa v15, v8, v225 dst_sel:DWORD dst_unused:UNUSED_PAD src0_sel:WORD_1 src1_sel:DWORD
	v_add3_u32 v9, v9, v14, s23
	v_add3_u32 v8, v8, v15, s23
	v_and_b32_e32 v9, 0xffff0000, v9
	v_and_b32_e32 v8, 0xffff0000, v8
	v_or_b32_sdwa v7, v9, v7 dst_sel:DWORD dst_unused:UNUSED_PAD src0_sel:DWORD src1_sel:WORD_1
	v_or_b32_sdwa v6, v8, v6 dst_sel:DWORD dst_unused:UNUSED_PAD src0_sel:DWORD src1_sel:WORD_1
	v_lshl_add_u64 v[8:9], v[34:35], 0, v[90:91]
	flat_store_dwordx2 v[8:9], v[6:7]
	v_exp_f32_e32 v8, v3
	v_mul_f32_e32 v3, 0xbfb8aa3b, v4
	v_exp_f32_e32 v3, v3
	ds_read_b64 v[6:7], v111
	v_mul_f32_e32 v4, 0xbfb8aa3b, v5
	v_exp_f32_e32 v9, v4
	v_pk_add_f32 v[2:3], v[2:3], 1.0 op_sel_hi:[1,0]
	s_waitcnt lgkmcnt(0)
	v_lshlrev_b32_e32 v5, 16, v7
	v_lshlrev_b32_e32 v4, 16, v6
	v_and_b32_e32 v7, 0xffff0000, v7
	v_and_b32_e32 v6, 0xffff0000, v6
	v_rcp_f32_e32 v3, v3
	s_nop 0
	s_nop 0
	v_rcp_f32_e32 v2, v2
	s_nop 0
	v_pk_mul_f32 v[2:3], v[2:3], v[4:5]
	v_pk_add_f32 v[4:5], v[8:9], 1.0 op_sel_hi:[1,0]
	s_nop 0
	s_nop 0
	v_rcp_f32_e32 v5, v5
	s_nop 0
	s_nop 0
	v_rcp_f32_e32 v4, v4
	s_nop 0
	v_pk_mul_f32 v[4:5], v[4:5], v[6:7]
	v_and_b32_sdwa v6, v3, v225 dst_sel:DWORD dst_unused:UNUSED_PAD src0_sel:WORD_1 src1_sel:DWORD
	v_and_b32_sdwa v7, v2, v225 dst_sel:DWORD dst_unused:UNUSED_PAD src0_sel:WORD_1 src1_sel:DWORD
	v_add3_u32 v2, v2, v7, s23
	v_add3_u32 v3, v3, v6, s23
	v_and_b32_sdwa v6, v5, v225 dst_sel:DWORD dst_unused:UNUSED_PAD src0_sel:WORD_1 src1_sel:DWORD
	v_and_b32_sdwa v7, v4, v225 dst_sel:DWORD dst_unused:UNUSED_PAD src0_sel:WORD_1 src1_sel:DWORD
	v_add3_u32 v5, v5, v6, s23
	v_add3_u32 v4, v4, v7, s23
	v_and_b32_e32 v5, 0xffff0000, v5
	v_and_b32_e32 v4, 0xffff0000, v4
	v_or_b32_sdwa v3, v5, v3 dst_sel:DWORD dst_unused:UNUSED_PAD src0_sel:DWORD src1_sel:WORD_1
	v_or_b32_sdwa v2, v4, v2 dst_sel:DWORD dst_unused:UNUSED_PAD src0_sel:DWORD src1_sel:WORD_1
	v_lshl_add_u64 v[4:5], v[30:31], 0, v[90:91]
	flat_store_dwordx2 v[4:5], v[2:3]
	s_waitcnt lgkmcnt(0)
	s_barrier
	s_cbranch_scc0 .LBB0_1195

.LBB0_1217:
	s_or_b64 exec, exec, s[84:85]
	v_lshl_add_u32 v0, v115, 2, s10
	s_waitcnt lgkmcnt(0)
	s_barrier
	ds_read2st64_b32 v[78:79], v0 offset1:1
	s_and_b32 s10, s12, 0xfffff000
	s_and_b32 s84, s8, 0xfc0
	s_or_b32 s10, s10, s84
	v_mov_b64_e32 v[80:81], s[0:1]
	s_waitcnt lgkmcnt(0)
	v_add_f32_e32 v0, v78, v79
	v_fmamk_f32 v0, v0, 0x3c000000, v224
	v_cmp_gt_f32_e32 vcc, s19, v0
	v_mul_f32_e32 v78, 0x4b800000, v0
	v_mov_b32_e32 v128, v82
	v_cndmask_b32_e32 v0, v0, v78, vcc
	v_rsq_f32_e32 v0, v0
	v_mov_b32_e32 v129, v84
	v_mul_f32_e32 v78, 0x45800000, v0
	v_cndmask_b32_e32 v0, v0, v78, vcc
	v_or_b32_e32 v78, s10, v115
	s_and_b32 s10, s87, 0x180
	v_mad_i64_i32 v[80:81], s[84:85], v78, s20, v[80:81]
	s_lshl_b32 s90, s10, 2
	v_lshl_add_u64 v[80:81], v[80:81], 0, s[90:91]
	s_mov_b64 s[84:85], 0x12c01000
	v_ashrrev_i32_e32 v79, 31, v78
	v_lshl_add_u64 v[104:105], v[80:81], 0, s[84:85]
	s_add_u32 s84, s11, s90
	v_lshlrev_b64 v[106:107], 12, v[78:79]
	s_addc_u32 s85, s18, 0
	v_lshlrev_b64 v[78:79], 2, v[94:95]
	v_lshl_add_u64 v[80:81], s[84:85], 0, v[78:79]
	v_lshl_add_u64 v[78:79], v[104:105], 0, v[78:79]
	global_load_dwordx4 v[86:89], v[80:81], off
	v_pk_mul_f32 v[128:129], v[128:129], v[0:1] op_sel_hi:[1,0]
	flat_load_dwordx4 v[78:81], v[78:79]
	s_lshl_b32 s90, s10, 1
	s_xor_b32 s34, s34, 1
	s_waitcnt vmcnt(0)
	v_mov_b32_e32 v130, v86
	v_mov_b32_e32 v131, v88
	s_waitcnt lgkmcnt(0)
	v_mul_f32_e32 v103, 0xbfb8aa3b, v78
	v_exp_f32_e32 v108, v103
	v_mul_f32_e32 v103, 0xbfb8aa3b, v79
	v_exp_f32_e32 v110, v103
	v_mul_f32_e32 v103, 0xbfb8aa3b, v80
	v_exp_f32_e32 v109, v103
	v_mul_f32_e32 v103, 0xbfb8aa3b, v81
	v_exp_f32_e32 v111, v103
	v_pk_mul_f32 v[128:129], v[130:131], v[128:129]
	v_pk_add_f32 v[108:109], v[108:109], 1.0 op_sel_hi:[1,0]
	v_mov_b32_e32 v130, v78
	v_mov_b32_e32 v131, v80
	v_rcp_f32_e32 v109, v109
	s_nop 0
	s_nop 0
	v_mov_b32_e32 v84, v83
	v_rcp_f32_e32 v108, v108
	s_nop 0
	v_pk_mul_f32 v[82:83], v[84:85], v[0:1] op_sel_hi:[1,0]
	v_pk_add_f32 v[84:85], v[110:111], 1.0 op_sel_hi:[1,0]
	v_mov_b32_e32 v88, v87
	v_pk_mul_f32 v[82:83], v[88:89], v[82:83]
	v_pk_mul_f32 v[108:109], v[130:131], v[108:109]
	v_rcp_f32_e32 v85, v85
	s_nop 0
	v_pk_mul_f32 v[108:109], v[108:109], v[128:129]
	v_mov_b32_e32 v128, v74
	v_mov_b32_e32 v129, v76
	v_rcp_f32_e32 v84, v84
	s_nop 0
	v_mov_b32_e32 v80, v79
	v_pk_mul_f32 v[78:79], v[80:81], v[84:85]
	v_and_b32_sdwa v80, v109, v225 dst_sel:DWORD dst_unused:UNUSED_PAD src0_sel:WORD_1 src1_sel:DWORD
	v_pk_mul_f32 v[78:79], v[78:79], v[82:83]
	v_and_b32_sdwa v81, v108, v225 dst_sel:DWORD dst_unused:UNUSED_PAD src0_sel:WORD_1 src1_sel:DWORD
	v_and_b32_sdwa v82, v79, v225 dst_sel:DWORD dst_unused:UNUSED_PAD src0_sel:WORD_1 src1_sel:DWORD
	v_and_b32_sdwa v83, v78, v225 dst_sel:DWORD dst_unused:UNUSED_PAD src0_sel:WORD_1 src1_sel:DWORD
	v_add3_u32 v79, v79, v82, s23
	v_add3_u32 v78, v78, v83, s23
	v_add3_u32 v81, v108, v81, s23
	v_add3_u32 v80, v109, v80, s23
	v_and_b32_e32 v79, 0xffff0000, v79
	v_and_b32_e32 v78, 0xffff0000, v78
	v_or_b32_sdwa v79, v79, v80 dst_sel:DWORD dst_unused:UNUSED_PAD src0_sel:DWORD src1_sel:WORD_1
	v_or_b32_sdwa v78, v78, v81 dst_sel:DWORD dst_unused:UNUSED_PAD src0_sel:DWORD src1_sel:WORD_1
	v_lshl_add_u64 v[80:81], s[76:77], 0, v[106:107]
	v_lshl_add_u64 v[86:87], v[80:81], 0, s[90:91]
	v_lshl_add_u64 v[80:81], v[94:95], 1, v[86:87]
	flat_store_dwordx2 v[80:81], v[78:79]
	v_lshlrev_b64 v[78:79], 2, v[98:99]
	v_lshl_add_u64 v[106:107], v[104:105], 0, v[78:79]
	v_lshl_add_u64 v[88:89], s[84:85], 0, v[78:79]
	flat_load_dwordx4 v[78:81], v[106:107] offset:64
	global_load_dwordx4 v[82:85], v[88:89], off offset:64
	v_pk_mul_f32 v[128:129], v[128:129], v[0:1] op_sel_hi:[1,0]
	s_waitcnt vmcnt(0) lgkmcnt(0)
	v_mul_f32_e32 v103, 0xbfb8aa3b, v78
	v_exp_f32_e32 v108, v103
	v_mul_f32_e32 v103, 0xbfb8aa3b, v79
	v_exp_f32_e32 v110, v103
	v_mul_f32_e32 v103, 0xbfb8aa3b, v80
	v_exp_f32_e32 v109, v103
	v_mov_b32_e32 v130, v82
	v_mul_f32_e32 v103, 0xbfb8aa3b, v81
	v_mov_b32_e32 v131, v84
	v_pk_add_f32 v[108:109], v[108:109], 1.0 op_sel_hi:[1,0]
	v_exp_f32_e32 v111, v103
	v_pk_mul_f32 v[128:129], v[130:131], v[128:129]
	v_mov_b32_e32 v130, v78
	v_mov_b32_e32 v131, v80
	v_rcp_f32_e32 v109, v109
	s_nop 0
	s_nop 0
	v_mov_b32_e32 v76, v75
	v_rcp_f32_e32 v108, v108
	s_nop 0
	v_pk_mul_f32 v[74:75], v[76:77], v[0:1] op_sel_hi:[1,0]
	v_pk_add_f32 v[76:77], v[110:111], 1.0 op_sel_hi:[1,0]
	v_mov_b32_e32 v84, v83
	v_pk_mul_f32 v[74:75], v[84:85], v[74:75]
	v_pk_mul_f32 v[108:109], v[130:131], v[108:109]
	v_rcp_f32_e32 v77, v77
	s_nop 0
	v_pk_mul_f32 v[108:109], v[128:129], v[108:109]
	v_rcp_f32_e32 v76, v76
	s_nop 0
	v_mov_b32_e32 v80, v79
	v_pk_mul_f32 v[76:77], v[80:81], v[76:77]
	s_nop 0
	v_pk_mul_f32 v[74:75], v[74:75], v[76:77]
	v_and_b32_sdwa v76, v109, v225 dst_sel:DWORD dst_unused:UNUSED_PAD src0_sel:WORD_1 src1_sel:DWORD
	v_and_b32_sdwa v78, v75, v225 dst_sel:DWORD dst_unused:UNUSED_PAD src0_sel:WORD_1 src1_sel:DWORD
	v_and_b32_sdwa v79, v74, v225 dst_sel:DWORD dst_unused:UNUSED_PAD src0_sel:WORD_1 src1_sel:DWORD
	v_and_b32_sdwa v77, v108, v225 dst_sel:DWORD dst_unused:UNUSED_PAD src0_sel:WORD_1 src1_sel:DWORD
	v_add3_u32 v75, v75, v78, s23
	v_add3_u32 v74, v74, v79, s23
	v_add3_u32 v77, v108, v77, s23
	v_add3_u32 v76, v109, v76, s23
	v_and_b32_e32 v75, 0xffff0000, v75
	v_and_b32_e32 v74, 0xffff0000, v74
	v_or_b32_sdwa v75, v75, v76 dst_sel:DWORD dst_unused:UNUSED_PAD src0_sel:DWORD src1_sel:WORD_1
	v_or_b32_sdwa v74, v74, v77 dst_sel:DWORD dst_unused:UNUSED_PAD src0_sel:DWORD src1_sel:WORD_1
	v_lshl_add_u64 v[78:79], v[98:99], 1, v[86:87]
	flat_store_dwordx2 v[78:79], v[74:75] offset:32
	global_load_dwordx4 v[82:85], v[88:89], off offset:128
	s_nop 0
	flat_load_dwordx4 v[74:77], v[106:107] offset:128
	v_mov_b32_e32 v106, v70
	v_mov_b32_e32 v107, v72
	v_pk_mul_f32 v[106:107], v[106:107], v[0:1] op_sel_hi:[1,0]
	s_waitcnt vmcnt(0)
	v_mov_b32_e32 v108, v82
	s_waitcnt lgkmcnt(0)
	v_mul_f32_e32 v81, 0xbfb8aa3b, v75
	v_mul_f32_e32 v80, 0xbfb8aa3b, v74
	v_exp_f32_e32 v88, v81
	v_mul_f32_e32 v81, 0xbfb8aa3b, v76
	v_exp_f32_e32 v80, v80
	v_exp_f32_e32 v81, v81
	v_mov_b32_e32 v109, v84
	v_mul_f32_e32 v89, 0xbfb8aa3b, v77
	v_exp_f32_e32 v89, v89
	v_pk_add_f32 v[80:81], v[80:81], 1.0 op_sel_hi:[1,0]
	v_pk_mul_f32 v[106:107], v[108:109], v[106:107]
	v_mov_b32_e32 v108, v74
	v_mov_b32_e32 v109, v76
	v_rcp_f32_e32 v81, v81
	s_nop 0
	s_nop 0
	v_mov_b32_e32 v72, v71
	v_rcp_f32_e32 v80, v80
	s_nop 0
	v_pk_mul_f32 v[70:71], v[72:73], v[0:1] op_sel_hi:[1,0]
	v_pk_add_f32 v[72:73], v[88:89], 1.0 op_sel_hi:[1,0]
	v_mov_b32_e32 v84, v83
	v_pk_mul_f32 v[70:71], v[84:85], v[70:71]
	v_pk_mul_f32 v[80:81], v[108:109], v[80:81]
	v_rcp_f32_e32 v73, v73
	s_nop 0
	v_pk_mul_f32 v[80:81], v[106:107], v[80:81]
	v_rcp_f32_e32 v72, v72
	s_nop 0
	v_mov_b32_e32 v76, v75
	v_pk_mul_f32 v[72:73], v[76:77], v[72:73]
	v_mov_b32_e32 v82, v66
	v_pk_mul_f32 v[70:71], v[70:71], v[72:73]
	v_and_b32_sdwa v72, v81, v225 dst_sel:DWORD dst_unused:UNUSED_PAD src0_sel:WORD_1 src1_sel:DWORD
	v_and_b32_sdwa v74, v71, v225 dst_sel:DWORD dst_unused:UNUSED_PAD src0_sel:WORD_1 src1_sel:DWORD
	v_and_b32_sdwa v75, v70, v225 dst_sel:DWORD dst_unused:UNUSED_PAD src0_sel:WORD_1 src1_sel:DWORD
	v_and_b32_sdwa v73, v80, v225 dst_sel:DWORD dst_unused:UNUSED_PAD src0_sel:WORD_1 src1_sel:DWORD
	v_add3_u32 v71, v71, v74, s23
	v_add3_u32 v70, v70, v75, s23
	v_add3_u32 v73, v80, v73, s23
	v_add3_u32 v72, v81, v72, s23
	v_and_b32_e32 v71, 0xffff0000, v71
	v_and_b32_e32 v70, 0xffff0000, v70
	v_or_b32_sdwa v71, v71, v72 dst_sel:DWORD dst_unused:UNUSED_PAD src0_sel:DWORD src1_sel:WORD_1
	v_or_b32_sdwa v70, v70, v73 dst_sel:DWORD dst_unused:UNUSED_PAD src0_sel:DWORD src1_sel:WORD_1
	v_lshlrev_b64 v[74:75], 2, v[96:97]
	flat_store_dwordx2 v[78:79], v[70:71] offset:64
	v_lshl_add_u64 v[70:71], s[84:85], 0, v[74:75]
	v_lshl_add_u64 v[74:75], v[104:105], 0, v[74:75]
	flat_load_dwordx4 v[74:77], v[74:75]
	v_mov_b32_e32 v83, v68
	global_load_dwordx4 v[70:73], v[70:71], off
	v_pk_mul_f32 v[82:83], v[82:83], v[0:1] op_sel_hi:[1,0]
	s_waitcnt vmcnt(0) lgkmcnt(0)
	v_mul_f32_e32 v79, 0xbfb8aa3b, v75
	v_mul_f32_e32 v78, 0xbfb8aa3b, v74
	v_exp_f32_e32 v80, v79
	v_mul_f32_e32 v79, 0xbfb8aa3b, v76
	v_exp_f32_e32 v78, v78
	v_exp_f32_e32 v79, v79
	v_mov_b32_e32 v84, v70
	v_mov_b32_e32 v85, v72
	v_pk_mul_f32 v[82:83], v[82:83], v[84:85]
	v_pk_add_f32 v[78:79], v[78:79], 1.0 op_sel_hi:[1,0]
	v_mul_f32_e32 v81, 0xbfb8aa3b, v77
	v_exp_f32_e32 v81, v81
	v_mov_b32_e32 v85, v76
	v_mov_b32_e32 v76, v75
	v_rcp_f32_e32 v79, v79
	s_nop 0
	s_nop 0
	v_mov_b32_e32 v68, v67
	v_rcp_f32_e32 v78, v78
	s_nop 0
	v_pk_mul_f32 v[66:67], v[68:69], v[0:1] op_sel_hi:[1,0]
	v_pk_add_f32 v[68:69], v[80:81], 1.0 op_sel_hi:[1,0]
	v_mov_b32_e32 v72, v71
	v_pk_mul_f32 v[66:67], v[66:67], v[72:73]
	v_mov_b32_e32 v84, v74
	v_pk_mul_f32 v[78:79], v[84:85], v[78:79]
	v_rcp_f32_e32 v69, v69
	s_nop 0
	v_pk_mul_f32 v[78:79], v[82:83], v[78:79]
	v_rcp_f32_e32 v68, v68
	s_nop 0
	v_pk_mul_f32 v[68:69], v[76:77], v[68:69]
	v_and_b32_sdwa v0, v79, v225 dst_sel:DWORD dst_unused:UNUSED_PAD src0_sel:WORD_1 src1_sel:DWORD
	v_pk_mul_f32 v[66:67], v[66:67], v[68:69]
	v_and_b32_sdwa v68, v78, v225 dst_sel:DWORD dst_unused:UNUSED_PAD src0_sel:WORD_1 src1_sel:DWORD
	v_and_b32_sdwa v69, v67, v225 dst_sel:DWORD dst_unused:UNUSED_PAD src0_sel:WORD_1 src1_sel:DWORD
	v_and_b32_sdwa v70, v66, v225 dst_sel:DWORD dst_unused:UNUSED_PAD src0_sel:WORD_1 src1_sel:DWORD
	v_add3_u32 v67, v67, v69, s23
	v_add3_u32 v66, v66, v70, s23
	v_add3_u32 v68, v78, v68, s23
	v_add3_u32 v0, v79, v0, s23
	v_and_b32_e32 v67, 0xffff0000, v67
	v_and_b32_e32 v66, 0xffff0000, v66
	v_or_b32_sdwa v67, v67, v0 dst_sel:DWORD dst_unused:UNUSED_PAD src0_sel:DWORD src1_sel:WORD_1
	v_or_b32_sdwa v66, v66, v68 dst_sel:DWORD dst_unused:UNUSED_PAD src0_sel:DWORD src1_sel:WORD_1
	v_lshl_add_u64 v[68:69], v[96:97], 1, v[86:87]
	s_andn2_b64 vcc, exec, s[82:83]
	flat_store_dwordx2 v[68:69], v[66:67]
	s_cbranch_vccnz .LBB0_1206
	v_sub_f32_e32 v0, v2, v10
	v_mul_f32_e32 v66, 0x3fb8aa3b, v0
	v_mul_f32_e32 v0, 0xbfb8aa3b, v0
	v_exp_f32_e32 v70, v0
	v_sub_f32_e32 v0, v3, v11
	v_mul_f32_e32 v67, 0x3fb8aa3b, v0
	v_mul_f32_e32 v0, 0xbfb8aa3b, v0
	v_exp_f32_e32 v72, v0
	v_sub_f32_e32 v0, v4, v12
	v_exp_f32_e32 v68, v67
	v_mul_f32_e32 v67, 0x3fb8aa3b, v0
	v_mul_f32_e32 v0, 0xbfb8aa3b, v0
	v_exp_f32_e32 v71, v0
	v_sub_f32_e32 v0, v5, v13
	v_mul_f32_e32 v69, 0x3fb8aa3b, v0
	v_mul_f32_e32 v0, 0xbfb8aa3b, v0
	v_exp_f32_e32 v73, v0
	v_sub_f32_e32 v0, v6, v14
	v_mul_f32_e32 v74, 0x3fb8aa3b, v0
	v_mul_f32_e32 v0, 0xbfb8aa3b, v0
	v_exp_f32_e32 v66, v66
	v_exp_f32_e32 v67, v67
	v_exp_f32_e32 v76, v0
	v_sub_f32_e32 v0, v7, v15
	v_mul_f32_e32 v75, 0x3fb8aa3b, v0
	v_mul_f32_e32 v0, 0xbfb8aa3b, v0
	v_exp_f32_e32 v69, v69
	v_exp_f32_e32 v80, v0
	v_sub_f32_e32 v0, v8, v16
	v_mov_b32_e32 v82, v18
	v_mov_b32_e32 v83, v20
	v_exp_f32_e32 v78, v75
	v_mul_f32_e32 v75, 0x3fb8aa3b, v0
	v_mul_f32_e32 v0, 0xbfb8aa3b, v0
	v_pk_mul_f32 v[82:83], v[82:83], s[36:37] op_sel_hi:[1,0]
	v_exp_f32_e32 v74, v74
	v_exp_f32_e32 v75, v75
	v_exp_f32_e32 v77, v0
	v_sub_f32_e32 v0, v9, v17
	v_pk_mul_f32 v[66:67], v[82:83], v[66:67]
	v_mov_b32_e32 v82, v19
	v_mov_b32_e32 v83, v21
	v_mul_f32_e32 v79, 0x3fb8aa3b, v0
	v_pk_mul_f32 v[82:83], v[82:83], s[36:37] op_sel_hi:[1,0]
	v_exp_f32_e32 v79, v79
	v_pk_mul_f32 v[68:69], v[82:83], v[68:69]
	v_mov_b32_e32 v82, v22
	v_mov_b32_e32 v83, v24
	v_pk_mul_f32 v[82:83], v[82:83], s[36:37] op_sel_hi:[1,0]
	v_mul_f32_e32 v0, 0xbfb8aa3b, v0
	v_pk_mul_f32 v[74:75], v[82:83], v[74:75]
	v_mov_b32_e32 v82, v23
	v_mov_b32_e32 v83, v25
	v_pk_mul_f32 v[82:83], v[82:83], s[36:37] op_sel_hi:[1,0]
	v_bfe_u32 v84, v68, 16, 1
	v_pk_mul_f32 v[78:79], v[82:83], v[78:79]
	v_exp_f32_e32 v81, v0
	v_bfe_u32 v82, v78, 16, 1
	v_bfe_u32 v0, v79, 16, 1
	v_bfe_u32 v83, v69, 16, 1
	v_add3_u32 v84, v68, v84, s23
	v_add3_u32 v68, v78, v82, s23
	v_bfe_u32 v82, v75, 16, 1
	v_add3_u32 v83, v69, v83, s23
	v_add3_u32 v0, v79, v0, s23
	v_bfe_u32 v69, v66, 16, 1
	v_bfe_u32 v78, v67, 16, 1
	v_bfe_u32 v79, v74, 16, 1
	v_add3_u32 v75, v75, v82, s23
	s_mul_i32 s10, s34, 0xd800
	v_add3_u32 v74, v74, v79, s23
	v_add3_u32 v67, v67, v78, s23
	v_add3_u32 v66, v66, v69, s23
	v_lshrrev_b32_e32 v69, 16, v75
	s_add_i32 s10, s10, 0
	v_lshrrev_b32_e32 v66, 16, v66
	v_lshrrev_b32_e32 v67, 16, v67
	v_lshrrev_b32_e32 v74, 16, v74
	v_and_or_b32 v69, v0, s15, v69
	v_lshlrev_b32_e32 v0, 1, v92
	v_and_or_b32 v68, v68, s15, v74
	v_and_or_b32 v67, v83, s15, v67
	v_and_or_b32 v66, v84, s15, v66
	v_add3_u32 v0, s10, v113, v0
	ds_write_b128 v0, v[66:69]
	v_mov_b32_e32 v68, v27
	v_mov_b32_e32 v69, v29
	v_mov_b32_e32 v66, v26
	v_mov_b32_e32 v67, v28
	v_pk_mul_f32 v[68:69], v[68:69], v[72:73]
	v_mov_b32_e32 v72, v51
	v_mov_b32_e32 v73, v53
	v_pk_mul_f32 v[66:67], v[66:67], v[70:71]
	v_mov_b32_e32 v70, v50
	v_mov_b32_e32 v71, v52
	v_pk_mul_f32 v[72:73], v[72:73], v[80:81]
	v_pk_mul_f32 v[70:71], v[70:71], v[76:77]
	v_bfe_u32 v74, v73, 16, 1
	v_bfe_u32 v75, v72, 16, 1
	v_bfe_u32 v76, v69, 16, 1
	v_bfe_u32 v77, v68, 16, 1
	v_add3_u32 v77, v68, v77, s23
	v_add3_u32 v76, v69, v76, s23
	v_add3_u32 v68, v72, v75, s23
	v_add3_u32 v69, v73, v74, s23
	v_bfe_u32 v72, v66, 16, 1
	v_bfe_u32 v73, v67, 16, 1
	v_bfe_u32 v74, v70, 16, 1
	v_bfe_u32 v75, v71, 16, 1
	v_add3_u32 v71, v71, v75, s23
	v_add3_u32 v70, v70, v74, s23
	v_add3_u32 v67, v67, v73, s23
	v_add3_u32 v66, v66, v72, s23
	v_lshrrev_b32_e32 v66, 16, v66
	v_lshrrev_b32_e32 v67, 16, v67
	v_lshrrev_b32_e32 v70, 16, v70
	v_lshrrev_b32_e32 v71, 16, v71
	v_and_or_b32 v69, v69, s15, v71
	v_and_or_b32 v68, v68, s15, v70
	v_and_or_b32 v67, v76, s15, v67
	v_and_or_b32 v66, v77, s15, v66
	ds_write_b128 v0, v[66:69] offset:9216
	v_mul_f32_e32 v0, 0x3fb8aa3b, v112
	v_exp_f32_e32 v0, v0
	v_bfe_u32 v66, v30, 16, 1
	v_add3_u32 v66, v30, v66, s23
	v_lshl_add_u32 v67, v114, 1, s10
	ds_write_b16_d16_hi v67, v66 offset:18432
	v_mul_f32_e32 v66, v0, v46
	v_bfe_u32 v68, v66, 16, 1
	v_add3_u32 v66, v66, v68, s23
	ds_write_b16_d16_hi v67, v66 offset:36864
	v_bfe_u32 v66, v31, 16, 1
	v_add3_u32 v66, v31, v66, s23
	ds_write_b16_d16_hi v67, v66 offset:18576
	v_mul_f32_e32 v66, v0, v47
	v_bfe_u32 v68, v66, 16, 1
	v_add3_u32 v66, v66, v68, s23
	ds_write_b16_d16_hi v67, v66 offset:37008
	v_bfe_u32 v66, v32, 16, 1
	v_add3_u32 v66, v32, v66, s23
	ds_write_b16_d16_hi v67, v66 offset:18720
	v_mul_f32_e32 v66, v0, v48
	v_bfe_u32 v68, v66, 16, 1
	v_add3_u32 v66, v66, v68, s23
	ds_write_b16_d16_hi v67, v66 offset:37152
	v_bfe_u32 v66, v33, 16, 1
	v_add3_u32 v66, v33, v66, s23
	ds_write_b16_d16_hi v67, v66 offset:18864
	v_mul_f32_e32 v66, v0, v49
	v_bfe_u32 v68, v66, 16, 1
	v_add3_u32 v66, v66, v68, s23
	ds_write_b16_d16_hi v67, v66 offset:37296
	v_bfe_u32 v66, v34, 16, 1
	v_add3_u32 v66, v34, v66, s23
	ds_write_b16_d16_hi v67, v66 offset:19008
	v_mul_f32_e32 v66, v0, v54
	v_bfe_u32 v68, v66, 16, 1
	v_add3_u32 v66, v66, v68, s23
	ds_write_b16_d16_hi v67, v66 offset:37440
	v_bfe_u32 v66, v35, 16, 1
	v_add3_u32 v66, v35, v66, s23
	ds_write_b16_d16_hi v67, v66 offset:19152
	v_mul_f32_e32 v66, v0, v55
	v_bfe_u32 v68, v66, 16, 1
	v_add3_u32 v66, v66, v68, s23
	ds_write_b16_d16_hi v67, v66 offset:37584
	v_bfe_u32 v66, v36, 16, 1
	v_add3_u32 v66, v36, v66, s23
	ds_write_b16_d16_hi v67, v66 offset:19296
	v_mul_f32_e32 v66, v0, v56
	v_bfe_u32 v68, v66, 16, 1
	v_add3_u32 v66, v66, v68, s23
	ds_write_b16_d16_hi v67, v66 offset:37728
	v_bfe_u32 v66, v37, 16, 1
	v_add3_u32 v66, v37, v66, s23
	ds_write_b16_d16_hi v67, v66 offset:19440
	v_mul_f32_e32 v66, v0, v57
	v_bfe_u32 v68, v66, 16, 1
	v_add3_u32 v66, v66, v68, s23
	ds_write_b16_d16_hi v67, v66 offset:37872
	v_bfe_u32 v66, v38, 16, 1
	v_add3_u32 v66, v38, v66, s23
	ds_write_b16_d16_hi v67, v66 offset:19584
	v_mul_f32_e32 v66, v0, v58
	v_bfe_u32 v68, v66, 16, 1
	v_add3_u32 v66, v66, v68, s23
	ds_write_b16_d16_hi v67, v66 offset:38016
	v_bfe_u32 v66, v39, 16, 1
	v_add3_u32 v66, v39, v66, s23
	ds_write_b16_d16_hi v67, v66 offset:19728
	v_mul_f32_e32 v66, v0, v59
	v_bfe_u32 v68, v66, 16, 1
	v_add3_u32 v66, v66, v68, s23
	ds_write_b16_d16_hi v67, v66 offset:38160
	v_bfe_u32 v66, v40, 16, 1
	v_add3_u32 v66, v40, v66, s23
	ds_write_b16_d16_hi v67, v66 offset:19872
	v_mul_f32_e32 v66, v0, v60
	v_bfe_u32 v68, v66, 16, 1
	v_add3_u32 v66, v66, v68, s23
	ds_write_b16_d16_hi v67, v66 offset:38304
	v_bfe_u32 v66, v41, 16, 1
	v_add3_u32 v66, v41, v66, s23
	ds_write_b16_d16_hi v67, v66 offset:20016
	v_mul_f32_e32 v66, v0, v61
	v_bfe_u32 v68, v66, 16, 1
	v_add3_u32 v66, v66, v68, s23
	ds_write_b16_d16_hi v67, v66 offset:38448
	v_bfe_u32 v66, v42, 16, 1
	v_add3_u32 v66, v42, v66, s23
	ds_write_b16_d16_hi v67, v66 offset:20160
	v_mul_f32_e32 v66, v0, v62
	v_bfe_u32 v68, v66, 16, 1
	v_add3_u32 v66, v66, v68, s23
	ds_write_b16_d16_hi v67, v66 offset:38592
	v_bfe_u32 v66, v43, 16, 1
	v_add3_u32 v66, v43, v66, s23
	ds_write_b16_d16_hi v67, v66 offset:20304
	v_mul_f32_e32 v66, v0, v63
	v_bfe_u32 v68, v66, 16, 1
	v_add3_u32 v66, v66, v68, s23
	ds_write_b16_d16_hi v67, v66 offset:38736
	v_bfe_u32 v66, v44, 16, 1
	v_add3_u32 v66, v44, v66, s23
	ds_write_b16_d16_hi v67, v66 offset:20448
	v_mul_f32_e32 v66, v0, v64
	v_bfe_u32 v68, v66, 16, 1
	v_add3_u32 v66, v66, v68, s23
	ds_write_b16_d16_hi v67, v66 offset:38880
	v_bfe_u32 v66, v45, 16, 1
	v_add3_u32 v66, v45, v66, s23
	v_mul_f32_e32 v0, v0, v65
	ds_write_b16_d16_hi v67, v66 offset:20592
	v_bfe_u32 v66, v0, 16, 1
	v_add3_u32 v0, v0, v66, s23
	ds_write_b16_d16_hi v67, v0 offset:39024
	s_branch .LBB0_1206

.LBB0_1222:
	v_ashrrev_i32_e32 v2, 6, v4
	v_ashrrev_i32_e32 v3, 31, v2
	v_lshlrev_b64 v[6:7], 6, v[2:3]
	v_and_b32_e32 v0, 56, v4
	v_lshl_add_u64 v[8:9], s[38:39], 0, v[6:7]
	v_lshl_add_u64 v[10:11], s[40:41], 0, v[6:7]
	v_lshl_add_u64 v[6:7], s[42:43], 0, v[6:7]
	v_lshl_add_u64 v[8:9], v[8:9], 0, v[0:1]
	v_lshl_add_u64 v[10:11], v[10:11], 0, v[0:1]
	v_lshl_add_u64 v[6:7], v[6:7], 0, v[0:1]
	flat_load_dwordx2 v[8:9], v[8:9]
	s_mov_b32 s8, 0x1000000
	flat_load_dwordx2 v[10:11], v[10:11]
	v_add_u32_e32 v4, s84, v4
	flat_load_dwordx2 v[6:7], v[6:7]
	s_waitcnt vmcnt(0) lgkmcnt(0)
	v_max3_f32 v0, v8, v10, v6
	v_sub_f32_e32 v8, v8, v0
	v_mul_f32_e32 v8, 0x3fb8aa3b, v8
	v_exp_f32_e32 v14, v8
	v_sub_f32_e32 v8, v10, v0
	v_sub_f32_e32 v0, v6, v0
	v_mul_f32_e32 v8, 0x3fb8aa3b, v8
	v_mul_f32_e32 v0, 0x3fb8aa3b, v0
	v_exp_f32_e32 v17, v8
	v_exp_f32_e32 v16, v0
	v_mov_b32_e32 v10, v7
	v_fma_f32 v0, v9, v14, 0
	v_pk_mul_f32 v[6:7], v[10:11], v[16:17]
	s_nop 0
	v_add_f32_e32 v0, v7, v0
	v_add_f32_e32 v15, v6, v0
	v_lshlrev_b64 v[6:7], 10, v[2:3]
	v_and_b32_e32 v0, 0x1f8, v5
	v_lshl_add_u64 v[6:7], s[6:7], 0, v[6:7]
	v_lshlrev_b32_e32 v0, 1, v0
	v_lshl_add_u64 v[10:11], v[6:7], 0, v[0:1]
	flat_load_dwordx4 v[6:9], v[10:11]
	v_lshlrev_b64 v[2:3], 12, v[2:3]
	v_lshl_add_u64 v[2:3], s[0:1], 0, v[2:3]
	v_lshl_add_u64 v[2:3], v[2:3], 0, v[0:1]
	v_add_u32_e32 v5, s12, v5
	s_waitcnt vmcnt(0) lgkmcnt(0)
	v_lshlrev_b32_e32 v18, 16, v6
	v_and_b32_e32 v20, 0xffff0000, v6
	v_add_co_u32_e32 v6, vcc, s19, v10
	v_lshlrev_b32_e32 v19, 16, v7
	v_and_b32_e32 v21, 0xffff0000, v7
	v_addc_co_u32_e32 v7, vcc, 0, v11, vcc
	v_add_co_u32_e32 v10, vcc, s8, v10
	v_lshlrev_b32_e32 v22, 16, v8
	v_and_b32_e32 v24, 0xffff0000, v8
	v_lshlrev_b32_e32 v23, 16, v9
	v_and_b32_e32 v25, 0xffff0000, v9
	flat_load_dwordx4 v[6:9], v[6:7]
	v_addc_co_u32_e32 v11, vcc, 0, v11, vcc
	flat_load_dwordx4 v[10:13], v[10:11]
	v_pk_fma_f32 v[18:19], v[14:15], v[18:19], 0 op_sel_hi:[0,1,0]
	v_pk_fma_f32 v[20:21], v[14:15], v[20:21], 0 op_sel_hi:[0,1,0]
	v_mov_b32_e32 v30, v17
	v_rcp_f32_e32 v26, v15
	s_nop 0
	v_add_co_u32_e32 v2, vcc, 0x23c00000, v2
	s_mov_b32 s8, 0x7ffff
	s_nop 0
	v_addc_co_u32_e32 v3, vcc, 0, v3, vcc
	v_cmp_lt_i32_e32 vcc, s8, v4
	s_or_b64 s[44:45], vcc, s[44:45]
	s_waitcnt vmcnt(0) lgkmcnt(0)
	v_lshlrev_b32_e32 v29, 16, v7
	v_lshlrev_b32_e32 v28, 16, v6
	v_and_b32_e32 v7, 0xffff0000, v7
	v_and_b32_e32 v6, 0xffff0000, v6
	v_pk_fma_f32 v[18:19], v[30:31], v[28:29], v[18:19] op_sel_hi:[0,1,1]
	v_pk_fma_f32 v[6:7], v[30:31], v[6:7], v[20:21] op_sel_hi:[0,1,1]
	v_lshlrev_b32_e32 v21, 16, v11
	v_lshlrev_b32_e32 v20, 16, v10
	v_pk_fma_f32 v[18:19], v[16:17], v[20:21], v[18:19] op_sel_hi:[0,1,1]
	v_and_b32_e32 v11, 0xffff0000, v11
	v_and_b32_e32 v10, 0xffff0000, v10
	v_pk_fma_f32 v[6:7], v[16:17], v[10:11], v[6:7] op_sel_hi:[0,1,1]
	v_pk_mul_f32 v[10:11], v[18:19], v[26:27] op_sel_hi:[1,0]
	v_pk_fma_f32 v[18:19], v[14:15], v[22:23], 0 op_sel_hi:[0,1,0]
	v_pk_fma_f32 v[14:15], v[14:15], v[24:25], 0 op_sel_hi:[0,1,0]
	v_lshlrev_b32_e32 v21, 16, v9
	v_lshlrev_b32_e32 v20, 16, v8
	v_and_b32_e32 v9, 0xffff0000, v9
	v_and_b32_e32 v8, 0xffff0000, v8
	v_pk_fma_f32 v[8:9], v[30:31], v[8:9], v[14:15] op_sel_hi:[0,1,1]
	v_lshlrev_b32_e32 v15, 16, v13
	v_lshlrev_b32_e32 v14, 16, v12
	v_and_b32_e32 v13, 0xffff0000, v13
	v_and_b32_e32 v12, 0xffff0000, v12
	v_pk_fma_f32 v[18:19], v[30:31], v[20:21], v[18:19] op_sel_hi:[0,1,1]
	v_pk_fma_f32 v[8:9], v[16:17], v[12:13], v[8:9] op_sel_hi:[0,1,1]
	v_pk_mul_f32 v[6:7], v[6:7], v[26:27] op_sel_hi:[1,0]
	v_pk_fma_f32 v[14:15], v[16:17], v[14:15], v[18:19] op_sel_hi:[0,1,1]
	v_pk_mul_f32 v[8:9], v[8:9], v[26:27] op_sel_hi:[1,0]
	v_pk_mul_f32 v[12:13], v[14:15], v[26:27] op_sel_hi:[1,0]
	v_bfe_u32 v14, v9, 16, 1
	v_bfe_u32 v15, v8, 16, 1
	v_bfe_u32 v16, v7, 16, 1
	v_bfe_u32 v17, v6, 16, 1
	v_add3_u32 v6, v6, v17, s23
	v_add3_u32 v7, v7, v16, s23
	v_add3_u32 v8, v8, v15, s23
	v_add3_u32 v9, v9, v14, s23
	v_bfe_u32 v14, v10, 16, 1
	v_bfe_u32 v15, v11, 16, 1
	v_bfe_u32 v16, v12, 16, 1
	v_bfe_u32 v17, v13, 16, 1
	v_add3_u32 v13, v13, v17, s23
	v_add3_u32 v12, v12, v16, s23
	v_add3_u32 v11, v11, v15, s23
	v_add3_u32 v10, v10, v14, s23
	v_lshrrev_b32_e32 v10, 16, v10
	v_lshrrev_b32_e32 v11, 16, v11
	v_lshrrev_b32_e32 v12, 16, v12
	v_lshrrev_b32_e32 v13, 16, v13
	v_and_or_b32 v9, v9, s15, v13
	v_and_or_b32 v8, v8, s15, v12
	v_and_or_b32 v7, v7, s15, v11
	v_and_or_b32 v6, v6, s15, v10
	flat_store_dwordx4 v[2:3], v[6:9] offset:2048
	s_andn2_b64 exec, exec, s[44:45]
	s_cbranch_execnz .LBB0_1222
	s_or_b64 exec, exec, s[44:45]

.LBB0_1294:
	s_waitcnt vmcnt(0) lgkmcnt(0)
	v_lshlrev_b32_e32 v192, 16, v154
	v_and_b32_e32 v193, 0xffff0000, v154
	v_lshlrev_b32_e32 v154, 16, v155
	v_and_b32_e32 v155, 0xffff0000, v155
	v_lshlrev_b32_e32 v194, 16, v156
	v_and_b32_e32 v195, 0xffff0000, v156
	v_lshlrev_b32_e32 v156, 16, v157
	s_and_b64 vcc, exec, s[40:41]
	v_and_b32_e32 v157, 0xffff0000, v157
	s_cbranch_vccnz .LBB0_1296
	v_lshlrev_b32_e32 v196, 16, v158
	v_and_b32_e32 v158, 0xffff0000, v158
	v_max_f32_e32 v158, v158, v158
	v_lshlrev_b32_e32 v197, 16, v159
	v_and_b32_e32 v202, 0xffff0000, v159
	v_max_f32_e32 v159, v196, v196
	v_max_f32_e32 v158, 0xda24260, v158
	v_max_f32_e32 v196, 0xda24260, v159
	v_lshlrev_b32_e32 v203, 16, v160
	v_and_b32_e32 v160, 0xffff0000, v160
	v_lshlrev_b32_e32 v204, 16, v161
	v_rcp_f32_e32 v159, v158
	s_nop 0
	v_and_b32_e32 v161, 0xffff0000, v161
	v_rcp_f32_e32 v158, v196
	s_nop 0
	v_pk_mul_f32 v[192:193], v[158:159], v[192:193]
	v_max_f32_e32 v159, v202, v202
	v_max_f32_e32 v159, 0xda24260, v159
	v_max_f32_e32 v158, v197, v197
	v_max_f32_e32 v158, 0xda24260, v158
	v_rcp_f32_e32 v159, v159
	s_nop 0
	s_nop 0
	v_rcp_f32_e32 v158, v158
	s_nop 0
	v_pk_mul_f32 v[154:155], v[158:159], v[154:155]
	v_max_f32_e32 v159, v160, v160
	v_max_f32_e32 v159, 0xda24260, v159
	v_max_f32_e32 v158, v203, v203
	v_max_f32_e32 v158, 0xda24260, v158
	v_rcp_f32_e32 v159, v159
	s_nop 0
	s_nop 0
	v_rcp_f32_e32 v158, v158
	s_nop 0
	v_pk_mul_f32 v[194:195], v[158:159], v[194:195]
	v_max_f32_e32 v159, v161, v161
	v_max_f32_e32 v159, 0xda24260, v159
	v_max_f32_e32 v158, v204, v204
	v_max_f32_e32 v158, 0xda24260, v158
	v_rcp_f32_e32 v159, v159
	s_nop 0
	s_nop 0
	v_rcp_f32_e32 v158, v158
	s_nop 0
	v_pk_mul_f32 v[156:157], v[158:159], v[156:157]

.LBB0_1298:
	s_nop 1
	v_lshlrev_b32_e32 v156, 16, v150
	v_and_b32_e32 v157, 0xffff0000, v150
	v_lshlrev_b32_e32 v150, 16, v151
	v_and_b32_e32 v151, 0xffff0000, v151
	v_lshlrev_b32_e32 v158, 16, v152
	v_and_b32_e32 v159, 0xffff0000, v152
	v_lshlrev_b32_e32 v152, 16, v153
	s_and_b64 vcc, exec, s[40:41]
	v_and_b32_e32 v153, 0xffff0000, v153
	s_cbranch_vccnz .LBB0_1300
	v_lshlrev_b32_e32 v160, 16, v146
	v_and_b32_e32 v146, 0xffff0000, v146
	v_max_f32_e32 v146, v146, v146
	v_lshlrev_b32_e32 v161, 16, v147
	v_and_b32_e32 v175, 0xffff0000, v147
	v_max_f32_e32 v147, v160, v160
	v_max_f32_e32 v146, 0xda24260, v146
	v_max_f32_e32 v160, 0xda24260, v147
	v_lshlrev_b32_e32 v192, 16, v148
	v_and_b32_e32 v148, 0xffff0000, v148
	v_lshlrev_b32_e32 v193, 16, v149
	v_rcp_f32_e32 v147, v146
	s_nop 0
	v_and_b32_e32 v149, 0xffff0000, v149
	v_rcp_f32_e32 v146, v160
	s_nop 0
	v_pk_mul_f32 v[156:157], v[146:147], v[156:157]
	v_max_f32_e32 v147, v175, v175
	v_max_f32_e32 v147, 0xda24260, v147
	v_max_f32_e32 v146, v161, v161
	v_max_f32_e32 v146, 0xda24260, v146
	v_rcp_f32_e32 v147, v147
	s_nop 0
	s_nop 0
	v_rcp_f32_e32 v146, v146
	s_nop 0
	v_pk_mul_f32 v[150:151], v[146:147], v[150:151]
	v_max_f32_e32 v147, v148, v148
	v_max_f32_e32 v147, 0xda24260, v147
	v_max_f32_e32 v146, v192, v192
	v_max_f32_e32 v146, 0xda24260, v146
	v_rcp_f32_e32 v147, v147
	s_nop 0
	s_nop 0
	v_rcp_f32_e32 v146, v146
	s_nop 0
	v_pk_mul_f32 v[158:159], v[146:147], v[158:159]
	v_max_f32_e32 v147, v149, v149
	v_max_f32_e32 v147, 0xda24260, v147
	v_max_f32_e32 v146, v193, v193
	v_max_f32_e32 v146, 0xda24260, v146
	v_rcp_f32_e32 v147, v147
	s_nop 0
	s_nop 0
	v_rcp_f32_e32 v146, v146
	s_nop 0
	v_pk_mul_f32 v[152:153], v[146:147], v[152:153]

.LBB0_1302:
	s_nop 1
	v_lshlrev_b32_e32 v146, 16, v142
	v_and_b32_e32 v147, 0xffff0000, v142
	v_lshlrev_b32_e32 v142, 16, v143
	v_and_b32_e32 v143, 0xffff0000, v143
	v_lshlrev_b32_e32 v148, 16, v144
	v_and_b32_e32 v149, 0xffff0000, v144
	v_lshlrev_b32_e32 v144, 16, v145
	s_and_b64 vcc, exec, s[40:41]
	v_and_b32_e32 v145, 0xffff0000, v145
	s_cbranch_vccnz .LBB0_1304
	v_lshlrev_b32_e32 v150, 16, v138
	v_and_b32_e32 v138, 0xffff0000, v138
	v_max_f32_e32 v138, v138, v138
	v_lshlrev_b32_e32 v151, 16, v139
	v_and_b32_e32 v152, 0xffff0000, v139
	v_max_f32_e32 v139, v150, v150
	v_max_f32_e32 v138, 0xda24260, v138
	v_max_f32_e32 v150, 0xda24260, v139
	v_lshlrev_b32_e32 v153, 16, v140
	v_and_b32_e32 v140, 0xffff0000, v140
	v_lshlrev_b32_e32 v154, 16, v141
	v_rcp_f32_e32 v139, v138
	s_nop 0
	v_and_b32_e32 v141, 0xffff0000, v141
	v_rcp_f32_e32 v138, v150
	s_nop 0
	v_pk_mul_f32 v[146:147], v[138:139], v[146:147]
	v_max_f32_e32 v139, v152, v152
	v_max_f32_e32 v139, 0xda24260, v139
	v_max_f32_e32 v138, v151, v151
	v_max_f32_e32 v138, 0xda24260, v138
	v_rcp_f32_e32 v139, v139
	s_nop 0
	s_nop 0
	v_rcp_f32_e32 v138, v138
	s_nop 0
	v_pk_mul_f32 v[142:143], v[138:139], v[142:143]
	v_max_f32_e32 v139, v140, v140
	v_max_f32_e32 v139, 0xda24260, v139
	v_max_f32_e32 v138, v153, v153
	v_max_f32_e32 v138, 0xda24260, v138
	v_rcp_f32_e32 v139, v139
	s_nop 0
	s_nop 0
	v_rcp_f32_e32 v138, v138
	s_nop 0
	v_pk_mul_f32 v[148:149], v[138:139], v[148:149]
	v_max_f32_e32 v139, v141, v141
	v_max_f32_e32 v139, 0xda24260, v139
	v_max_f32_e32 v138, v154, v154
	v_max_f32_e32 v138, 0xda24260, v138
	v_rcp_f32_e32 v139, v139
	s_nop 0
	s_nop 0
	v_rcp_f32_e32 v138, v138
	s_nop 0
	v_pk_mul_f32 v[144:145], v[138:139], v[144:145]

.LBB0_1306:
	s_nop 1
	v_lshlrev_b32_e32 v140, 16, v134
	v_and_b32_e32 v141, 0xffff0000, v134
	v_lshlrev_b32_e32 v134, 16, v135
	v_and_b32_e32 v135, 0xffff0000, v135
	v_lshlrev_b32_e32 v142, 16, v136
	v_and_b32_e32 v143, 0xffff0000, v136
	v_lshlrev_b32_e32 v136, 16, v137
	s_and_b64 vcc, exec, s[40:41]
	v_and_b32_e32 v137, 0xffff0000, v137
	s_cbranch_vccnz .LBB0_1308
	v_lshlrev_b32_e32 v144, 16, v130
	v_and_b32_e32 v130, 0xffff0000, v130
	v_max_f32_e32 v130, v130, v130
	v_lshlrev_b32_e32 v145, 16, v131
	v_and_b32_e32 v146, 0xffff0000, v131
	v_max_f32_e32 v131, v144, v144
	v_max_f32_e32 v130, 0xda24260, v130
	v_max_f32_e32 v144, 0xda24260, v131
	v_lshlrev_b32_e32 v147, 16, v132
	v_and_b32_e32 v132, 0xffff0000, v132
	v_lshlrev_b32_e32 v148, 16, v133
	v_rcp_f32_e32 v131, v130
	s_nop 0
	v_and_b32_e32 v133, 0xffff0000, v133
	v_rcp_f32_e32 v130, v144
	s_nop 0
	v_pk_mul_f32 v[140:141], v[130:131], v[140:141]
	v_max_f32_e32 v131, v146, v146
	v_max_f32_e32 v131, 0xda24260, v131
	v_max_f32_e32 v130, v145, v145
	v_max_f32_e32 v130, 0xda24260, v130
	v_rcp_f32_e32 v131, v131
	s_nop 0
	s_nop 0
	v_rcp_f32_e32 v130, v130
	s_nop 0
	v_pk_mul_f32 v[134:135], v[130:131], v[134:135]
	v_max_f32_e32 v131, v132, v132
	v_max_f32_e32 v131, 0xda24260, v131
	v_max_f32_e32 v130, v147, v147
	v_max_f32_e32 v130, 0xda24260, v130
	v_rcp_f32_e32 v131, v131
	s_nop 0
	s_nop 0
	v_rcp_f32_e32 v130, v130
	s_nop 0
	v_pk_mul_f32 v[142:143], v[130:131], v[142:143]
	v_max_f32_e32 v131, v133, v133
	v_max_f32_e32 v131, 0xda24260, v131
	v_max_f32_e32 v130, v148, v148
	v_max_f32_e32 v130, 0xda24260, v130
	v_rcp_f32_e32 v131, v131
	s_nop 0
	s_nop 0
	v_rcp_f32_e32 v130, v130
	s_nop 0
	v_pk_mul_f32 v[136:137], v[130:131], v[136:137]

.LBB0_1318:
	s_waitcnt vmcnt(0) lgkmcnt(0)
	v_lshlrev_b32_e32 v194, 16, v158
	v_and_b32_e32 v195, 0xffff0000, v158
	v_lshlrev_b32_e32 v158, 16, v159
	v_and_b32_e32 v159, 0xffff0000, v159
	v_lshlrev_b32_e32 v196, 16, v160
	v_and_b32_e32 v197, 0xffff0000, v160
	v_lshlrev_b32_e32 v160, 16, v161
	s_and_b64 vcc, exec, s[40:41]
	v_and_b32_e32 v161, 0xffff0000, v161
	s_cbranch_vccnz .LBB0_1320
	v_lshlrev_b32_e32 v175, 16, v154
	v_and_b32_e32 v154, 0xffff0000, v154
	v_max_f32_e32 v154, v154, v154
	v_lshlrev_b32_e32 v202, 16, v155
	v_and_b32_e32 v203, 0xffff0000, v155
	v_max_f32_e32 v155, v175, v175
	v_max_f32_e32 v154, 0xda24260, v154
	v_max_f32_e32 v175, 0xda24260, v155
	v_lshlrev_b32_e32 v204, 16, v156
	v_and_b32_e32 v156, 0xffff0000, v156
	v_lshlrev_b32_e32 v205, 16, v157
	v_rcp_f32_e32 v155, v154
	s_nop 0
	v_and_b32_e32 v157, 0xffff0000, v157
	v_rcp_f32_e32 v154, v175
	s_nop 0
	v_pk_mul_f32 v[194:195], v[154:155], v[194:195]
	v_max_f32_e32 v155, v203, v203
	v_max_f32_e32 v155, 0xda24260, v155
	v_max_f32_e32 v154, v202, v202
	v_max_f32_e32 v154, 0xda24260, v154
	v_rcp_f32_e32 v155, v155
	s_nop 0
	s_nop 0
	v_rcp_f32_e32 v154, v154
	s_nop 0
	v_pk_mul_f32 v[158:159], v[154:155], v[158:159]
	v_max_f32_e32 v155, v156, v156
	v_max_f32_e32 v155, 0xda24260, v155
	v_max_f32_e32 v154, v204, v204
	v_max_f32_e32 v154, 0xda24260, v154
	v_rcp_f32_e32 v155, v155
	s_nop 0
	s_nop 0
	v_rcp_f32_e32 v154, v154
	s_nop 0
	v_pk_mul_f32 v[196:197], v[154:155], v[196:197]
	v_max_f32_e32 v155, v157, v157
	v_max_f32_e32 v155, 0xda24260, v155
	v_max_f32_e32 v154, v205, v205
	v_max_f32_e32 v154, 0xda24260, v154
	v_rcp_f32_e32 v155, v155
	s_nop 0
	s_nop 0
	v_rcp_f32_e32 v154, v154
	s_nop 0
	v_pk_mul_f32 v[160:161], v[154:155], v[160:161]

.LBB0_1366:
	s_waitcnt vmcnt(0) lgkmcnt(0)
	v_lshlrev_b32_e32 v176, 16, v158
	v_and_b32_e32 v177, 0xffff0000, v158
	v_lshlrev_b32_e32 v158, 16, v159
	v_and_b32_e32 v159, 0xffff0000, v159
	v_lshlrev_b32_e32 v192, 16, v160
	v_and_b32_e32 v193, 0xffff0000, v160
	v_lshlrev_b32_e32 v160, 16, v161
	s_and_b64 vcc, exec, s[40:41]
	v_and_b32_e32 v161, 0xffff0000, v161
	s_cbranch_vccnz .LBB0_1368
	v_lshlrev_b32_e32 v194, 16, v154
	v_and_b32_e32 v154, 0xffff0000, v154
	v_max_f32_e32 v154, v154, v154
	v_lshlrev_b32_e32 v195, 16, v155
	v_and_b32_e32 v196, 0xffff0000, v155
	v_max_f32_e32 v155, v194, v194
	v_max_f32_e32 v154, 0xda24260, v154
	v_max_f32_e32 v194, 0xda24260, v155
	v_lshlrev_b32_e32 v197, 16, v156
	v_and_b32_e32 v156, 0xffff0000, v156
	v_lshlrev_b32_e32 v202, 16, v157
	v_rcp_f32_e32 v155, v154
	s_nop 0
	v_and_b32_e32 v157, 0xffff0000, v157
	v_rcp_f32_e32 v154, v194
	s_nop 0
	v_pk_mul_f32 v[176:177], v[154:155], v[176:177]
	v_max_f32_e32 v155, v196, v196
	v_max_f32_e32 v155, 0xda24260, v155
	v_max_f32_e32 v154, v195, v195
	v_max_f32_e32 v154, 0xda24260, v154
	v_rcp_f32_e32 v155, v155
	s_nop 0
	s_nop 0
	v_rcp_f32_e32 v154, v154
	s_nop 0
	v_pk_mul_f32 v[158:159], v[154:155], v[158:159]
	v_max_f32_e32 v155, v156, v156
	v_max_f32_e32 v155, 0xda24260, v155
	v_max_f32_e32 v154, v197, v197
	v_max_f32_e32 v154, 0xda24260, v154
	v_rcp_f32_e32 v155, v155
	s_nop 0
	s_nop 0
	v_rcp_f32_e32 v154, v154
	s_nop 0
	v_pk_mul_f32 v[192:193], v[154:155], v[192:193]
	v_max_f32_e32 v155, v157, v157
	v_max_f32_e32 v155, 0xda24260, v155
	v_max_f32_e32 v154, v202, v202
	v_max_f32_e32 v154, 0xda24260, v154
	v_rcp_f32_e32 v155, v155
	s_nop 0
	s_nop 0
	v_rcp_f32_e32 v154, v154
	s_nop 0
	v_pk_mul_f32 v[160:161], v[154:155], v[160:161]

.LBB0_1370:
	s_nop 1
	v_lshlrev_b32_e32 v156, 16, v150
	v_and_b32_e32 v157, 0xffff0000, v150
	v_lshlrev_b32_e32 v150, 16, v151
	v_and_b32_e32 v151, 0xffff0000, v151
	v_lshlrev_b32_e32 v158, 16, v152
	v_and_b32_e32 v159, 0xffff0000, v152
	v_lshlrev_b32_e32 v152, 16, v153
	s_and_b64 vcc, exec, s[40:41]
	v_and_b32_e32 v153, 0xffff0000, v153
	s_cbranch_vccnz .LBB0_1372
	v_lshlrev_b32_e32 v160, 16, v146
	v_and_b32_e32 v146, 0xffff0000, v146
	v_max_f32_e32 v146, v146, v146
	v_lshlrev_b32_e32 v161, 16, v147
	v_and_b32_e32 v176, 0xffff0000, v147
	v_max_f32_e32 v147, v160, v160
	v_max_f32_e32 v146, 0xda24260, v146
	v_max_f32_e32 v160, 0xda24260, v147
	v_lshlrev_b32_e32 v177, 16, v148
	v_and_b32_e32 v148, 0xffff0000, v148
	v_lshlrev_b32_e32 v190, 16, v149
	v_rcp_f32_e32 v147, v146
	s_nop 0
	v_and_b32_e32 v149, 0xffff0000, v149
	v_rcp_f32_e32 v146, v160
	s_nop 0
	v_pk_mul_f32 v[156:157], v[146:147], v[156:157]
	v_max_f32_e32 v147, v176, v176
	v_max_f32_e32 v147, 0xda24260, v147
	v_max_f32_e32 v146, v161, v161
	v_max_f32_e32 v146, 0xda24260, v146
	v_rcp_f32_e32 v147, v147
	s_nop 0
	s_nop 0
	v_rcp_f32_e32 v146, v146
	s_nop 0
	v_pk_mul_f32 v[150:151], v[146:147], v[150:151]
	v_max_f32_e32 v147, v148, v148
	v_max_f32_e32 v147, 0xda24260, v147
	v_max_f32_e32 v146, v177, v177
	v_max_f32_e32 v146, 0xda24260, v146
	v_rcp_f32_e32 v147, v147
	s_nop 0
	s_nop 0
	v_rcp_f32_e32 v146, v146
	s_nop 0
	v_pk_mul_f32 v[158:159], v[146:147], v[158:159]
	v_max_f32_e32 v147, v149, v149
	v_max_f32_e32 v147, 0xda24260, v147
	v_max_f32_e32 v146, v190, v190
	v_max_f32_e32 v146, 0xda24260, v146
	v_rcp_f32_e32 v147, v147
	s_nop 0
	s_nop 0
	v_rcp_f32_e32 v146, v146
	s_nop 0
	v_pk_mul_f32 v[152:153], v[146:147], v[152:153]

.LBB0_1542:
	v_lshl_add_u32 v140, s11, 8, v146
	v_ashrrev_i32_e32 v141, 31, v140
	v_lshl_add_u64 v[142:143], v[140:141], 2, s[46:47]
	flat_load_dword v144, v[142:143]
	flat_load_dword v162, v[142:143] offset:64
	flat_load_dword v160, v[142:143] offset:128
	flat_load_dword v158, v[142:143] offset:192
	flat_load_dword v156, v[142:143] offset:512
	flat_load_dword v154, v[142:143] offset:576
	flat_load_dword v152, v[142:143] offset:640
	flat_load_dword v150, v[142:143] offset:704
	v_mov_b32_e32 v164, v122
	v_mov_b32_e32 v165, v126
	v_lshl_or_b32 v142, s8, 7, v148
	v_ashrrev_i32_e32 v143, 31, v142
	s_movk_i32 s6, 0x2c00
	v_or_b32_e32 v161, 16, v140
	v_or_b32_e32 v159, 32, v140
	v_or_b32_e32 v157, 48, v140
	v_add_u32_e32 v155, 0x80, v140
	v_add_u32_e32 v153, 0x90, v140
	v_add_u32_e32 v151, 0xa0, v140
	v_add_u32_e32 v141, 0xb0, v140
	s_waitcnt vmcnt(0) lgkmcnt(0)
	v_fmamk_f32 v144, v144, 0x3a000000, v224
	v_cmp_gt_f32_e32 vcc, s19, v144
	v_mul_f32_e32 v163, 0x4b800000, v144
	s_nop 0
	v_cndmask_b32_e32 v144, v144, v163, vcc
	v_rsq_f32_e32 v144, v144
	s_nop 0
	v_mul_f32_e32 v163, 0x45800000, v144
	v_cndmask_b32_e32 v144, v144, v163, vcc
	v_pk_mul_f32 v[164:165], v[164:165], v[144:145] op_sel_hi:[1,0]
	s_nop 0
	v_mul_f32_e32 v122, 0xbfb8aa3b, v165
	v_exp_f32_e32 v122, v122
	s_nop 0
	v_add_f32_e32 v122, 1.0, v122
	s_nop 0
	v_rcp_f32_e32 v122, v122
	s_nop 0
	v_mul_f32_e32 v122, v165, v122
	v_mov_b32_e32 v126, v123
	v_mul_f32_e32 v163, v164, v122
	v_pk_mul_f32 v[122:123], v[126:127], v[144:145] op_sel_hi:[1,0]
	s_nop 0
	v_mul_f32_e32 v126, 0xbfb8aa3b, v123
	v_exp_f32_e32 v126, v126
	s_nop 0
	v_add_f32_e32 v126, 1.0, v126
	s_nop 0
	v_rcp_f32_e32 v126, v126
	s_nop 0
	v_mul_f32_e32 v123, v123, v126
	v_mul_f32_e32 v126, v122, v123
	v_mov_b32_e32 v122, v124
	v_mov_b32_e32 v123, v128
	v_pk_mul_f32 v[122:123], v[122:123], v[144:145] op_sel_hi:[1,0]
	s_nop 0
	v_mul_f32_e32 v124, 0xbfb8aa3b, v123
	v_exp_f32_e32 v124, v124
	s_nop 0
	v_add_f32_e32 v124, 1.0, v124
	s_nop 0
	v_rcp_f32_e32 v124, v124
	s_nop 0
	v_mul_f32_e32 v123, v123, v124
	v_mov_b32_e32 v128, v125
	v_mul_f32_e32 v124, v122, v123
	v_pk_mul_f32 v[122:123], v[128:129], v[144:145] op_sel_hi:[1,0]
	s_nop 0
	v_mul_f32_e32 v125, 0xbfb8aa3b, v123
	v_exp_f32_e32 v125, v125
	s_nop 0
	v_add_f32_e32 v125, 1.0, v125
	s_nop 0
	v_rcp_f32_e32 v125, v125
	s_nop 0
	v_mul_f32_e32 v123, v123, v125
	v_mul_f32_e32 v125, v122, v123
	v_mov_b32_e32 v122, v114
	v_mov_b32_e32 v123, v118
	v_pk_mul_f32 v[122:123], v[122:123], v[144:145] op_sel_hi:[1,0]
	s_nop 0
	v_mul_f32_e32 v114, 0xbfb8aa3b, v123
	v_exp_f32_e32 v114, v114
	s_nop 0
	v_add_f32_e32 v114, 1.0, v114
	s_nop 0
	v_rcp_f32_e32 v114, v114
	s_nop 0
	v_mul_f32_e32 v114, v123, v114
	v_mov_b32_e32 v118, v115
	v_mul_f32_e32 v122, v122, v114
	v_pk_mul_f32 v[114:115], v[118:119], v[144:145] op_sel_hi:[1,0]
	s_nop 0
	v_mul_f32_e32 v118, 0xbfb8aa3b, v115
	v_exp_f32_e32 v118, v118
	s_nop 0
	v_add_f32_e32 v118, 1.0, v118
	s_nop 0
	v_rcp_f32_e32 v118, v118
	s_nop 0
	v_mul_f32_e32 v115, v115, v118
	v_mul_f32_e32 v123, v114, v115
	v_mov_b32_e32 v114, v116
	v_mov_b32_e32 v115, v120
	v_pk_mul_f32 v[114:115], v[114:115], v[144:145] op_sel_hi:[1,0]
	s_nop 0
	v_mul_f32_e32 v116, 0xbfb8aa3b, v115
	v_exp_f32_e32 v116, v116
	s_nop 0
	v_add_f32_e32 v116, 1.0, v116
	s_nop 0
	v_rcp_f32_e32 v116, v116
	s_nop 0
	v_mul_f32_e32 v115, v115, v116
	v_mov_b32_e32 v120, v117
	v_mul_f32_e32 v116, v114, v115
	v_pk_mul_f32 v[114:115], v[120:121], v[144:145] op_sel_hi:[1,0]
	s_nop 0
	v_mul_f32_e32 v117, 0xbfb8aa3b, v115
	v_exp_f32_e32 v117, v117
	s_nop 0
	v_add_f32_e32 v117, 1.0, v117
	s_nop 0
	v_rcp_f32_e32 v117, v117
	s_nop 0
	v_mul_f32_e32 v115, v115, v117
	v_mul_f32_e32 v114, v114, v115
	v_cvt_pk_bf16_f32 v118, v163, v126
	v_cvt_pk_bf16_f32 v119, v124, v125
	v_cvt_pk_bf16_f32 v120, v122, v123
	v_cvt_pk_bf16_f32 v121, v116, v114
	v_mov_b64_e32 v[114:115], s[44:45]
	v_mad_i64_i32 v[122:123], s[4:5], v140, s6, v[114:115]
	v_lshlrev_b64 v[116:117], 1, v[142:143]
	v_lshl_add_u64 v[122:123], v[122:123], 0, v[116:117]
	flat_store_dwordx4 v[122:123], v[118:121] nt
	s_nop 1
	v_fmamk_f32 v118, v162, 0x3a000000, v224
	v_cmp_gt_f32_e32 vcc, s19, v118
	v_mul_f32_e32 v119, 0x4b800000, v118
	v_mov_b32_e32 v120, v106
	v_cndmask_b32_e32 v118, v118, v119, vcc
	v_rsq_f32_e32 v118, v118
	v_mov_b32_e32 v121, v110
	v_mul_f32_e32 v119, 0x45800000, v118
	v_cndmask_b32_e32 v118, v118, v119, vcc
	v_pk_mul_f32 v[120:121], v[120:121], v[118:119] op_sel_hi:[1,0]
	s_nop 0
	v_mul_f32_e32 v106, 0xbfb8aa3b, v121
	v_exp_f32_e32 v106, v106
	s_nop 0
	v_add_f32_e32 v106, 1.0, v106
	s_nop 0
	v_rcp_f32_e32 v106, v106
	s_nop 0
	v_mul_f32_e32 v106, v121, v106
	v_mul_f32_e32 v119, v120, v106
	v_mov_b32_e32 v110, v107
	v_pk_mul_f32 v[106:107], v[110:111], v[118:119] op_sel_hi:[1,0]
	s_nop 0
	v_mul_f32_e32 v110, 0xbfb8aa3b, v107
	v_exp_f32_e32 v110, v110
	s_nop 0
	v_add_f32_e32 v110, 1.0, v110
	s_nop 0
	v_rcp_f32_e32 v110, v110
	s_nop 0
	v_mul_f32_e32 v107, v107, v110
	v_mul_f32_e32 v110, v106, v107
	v_mov_b32_e32 v106, v108
	v_mov_b32_e32 v107, v112
	v_pk_mul_f32 v[106:107], v[106:107], v[118:119] op_sel_hi:[1,0]
	s_nop 0
	v_mul_f32_e32 v108, 0xbfb8aa3b, v107
	v_exp_f32_e32 v108, v108
	s_nop 0
	v_add_f32_e32 v108, 1.0, v108
	s_nop 0
	v_rcp_f32_e32 v108, v108
	s_nop 0
	v_mul_f32_e32 v107, v107, v108
	v_mov_b32_e32 v112, v109
	v_mul_f32_e32 v108, v106, v107
	v_pk_mul_f32 v[106:107], v[112:113], v[118:119] op_sel_hi:[1,0]
	s_nop 0
	v_mul_f32_e32 v109, 0xbfb8aa3b, v107
	v_exp_f32_e32 v109, v109
	s_nop 0
	v_add_f32_e32 v109, 1.0, v109
	s_nop 0
	v_rcp_f32_e32 v109, v109
	s_nop 0
	v_mul_f32_e32 v107, v107, v109
	v_mul_f32_e32 v109, v106, v107
	v_mov_b32_e32 v106, v98
	v_mov_b32_e32 v107, v102
	v_pk_mul_f32 v[106:107], v[106:107], v[118:119] op_sel_hi:[1,0]
	s_nop 0
	v_mul_f32_e32 v98, 0xbfb8aa3b, v107
	v_exp_f32_e32 v98, v98
	s_nop 0
	v_add_f32_e32 v98, 1.0, v98
	s_nop 0
	v_rcp_f32_e32 v98, v98
	s_nop 0
	v_mul_f32_e32 v98, v107, v98
	v_mov_b32_e32 v102, v99
	v_mul_f32_e32 v106, v106, v98
	v_pk_mul_f32 v[98:99], v[102:103], v[118:119] op_sel_hi:[1,0]
	s_nop 0
	v_mul_f32_e32 v102, 0xbfb8aa3b, v99
	v_exp_f32_e32 v102, v102
	s_nop 0
	v_add_f32_e32 v102, 1.0, v102
	s_nop 0
	v_rcp_f32_e32 v102, v102
	s_nop 0
	v_mul_f32_e32 v99, v99, v102
	v_mul_f32_e32 v102, v98, v99
	v_mov_b32_e32 v98, v100
	v_mov_b32_e32 v99, v104
	v_pk_mul_f32 v[98:99], v[98:99], v[118:119] op_sel_hi:[1,0]
	s_nop 0
	v_mul_f32_e32 v100, 0xbfb8aa3b, v99
	v_exp_f32_e32 v100, v100
	s_nop 0
	v_add_f32_e32 v100, 1.0, v100
	s_nop 0
	v_rcp_f32_e32 v100, v100
	s_nop 0
	v_mul_f32_e32 v99, v99, v100
	v_mov_b32_e32 v104, v101
	v_mul_f32_e32 v103, v98, v99
	v_pk_mul_f32 v[98:99], v[104:105], v[118:119] op_sel_hi:[1,0]
	s_nop 0
	v_mul_f32_e32 v100, 0xbfb8aa3b, v99
	v_exp_f32_e32 v100, v100
	s_nop 0
	v_add_f32_e32 v100, 1.0, v100
	s_nop 0
	v_rcp_f32_e32 v100, v100
	s_nop 0
	v_mul_f32_e32 v99, v99, v100
	v_mul_f32_e32 v101, v98, v99
	v_cvt_pk_bf16_f32 v98, v119, v110
	v_cvt_pk_bf16_f32 v99, v108, v109
	v_cvt_pk_bf16_f32 v100, v106, v102
	v_cvt_pk_bf16_f32 v101, v103, v101
	v_mad_i64_i32 v[102:103], s[4:5], v161, s6, v[114:115]
	v_lshl_add_u64 v[102:103], v[102:103], 0, v[116:117]
	flat_store_dwordx4 v[102:103], v[98:101] nt
	s_nop 1
	v_fmamk_f32 v98, v160, 0x3a000000, v224
	v_cmp_gt_f32_e32 vcc, s19, v98
	v_mul_f32_e32 v99, 0x4b800000, v98
	v_mov_b32_e32 v100, v90
	v_cndmask_b32_e32 v98, v98, v99, vcc
	v_rsq_f32_e32 v98, v98
	v_mov_b32_e32 v101, v94
	v_mul_f32_e32 v99, 0x45800000, v98
	v_cndmask_b32_e32 v98, v98, v99, vcc
	v_pk_mul_f32 v[100:101], v[100:101], v[98:99] op_sel_hi:[1,0]
	s_nop 0
	v_mul_f32_e32 v90, 0xbfb8aa3b, v101
	v_exp_f32_e32 v90, v90
	s_nop 0
	v_add_f32_e32 v90, 1.0, v90
	s_nop 0
	v_rcp_f32_e32 v90, v90
	s_nop 0
	v_mul_f32_e32 v90, v101, v90
	v_mul_f32_e32 v99, v100, v90
	v_mov_b32_e32 v94, v91
	v_pk_mul_f32 v[90:91], v[94:95], v[98:99] op_sel_hi:[1,0]
	s_nop 0
	v_mul_f32_e32 v94, 0xbfb8aa3b, v91
	v_exp_f32_e32 v94, v94
	s_nop 0
	v_add_f32_e32 v94, 1.0, v94
	s_nop 0
	v_rcp_f32_e32 v94, v94
	s_nop 0
	v_mul_f32_e32 v91, v91, v94
	v_mul_f32_e32 v94, v90, v91
	v_mov_b32_e32 v90, v92
	v_mov_b32_e32 v91, v96
	v_pk_mul_f32 v[90:91], v[90:91], v[98:99] op_sel_hi:[1,0]
	s_nop 0
	v_mul_f32_e32 v92, 0xbfb8aa3b, v91
	v_exp_f32_e32 v92, v92
	s_nop 0
	v_add_f32_e32 v92, 1.0, v92
	s_nop 0
	v_rcp_f32_e32 v92, v92
	s_nop 0
	v_mul_f32_e32 v91, v91, v92
	v_mov_b32_e32 v96, v93
	v_mul_f32_e32 v92, v90, v91
	v_pk_mul_f32 v[90:91], v[96:97], v[98:99] op_sel_hi:[1,0]
	s_nop 0
	v_mul_f32_e32 v93, 0xbfb8aa3b, v91
	v_exp_f32_e32 v93, v93
	s_nop 0
	v_add_f32_e32 v93, 1.0, v93
	s_nop 0
	v_rcp_f32_e32 v93, v93
	s_nop 0
	v_mul_f32_e32 v91, v91, v93
	v_mul_f32_e32 v93, v90, v91
	v_mov_b32_e32 v90, v82
	v_mov_b32_e32 v91, v86
	v_pk_mul_f32 v[90:91], v[90:91], v[98:99] op_sel_hi:[1,0]
	s_nop 0
	v_mul_f32_e32 v82, 0xbfb8aa3b, v91
	v_exp_f32_e32 v82, v82
	s_nop 0
	v_add_f32_e32 v82, 1.0, v82
	s_nop 0
	v_rcp_f32_e32 v82, v82
	s_nop 0
	v_mul_f32_e32 v82, v91, v82
	v_mov_b32_e32 v86, v83
	v_mul_f32_e32 v90, v90, v82
	v_pk_mul_f32 v[82:83], v[86:87], v[98:99] op_sel_hi:[1,0]
	s_nop 0
	v_mul_f32_e32 v86, 0xbfb8aa3b, v83
	v_exp_f32_e32 v86, v86
	s_nop 0
	v_add_f32_e32 v86, 1.0, v86
	s_nop 0
	v_rcp_f32_e32 v86, v86
	s_nop 0
	v_mul_f32_e32 v83, v83, v86
	v_mul_f32_e32 v86, v82, v83
	v_mov_b32_e32 v82, v84
	v_mov_b32_e32 v83, v88
	v_pk_mul_f32 v[82:83], v[82:83], v[98:99] op_sel_hi:[1,0]
	s_nop 0
	v_mul_f32_e32 v84, 0xbfb8aa3b, v83
	v_exp_f32_e32 v84, v84
	s_nop 0
	v_add_f32_e32 v84, 1.0, v84
	s_nop 0
	v_rcp_f32_e32 v84, v84
	s_nop 0
	v_mul_f32_e32 v83, v83, v84
	v_mov_b32_e32 v88, v85
	v_mul_f32_e32 v87, v82, v83
	v_pk_mul_f32 v[82:83], v[88:89], v[98:99] op_sel_hi:[1,0]
	s_nop 0
	v_mul_f32_e32 v84, 0xbfb8aa3b, v83
	v_exp_f32_e32 v84, v84
	s_nop 0
	v_add_f32_e32 v84, 1.0, v84
	s_nop 0
	v_rcp_f32_e32 v84, v84
	s_nop 0
	v_mul_f32_e32 v83, v83, v84
	v_mul_f32_e32 v85, v82, v83
	v_cvt_pk_bf16_f32 v82, v99, v94
	v_cvt_pk_bf16_f32 v83, v92, v93
	v_cvt_pk_bf16_f32 v84, v90, v86
	v_cvt_pk_bf16_f32 v85, v87, v85
	v_mad_i64_i32 v[86:87], s[4:5], v159, s6, v[114:115]
	v_lshl_add_u64 v[86:87], v[86:87], 0, v[116:117]
	flat_store_dwordx4 v[86:87], v[82:85] nt
	s_nop 1
	v_fmamk_f32 v82, v158, 0x3a000000, v224
	v_cmp_gt_f32_e32 vcc, s19, v82
	v_mul_f32_e32 v83, 0x4b800000, v82
	v_mov_b32_e32 v84, v74
	v_cndmask_b32_e32 v82, v82, v83, vcc
	v_rsq_f32_e32 v82, v82
	v_mov_b32_e32 v85, v78
	v_mul_f32_e32 v83, 0x45800000, v82
	v_cndmask_b32_e32 v82, v82, v83, vcc
	v_pk_mul_f32 v[84:85], v[84:85], v[82:83] op_sel_hi:[1,0]
	s_nop 0
	v_mul_f32_e32 v74, 0xbfb8aa3b, v85
	v_exp_f32_e32 v74, v74
	s_nop 0
	v_add_f32_e32 v74, 1.0, v74
	s_nop 0
	v_rcp_f32_e32 v74, v74
	s_nop 0
	v_mul_f32_e32 v74, v85, v74
	v_mul_f32_e32 v83, v84, v74
	v_mov_b32_e32 v78, v75
	v_pk_mul_f32 v[74:75], v[78:79], v[82:83] op_sel_hi:[1,0]
	s_nop 0
	v_mul_f32_e32 v78, 0xbfb8aa3b, v75
	v_exp_f32_e32 v78, v78
	s_nop 0
	v_add_f32_e32 v78, 1.0, v78
	s_nop 0
	v_rcp_f32_e32 v78, v78
	s_nop 0
	v_mul_f32_e32 v75, v75, v78
	v_mul_f32_e32 v78, v74, v75
	v_mov_b32_e32 v74, v76
	v_mov_b32_e32 v75, v80
	v_pk_mul_f32 v[74:75], v[74:75], v[82:83] op_sel_hi:[1,0]
	s_nop 0
	v_mul_f32_e32 v76, 0xbfb8aa3b, v75
	v_exp_f32_e32 v76, v76
	s_nop 0
	v_add_f32_e32 v76, 1.0, v76
	s_nop 0
	v_rcp_f32_e32 v76, v76
	s_nop 0
	v_mul_f32_e32 v75, v75, v76
	v_mov_b32_e32 v80, v77
	v_mul_f32_e32 v76, v74, v75
	v_pk_mul_f32 v[74:75], v[80:81], v[82:83] op_sel_hi:[1,0]
	s_nop 0
	v_mul_f32_e32 v77, 0xbfb8aa3b, v75
	v_exp_f32_e32 v77, v77
	s_nop 0
	v_add_f32_e32 v77, 1.0, v77
	s_nop 0
	v_rcp_f32_e32 v77, v77
	s_nop 0
	v_mul_f32_e32 v75, v75, v77
	v_mul_f32_e32 v77, v74, v75
	v_mov_b32_e32 v74, v66
	v_mov_b32_e32 v75, v70
	v_pk_mul_f32 v[74:75], v[74:75], v[82:83] op_sel_hi:[1,0]
	s_nop 0
	v_mul_f32_e32 v66, 0xbfb8aa3b, v75
	v_exp_f32_e32 v66, v66
	s_nop 0
	v_add_f32_e32 v66, 1.0, v66
	s_nop 0
	v_rcp_f32_e32 v66, v66
	s_nop 0
	v_mul_f32_e32 v66, v75, v66
	v_mov_b32_e32 v70, v67
	v_mul_f32_e32 v74, v74, v66
	v_pk_mul_f32 v[66:67], v[70:71], v[82:83] op_sel_hi:[1,0]
	s_nop 0
	v_mul_f32_e32 v70, 0xbfb8aa3b, v67
	v_exp_f32_e32 v70, v70
	s_nop 0
	v_add_f32_e32 v70, 1.0, v70
	s_nop 0
	v_rcp_f32_e32 v70, v70
	s_nop 0
	v_mul_f32_e32 v67, v67, v70
	v_mul_f32_e32 v70, v66, v67
	v_mov_b32_e32 v66, v68
	v_mov_b32_e32 v67, v72
	v_pk_mul_f32 v[66:67], v[66:67], v[82:83] op_sel_hi:[1,0]
	s_nop 0
	v_mul_f32_e32 v68, 0xbfb8aa3b, v67
	v_exp_f32_e32 v68, v68
	s_nop 0
	v_add_f32_e32 v68, 1.0, v68
	s_nop 0
	v_rcp_f32_e32 v68, v68
	s_nop 0
	v_mul_f32_e32 v67, v67, v68
	v_mov_b32_e32 v72, v69
	v_mul_f32_e32 v71, v66, v67
	v_pk_mul_f32 v[66:67], v[72:73], v[82:83] op_sel_hi:[1,0]
	s_nop 0
	v_mul_f32_e32 v68, 0xbfb8aa3b, v67
	v_exp_f32_e32 v68, v68
	s_nop 0
	v_add_f32_e32 v68, 1.0, v68
	s_nop 0
	v_rcp_f32_e32 v68, v68
	s_nop 0
	v_mul_f32_e32 v67, v67, v68
	v_mul_f32_e32 v69, v66, v67
	v_cvt_pk_bf16_f32 v66, v83, v78
	v_cvt_pk_bf16_f32 v67, v76, v77
	v_cvt_pk_bf16_f32 v68, v74, v70
	v_cvt_pk_bf16_f32 v69, v71, v69
	v_mad_i64_i32 v[70:71], s[4:5], v157, s6, v[114:115]
	v_lshl_add_u64 v[70:71], v[70:71], 0, v[116:117]
	flat_store_dwordx4 v[70:71], v[66:69] nt
	s_nop 1
	v_fmamk_f32 v66, v156, 0x3a000000, v224
	v_cmp_gt_f32_e32 vcc, s19, v66
	v_mul_f32_e32 v67, 0x4b800000, v66
	v_mov_b32_e32 v68, v58
	v_cndmask_b32_e32 v66, v66, v67, vcc
	v_rsq_f32_e32 v66, v66
	v_mov_b32_e32 v69, v62
	v_mul_f32_e32 v67, 0x45800000, v66
	v_cndmask_b32_e32 v66, v66, v67, vcc
	v_pk_mul_f32 v[68:69], v[68:69], v[66:67] op_sel_hi:[1,0]
	s_nop 0
	v_mul_f32_e32 v58, 0xbfb8aa3b, v69
	v_exp_f32_e32 v58, v58
	s_nop 0
	v_add_f32_e32 v58, 1.0, v58
	s_nop 0
	v_rcp_f32_e32 v58, v58
	s_nop 0
	v_mul_f32_e32 v58, v69, v58
	v_mul_f32_e32 v67, v68, v58
	v_mov_b32_e32 v62, v59
	v_pk_mul_f32 v[58:59], v[62:63], v[66:67] op_sel_hi:[1,0]
	s_nop 0
	v_mul_f32_e32 v62, 0xbfb8aa3b, v59
	v_exp_f32_e32 v62, v62
	s_nop 0
	v_add_f32_e32 v62, 1.0, v62
	s_nop 0
	v_rcp_f32_e32 v62, v62
	s_nop 0
	v_mul_f32_e32 v59, v59, v62
	v_mul_f32_e32 v62, v58, v59
	v_mov_b32_e32 v58, v60
	v_mov_b32_e32 v59, v64
	v_pk_mul_f32 v[58:59], v[58:59], v[66:67] op_sel_hi:[1,0]
	s_nop 0
	v_mul_f32_e32 v60, 0xbfb8aa3b, v59
	v_exp_f32_e32 v60, v60
	s_nop 0
	v_add_f32_e32 v60, 1.0, v60
	s_nop 0
	v_rcp_f32_e32 v60, v60
	s_nop 0
	v_mul_f32_e32 v59, v59, v60
	v_mov_b32_e32 v64, v61
	v_mul_f32_e32 v60, v58, v59
	v_pk_mul_f32 v[58:59], v[64:65], v[66:67] op_sel_hi:[1,0]
	s_nop 0
	v_mul_f32_e32 v61, 0xbfb8aa3b, v59
	v_exp_f32_e32 v61, v61
	s_nop 0
	v_add_f32_e32 v61, 1.0, v61
	s_nop 0
	v_rcp_f32_e32 v61, v61
	s_nop 0
	v_mul_f32_e32 v59, v59, v61
	v_mul_f32_e32 v61, v58, v59
	v_mov_b32_e32 v58, v50
	v_mov_b32_e32 v59, v54
	v_pk_mul_f32 v[58:59], v[58:59], v[66:67] op_sel_hi:[1,0]
	s_nop 0
	v_mul_f32_e32 v50, 0xbfb8aa3b, v59
	v_exp_f32_e32 v50, v50
	s_nop 0
	v_add_f32_e32 v50, 1.0, v50
	s_nop 0
	v_rcp_f32_e32 v50, v50
	s_nop 0
	v_mul_f32_e32 v50, v59, v50
	v_mov_b32_e32 v54, v51
	v_mul_f32_e32 v58, v58, v50
	v_pk_mul_f32 v[50:51], v[54:55], v[66:67] op_sel_hi:[1,0]
	s_nop 0
	v_mul_f32_e32 v54, 0xbfb8aa3b, v51
	v_exp_f32_e32 v54, v54
	s_nop 0
	v_add_f32_e32 v54, 1.0, v54
	s_nop 0
	v_rcp_f32_e32 v54, v54
	s_nop 0
	v_mul_f32_e32 v51, v51, v54
	v_mul_f32_e32 v54, v50, v51
	v_mov_b32_e32 v50, v52
	v_mov_b32_e32 v51, v56
	v_pk_mul_f32 v[50:51], v[50:51], v[66:67] op_sel_hi:[1,0]
	s_nop 0
	v_mul_f32_e32 v52, 0xbfb8aa3b, v51
	v_exp_f32_e32 v52, v52
	s_nop 0
	v_add_f32_e32 v52, 1.0, v52
	s_nop 0
	v_rcp_f32_e32 v52, v52
	s_nop 0
	v_mul_f32_e32 v51, v51, v52
	v_mov_b32_e32 v56, v53
	v_mul_f32_e32 v55, v50, v51
	v_pk_mul_f32 v[50:51], v[56:57], v[66:67] op_sel_hi:[1,0]
	s_nop 0
	v_mul_f32_e32 v52, 0xbfb8aa3b, v51
	v_exp_f32_e32 v52, v52
	s_nop 0
	v_add_f32_e32 v52, 1.0, v52
	s_nop 0
	v_rcp_f32_e32 v52, v52
	s_nop 0
	v_mul_f32_e32 v51, v51, v52
	v_mul_f32_e32 v53, v50, v51
	v_cvt_pk_bf16_f32 v50, v67, v62
	v_cvt_pk_bf16_f32 v51, v60, v61
	v_cvt_pk_bf16_f32 v52, v58, v54
	v_cvt_pk_bf16_f32 v53, v55, v53
	v_mad_i64_i32 v[54:55], s[4:5], v155, s6, v[114:115]
	v_lshl_add_u64 v[54:55], v[54:55], 0, v[116:117]
	flat_store_dwordx4 v[54:55], v[50:53] nt
	s_nop 1
	v_fmamk_f32 v50, v154, 0x3a000000, v224
	v_cmp_gt_f32_e32 vcc, s19, v50
	v_mul_f32_e32 v51, 0x4b800000, v50
	v_mov_b32_e32 v52, v42
	v_cndmask_b32_e32 v50, v50, v51, vcc
	v_rsq_f32_e32 v50, v50
	v_mov_b32_e32 v53, v46
	v_mul_f32_e32 v51, 0x45800000, v50
	v_cndmask_b32_e32 v50, v50, v51, vcc
	v_pk_mul_f32 v[52:53], v[52:53], v[50:51] op_sel_hi:[1,0]
	s_nop 0
	v_mul_f32_e32 v42, 0xbfb8aa3b, v53
	v_exp_f32_e32 v42, v42
	s_nop 0
	v_add_f32_e32 v42, 1.0, v42
	s_nop 0
	v_rcp_f32_e32 v42, v42
	s_nop 0
	v_mul_f32_e32 v42, v53, v42
	v_mul_f32_e32 v51, v52, v42
	v_mov_b32_e32 v46, v43
	v_pk_mul_f32 v[42:43], v[46:47], v[50:51] op_sel_hi:[1,0]
	s_nop 0
	v_mul_f32_e32 v46, 0xbfb8aa3b, v43
	v_exp_f32_e32 v46, v46
	s_nop 0
	v_add_f32_e32 v46, 1.0, v46
	s_nop 0
	v_rcp_f32_e32 v46, v46
	s_nop 0
	v_mul_f32_e32 v43, v43, v46
	v_mul_f32_e32 v46, v42, v43
	v_mov_b32_e32 v42, v44
	v_mov_b32_e32 v43, v48
	v_pk_mul_f32 v[42:43], v[42:43], v[50:51] op_sel_hi:[1,0]
	s_nop 0
	v_mul_f32_e32 v44, 0xbfb8aa3b, v43
	v_exp_f32_e32 v44, v44
	s_nop 0
	v_add_f32_e32 v44, 1.0, v44
	s_nop 0
	v_rcp_f32_e32 v44, v44
	s_nop 0
	v_mul_f32_e32 v43, v43, v44
	v_mov_b32_e32 v48, v45
	v_mul_f32_e32 v44, v42, v43
	v_pk_mul_f32 v[42:43], v[48:49], v[50:51] op_sel_hi:[1,0]
	s_nop 0
	v_mul_f32_e32 v45, 0xbfb8aa3b, v43
	v_exp_f32_e32 v45, v45
	s_nop 0
	v_add_f32_e32 v45, 1.0, v45
	s_nop 0
	v_rcp_f32_e32 v45, v45
	s_nop 0
	v_mul_f32_e32 v43, v43, v45
	v_mul_f32_e32 v45, v42, v43
	v_mov_b32_e32 v42, v34
	v_mov_b32_e32 v43, v38
	v_pk_mul_f32 v[42:43], v[42:43], v[50:51] op_sel_hi:[1,0]
	s_nop 0
	v_mul_f32_e32 v34, 0xbfb8aa3b, v43
	v_exp_f32_e32 v34, v34
	s_nop 0
	v_add_f32_e32 v34, 1.0, v34
	s_nop 0
	v_rcp_f32_e32 v34, v34
	s_nop 0
	v_mul_f32_e32 v34, v43, v34
	v_mov_b32_e32 v38, v35
	v_mul_f32_e32 v42, v42, v34
	v_pk_mul_f32 v[34:35], v[38:39], v[50:51] op_sel_hi:[1,0]
	s_nop 0
	v_mul_f32_e32 v38, 0xbfb8aa3b, v35
	v_exp_f32_e32 v38, v38
	s_nop 0
	v_add_f32_e32 v38, 1.0, v38
	s_nop 0
	v_rcp_f32_e32 v38, v38
	s_nop 0
	v_mul_f32_e32 v35, v35, v38
	v_mul_f32_e32 v38, v34, v35
	v_mov_b32_e32 v34, v36
	v_mov_b32_e32 v35, v40
	v_pk_mul_f32 v[34:35], v[34:35], v[50:51] op_sel_hi:[1,0]
	s_nop 0
	v_mul_f32_e32 v36, 0xbfb8aa3b, v35
	v_exp_f32_e32 v36, v36
	s_nop 0
	v_add_f32_e32 v36, 1.0, v36
	s_nop 0
	v_rcp_f32_e32 v36, v36
	s_nop 0
	v_mul_f32_e32 v35, v35, v36
	v_mov_b32_e32 v40, v37
	v_mul_f32_e32 v39, v34, v35
	v_pk_mul_f32 v[34:35], v[40:41], v[50:51] op_sel_hi:[1,0]
	s_nop 0
	v_mul_f32_e32 v36, 0xbfb8aa3b, v35
	v_exp_f32_e32 v36, v36
	s_nop 0
	v_add_f32_e32 v36, 1.0, v36
	s_nop 0
	v_rcp_f32_e32 v36, v36
	s_nop 0
	v_mul_f32_e32 v35, v35, v36
	v_mul_f32_e32 v37, v34, v35
	v_cvt_pk_bf16_f32 v34, v51, v46
	v_cvt_pk_bf16_f32 v35, v44, v45
	v_cvt_pk_bf16_f32 v36, v42, v38
	v_cvt_pk_bf16_f32 v37, v39, v37
	v_mad_i64_i32 v[38:39], s[4:5], v153, s6, v[114:115]
	v_lshl_add_u64 v[38:39], v[38:39], 0, v[116:117]
	flat_store_dwordx4 v[38:39], v[34:37] nt
	s_nop 1
	v_fmamk_f32 v34, v152, 0x3a000000, v224
	v_cmp_gt_f32_e32 vcc, s19, v34
	v_mul_f32_e32 v35, 0x4b800000, v34
	v_mov_b32_e32 v36, v26
	v_cndmask_b32_e32 v34, v34, v35, vcc
	v_rsq_f32_e32 v34, v34
	v_mov_b32_e32 v37, v30
	v_mul_f32_e32 v35, 0x45800000, v34
	v_cndmask_b32_e32 v34, v34, v35, vcc
	v_pk_mul_f32 v[36:37], v[36:37], v[34:35] op_sel_hi:[1,0]
	s_nop 0
	v_mul_f32_e32 v26, 0xbfb8aa3b, v37
	v_exp_f32_e32 v26, v26
	s_nop 0
	v_add_f32_e32 v26, 1.0, v26
	s_nop 0
	v_rcp_f32_e32 v26, v26
	s_nop 0
	v_mul_f32_e32 v26, v37, v26
	v_mul_f32_e32 v35, v36, v26
	v_mov_b32_e32 v30, v27
	v_pk_mul_f32 v[26:27], v[30:31], v[34:35] op_sel_hi:[1,0]
	s_nop 0
	v_mul_f32_e32 v30, 0xbfb8aa3b, v27
	v_exp_f32_e32 v30, v30
	s_nop 0
	v_add_f32_e32 v30, 1.0, v30
	s_nop 0
	v_rcp_f32_e32 v30, v30
	s_nop 0
	v_mul_f32_e32 v27, v27, v30
	v_mul_f32_e32 v30, v26, v27
	v_mov_b32_e32 v26, v28
	v_mov_b32_e32 v27, v32
	v_pk_mul_f32 v[26:27], v[26:27], v[34:35] op_sel_hi:[1,0]
	s_nop 0
	v_mul_f32_e32 v28, 0xbfb8aa3b, v27
	v_exp_f32_e32 v28, v28
	s_nop 0
	v_add_f32_e32 v28, 1.0, v28
	s_nop 0
	v_rcp_f32_e32 v28, v28
	s_nop 0
	v_mul_f32_e32 v27, v27, v28
	v_mov_b32_e32 v32, v29
	v_mul_f32_e32 v28, v26, v27
	v_pk_mul_f32 v[26:27], v[32:33], v[34:35] op_sel_hi:[1,0]
	s_nop 0
	v_mul_f32_e32 v29, 0xbfb8aa3b, v27
	v_exp_f32_e32 v29, v29
	s_nop 0
	v_add_f32_e32 v29, 1.0, v29
	s_nop 0
	v_rcp_f32_e32 v29, v29
	s_nop 0
	v_mul_f32_e32 v27, v27, v29
	v_mul_f32_e32 v29, v26, v27
	v_mov_b32_e32 v26, v18
	v_mov_b32_e32 v27, v22
	v_pk_mul_f32 v[26:27], v[26:27], v[34:35] op_sel_hi:[1,0]
	s_nop 0
	v_mul_f32_e32 v18, 0xbfb8aa3b, v27
	v_exp_f32_e32 v18, v18
	s_nop 0
	v_add_f32_e32 v18, 1.0, v18
	s_nop 0
	v_rcp_f32_e32 v18, v18
	s_nop 0
	v_mul_f32_e32 v18, v27, v18
	v_mov_b32_e32 v22, v19
	v_mul_f32_e32 v26, v26, v18
	v_pk_mul_f32 v[18:19], v[22:23], v[34:35] op_sel_hi:[1,0]
	s_nop 0
	v_mul_f32_e32 v22, 0xbfb8aa3b, v19
	v_exp_f32_e32 v22, v22
	s_nop 0
	v_add_f32_e32 v22, 1.0, v22
	s_nop 0
	v_rcp_f32_e32 v22, v22
	s_nop 0
	v_mul_f32_e32 v19, v19, v22
	v_mul_f32_e32 v22, v18, v19
	v_mov_b32_e32 v18, v20
	v_mov_b32_e32 v19, v24
	v_pk_mul_f32 v[18:19], v[18:19], v[34:35] op_sel_hi:[1,0]
	s_nop 0
	v_mul_f32_e32 v20, 0xbfb8aa3b, v19
	v_exp_f32_e32 v20, v20
	s_nop 0
	v_add_f32_e32 v20, 1.0, v20
	s_nop 0
	v_rcp_f32_e32 v20, v20
	s_nop 0
	v_mul_f32_e32 v19, v19, v20
	v_mov_b32_e32 v24, v21
	v_mul_f32_e32 v23, v18, v19
	v_pk_mul_f32 v[18:19], v[24:25], v[34:35] op_sel_hi:[1,0]
	s_nop 0
	v_mul_f32_e32 v20, 0xbfb8aa3b, v19
	v_exp_f32_e32 v20, v20
	s_nop 0
	v_add_f32_e32 v20, 1.0, v20
	s_nop 0
	v_rcp_f32_e32 v20, v20
	s_nop 0
	v_mul_f32_e32 v19, v19, v20
	v_mul_f32_e32 v21, v18, v19
	v_cvt_pk_bf16_f32 v18, v35, v30
	v_cvt_pk_bf16_f32 v19, v28, v29
	v_cvt_pk_bf16_f32 v20, v26, v22
	v_cvt_pk_bf16_f32 v21, v23, v21
	v_mad_i64_i32 v[22:23], s[4:5], v151, s6, v[114:115]
	v_lshl_add_u64 v[22:23], v[22:23], 0, v[116:117]
	flat_store_dwordx4 v[22:23], v[18:21] nt
	s_nop 1
	v_fmamk_f32 v18, v150, 0x3a000000, v224
	v_cmp_gt_f32_e32 vcc, s19, v18
	v_mul_f32_e32 v19, 0x4b800000, v18
	v_mov_b32_e32 v20, v10
	v_cndmask_b32_e32 v18, v18, v19, vcc
	v_rsq_f32_e32 v18, v18
	v_mov_b32_e32 v21, v14
	v_mul_f32_e32 v19, 0x45800000, v18
	v_cndmask_b32_e32 v18, v18, v19, vcc
	v_pk_mul_f32 v[20:21], v[20:21], v[18:19] op_sel_hi:[1,0]
	s_nop 0
	v_mul_f32_e32 v10, 0xbfb8aa3b, v21
	v_exp_f32_e32 v10, v10
	s_nop 0
	v_add_f32_e32 v10, 1.0, v10
	s_nop 0
	v_rcp_f32_e32 v10, v10
	s_nop 0
	v_mul_f32_e32 v10, v21, v10
	v_mul_f32_e32 v19, v20, v10
	v_mov_b32_e32 v14, v11
	v_pk_mul_f32 v[10:11], v[14:15], v[18:19] op_sel_hi:[1,0]
	s_nop 0
	v_mul_f32_e32 v14, 0xbfb8aa3b, v11
	v_exp_f32_e32 v14, v14
	s_nop 0
	v_add_f32_e32 v14, 1.0, v14
	s_nop 0
	v_rcp_f32_e32 v14, v14
	s_nop 0
	v_mul_f32_e32 v11, v11, v14
	v_mul_f32_e32 v14, v10, v11
	v_mov_b32_e32 v10, v12
	v_mov_b32_e32 v11, v16
	v_pk_mul_f32 v[10:11], v[10:11], v[18:19] op_sel_hi:[1,0]
	s_nop 0
	v_mul_f32_e32 v12, 0xbfb8aa3b, v11
	v_exp_f32_e32 v12, v12
	s_nop 0
	v_add_f32_e32 v12, 1.0, v12
	s_nop 0
	v_rcp_f32_e32 v12, v12
	s_nop 0
	v_mul_f32_e32 v11, v11, v12
	v_mov_b32_e32 v16, v13
	v_mul_f32_e32 v12, v10, v11
	v_pk_mul_f32 v[10:11], v[16:17], v[18:19] op_sel_hi:[1,0]
	s_nop 0
	v_mul_f32_e32 v13, 0xbfb8aa3b, v11
	v_exp_f32_e32 v13, v13
	s_nop 0
	v_add_f32_e32 v13, 1.0, v13
	s_nop 0
	v_rcp_f32_e32 v13, v13
	s_nop 0
	v_mul_f32_e32 v11, v11, v13
	v_mul_f32_e32 v13, v10, v11
	v_mov_b32_e32 v10, v2
	v_mov_b32_e32 v11, v6
	v_pk_mul_f32 v[10:11], v[10:11], v[18:19] op_sel_hi:[1,0]
	s_nop 0
	v_mul_f32_e32 v2, 0xbfb8aa3b, v11
	v_exp_f32_e32 v2, v2
	s_nop 0
	v_add_f32_e32 v2, 1.0, v2
	s_nop 0
	v_rcp_f32_e32 v2, v2
	s_nop 0
	v_mul_f32_e32 v2, v11, v2
	v_mov_b32_e32 v6, v3
	v_mul_f32_e32 v10, v10, v2
	v_pk_mul_f32 v[2:3], v[6:7], v[18:19] op_sel_hi:[1,0]
	s_nop 0
	v_mul_f32_e32 v6, 0xbfb8aa3b, v3
	v_exp_f32_e32 v6, v6
	s_nop 0
	v_add_f32_e32 v6, 1.0, v6
	s_nop 0
	v_rcp_f32_e32 v6, v6
	s_nop 0
	v_mul_f32_e32 v3, v3, v6
	v_mul_f32_e32 v6, v2, v3
	v_mov_b32_e32 v2, v4
	v_mov_b32_e32 v3, v8
	v_pk_mul_f32 v[2:3], v[2:3], v[18:19] op_sel_hi:[1,0]
	s_nop 0
	v_mul_f32_e32 v4, 0xbfb8aa3b, v3
	v_exp_f32_e32 v4, v4
	s_nop 0
	v_add_f32_e32 v4, 1.0, v4
	s_nop 0
	v_rcp_f32_e32 v4, v4
	s_nop 0
	v_mul_f32_e32 v3, v3, v4
	v_mov_b32_e32 v8, v5
	v_mul_f32_e32 v7, v2, v3
	v_pk_mul_f32 v[2:3], v[8:9], v[18:19] op_sel_hi:[1,0]
	s_nop 0
	v_mul_f32_e32 v4, 0xbfb8aa3b, v3
	v_exp_f32_e32 v4, v4
	s_nop 0
	v_add_f32_e32 v4, 1.0, v4
	s_nop 0
	v_rcp_f32_e32 v4, v4
	s_nop 0
	v_mul_f32_e32 v3, v3, v4
	v_mul_f32_e32 v5, v2, v3
	v_cvt_pk_bf16_f32 v2, v19, v14
	v_cvt_pk_bf16_f32 v3, v12, v13
	v_cvt_pk_bf16_f32 v4, v10, v6
	v_cvt_pk_bf16_f32 v5, v7, v5
	v_mad_i64_i32 v[6:7], s[4:5], v141, s6, v[114:115]
	v_lshl_add_u64 v[6:7], v[6:7], 0, v[116:117]
	s_mov_b64 s[4:5], -1
	s_andn2_b64 vcc, exec, s[40:41]
	flat_store_dwordx4 v[6:7], v[2:5] nt
	s_cbranch_vccnz .LBB0_1535
	s_andn2_b64 vcc, exec, s[42:43]
	s_cbranch_vccnz .LBB0_1534
	s_barrier
	s_branch .LBB0_1534
